# A/B: adjacent s_setprio 0 / s_setprio 1 pairs between the two 16-MFMA blocks of each GEMM super-phase removed (priority held across 32 MFMAs); on top of v37
# baseline (speedup 1.0000x reference)
; #define PG8_STAGE(bufoff, gbase, voff) do { _Pragma("unroll") for (int _i = 0; _i < 2; ++_i) \
;         __builtin_amdgcn_global_load_lds((const unsigned*)((const char*)(gbase) + (voff)[_i]), (PG8_LAS unsigned*)(lds + (bufoff) + ldsw + _i * 8192), 16, 0, 0); } while (0)
; #define PG8_LDA(dst, b, h) do { _Pragma("unroll") for (int m = 0; m < 4; ++m) _Pragma("unroll") for (int k = 0; k < 2; ++k) dst[m][k] = *(const PG8_LAS bf16x8*)(lds + PG8_SA(b, h) + aoff + m * 2048 + k * 1024); } while (0)
; #define PG8_LDB(dst, b, h) do { _Pragma("unroll") for (int n = 0; n < 2; ++n) _Pragma("unroll") for (int k = 0; k < 2; ++k) dst[n][k] = *(const PG8_LAS bf16x8*)(lds + PG8_SB(b, h) + boff + n * 2048 + k * 1024); } while (0)
; #define PG8_MMA(ai, bj, At, Bt) do { __builtin_amdgcn_s_setprio(1); _Pragma("unroll") for (int m = 0; m < 4; ++m) _Pragma("unroll") for (int n = 0; n < 2; ++n) _Pragma("unroll") for (int k = 0; k < 2; ++k) \
;         acc[ai][bj][m][n] = __builtin_amdgcn_mfma_f32_16x16x32_bf16(Bt[n][k], At[m][k], acc[ai][bj][m][n], 0, 0, 0); __builtin_amdgcn_s_setprio(0); } while (0)
; #define PG8_WAIT_V(n) asm volatile("s_waitcnt vmcnt(" #n ")" ::: "memory")
; #define PG8_BAR __builtin_amdgcn_s_barrier()
; template <class Epi, class Sched, bool ALIGN_EPI = false, bool SP2 = false>
; __device__ __forceinline__ void gemm_phase(PG8_LAS unsigned char* lds, const Gemm g, const Sched& S, const Epi& E) {
;     ...
;         for (int t = 0; t < nt; t += 2) {
;             const bool last = (t == nt - 2);
;             const char* a1 = cA + (size_t)(t + 1) * kstep;
;             const char* a2 = last ? nA : cA + (size_t)(t + 2) * kstep; const char* b2 = last ? nB : cB + (size_t)(t + 2) * kstep;
;             const char* a3 = a2 + kstep; const char* b3 = b2 + kstep;
;             if (last && has_next) S.a_ready(nxt);
;             if constexpr (SP2) {
;             PG8_LDB(B0, 0, 0); PG8_LDB(B1, 0, 1); PG8_SCHED; PG8_LDA(At, 0, 0); PG8_STAGE(PG8_SA(1, 1), a1 + hstepA, voffA);
;             PG8_WAIT_V(8); PG8_WAIT_L(0); PG8_BAR; PG8_MMA(0, 0, At, B0); PG8_MMA(0, 1, At, B1); PG8_BAR; PG8_SCHED;
;             PG8_LDA(At, 0, 1); PG8_STAGE(PG8_SB(0, 0), b2, voffB); PG8_STAGE(PG8_SB(0, 1), b2 + hstepB, voffB); PG8_STAGE(PG8_SA(0, 0), a2, voffA);
;             PG8_WAIT_V(8); PG8_WAIT_L(0); PG8_BAR; PG8_MMA(1, 0, At, B0); PG8_MMA(1, 1, At, B1); PG8_BAR; PG8_SCHED;
.LBB0_254:
	s_add_u32 s28, s26, 0xfffc0080
	s_addc_u32 s29, s27, -1
	s_add_i32 s53, 0, 0x10000
	s_cmp_eq_u32 s52, 12
	s_cselect_b32 s31, s7, s29
	s_cselect_b32 s30, s9, s28
	v_add_u32_e32 v150, s53, v153
	s_cselect_b32 s29, s19, s51
	s_cselect_b32 s28, s21, s50
	s_add_i32 s56, 0, 0x14000
	ds_read_b128 v[142:145], v150
	ds_read_b128 v[146:149], v150 offset:1024
	ds_read_b128 v[158:161], v150 offset:2048
	ds_read_b128 v[162:165], v150 offset:3072
	v_add_u32_e32 v150, s56, v153
	ds_read_b128 v[166:169], v150
	ds_read_b128 v[170:173], v150 offset:1024
	ds_read_b128 v[174:177], v150 offset:2048
	ds_read_b128 v[178:181], v150 offset:3072
	s_add_i32 m0, s40, 0xc000
	ds_read_b128 v[182:185], v156
	ds_read_b128 v[202:205], v156 offset:1024
	ds_read_b128 v[206:209], v156 offset:2048
	ds_read_b128 v[210:213], v156 offset:3072
	ds_read_b128 v[232:235], v156 offset:4096
	ds_read_b128 v[236:239], v156 offset:5120
	ds_read_b128 v[240:243], v156 offset:6144
	ds_read_b128 v[244:247], v156 offset:7168
	global_load_lds_dwordx4 v138, s[26:27]
	s_add_i32 m0, s40, 0xe000
	s_nop 0
	global_load_lds_dwordx4 v140, s[26:27]
	s_waitcnt vmcnt(8)
	s_waitcnt lgkmcnt(0)
	s_barrier
	s_setprio 1
	s_waitcnt lgkmcnt(0)
	v_mfma_f32_16x16x32_bf16 v[126:129], v[142:145], v[182:185], v[126:129]
	v_mfma_f32_16x16x32_bf16 v[122:125], v[158:161], v[182:185], v[122:125]
	v_mfma_f32_16x16x32_bf16 v[110:113], v[142:145], v[206:209], v[110:113]
	v_mfma_f32_16x16x32_bf16 v[106:109], v[158:161], v[206:209], v[106:109]
	v_mfma_f32_16x16x32_bf16 v[94:97], v[142:145], v[232:235], v[94:97]
	v_mfma_f32_16x16x32_bf16 v[90:93], v[158:161], v[232:235], v[90:93]
	v_mfma_f32_16x16x32_bf16 v[78:81], v[142:145], v[240:243], v[78:81]
	v_mfma_f32_16x16x32_bf16 v[74:77], v[158:161], v[240:243], v[74:77]
	v_mfma_f32_16x16x32_bf16 v[126:129], v[146:149], v[202:205], v[126:129]
	v_mfma_f32_16x16x32_bf16 v[122:125], v[162:165], v[202:205], v[122:125]
	v_mfma_f32_16x16x32_bf16 v[110:113], v[146:149], v[210:213], v[110:113]
	v_mfma_f32_16x16x32_bf16 v[106:109], v[162:165], v[210:213], v[106:109]
	v_mfma_f32_16x16x32_bf16 v[94:97], v[146:149], v[236:239], v[94:97]
	v_mfma_f32_16x16x32_bf16 v[90:93], v[162:165], v[236:239], v[90:93]
	v_mfma_f32_16x16x32_bf16 v[78:81], v[146:149], v[244:247], v[78:81]
	v_mfma_f32_16x16x32_bf16 v[74:77], v[162:165], v[244:247], v[74:77]
	v_mfma_f32_16x16x32_bf16 v[118:121], v[166:169], v[182:185], v[118:121]
	v_mfma_f32_16x16x32_bf16 v[114:117], v[174:177], v[182:185], v[114:117]
	v_mfma_f32_16x16x32_bf16 v[102:105], v[166:169], v[206:209], v[102:105]
	v_mfma_f32_16x16x32_bf16 v[98:101], v[174:177], v[206:209], v[98:101]
	v_mfma_f32_16x16x32_bf16 v[86:89], v[166:169], v[232:235], v[86:89]
	v_mfma_f32_16x16x32_bf16 v[82:85], v[174:177], v[232:235], v[82:85]
	v_mfma_f32_16x16x32_bf16 v[70:73], v[166:169], v[240:243], v[70:73]
	v_mfma_f32_16x16x32_bf16 v[66:69], v[174:177], v[240:243], v[66:69]
	v_mfma_f32_16x16x32_bf16 v[118:121], v[170:173], v[202:205], v[118:121]
	v_mfma_f32_16x16x32_bf16 v[114:117], v[178:181], v[202:205], v[114:117]
	v_mfma_f32_16x16x32_bf16 v[102:105], v[170:173], v[210:213], v[102:105]
	v_mfma_f32_16x16x32_bf16 v[98:101], v[178:181], v[210:213], v[98:101]
	v_mfma_f32_16x16x32_bf16 v[86:89], v[170:173], v[236:239], v[86:89]
	v_mfma_f32_16x16x32_bf16 v[82:85], v[178:181], v[236:239], v[82:85]
	v_mfma_f32_16x16x32_bf16 v[70:73], v[170:173], v[244:247], v[70:73]
	v_mfma_f32_16x16x32_bf16 v[66:69], v[178:181], v[244:247], v[66:69]
	s_setprio 0
	s_barrier
	s_add_i32 s53, s53, s39
	s_mov_b32 m0, s53
	ds_read_b128 v[182:185], v156 offset:16384
	ds_read_b128 v[202:205], v156 offset:17408
	ds_read_b128 v[206:209], v156 offset:18432
	ds_read_b128 v[210:213], v156 offset:19456
	ds_read_b128 v[232:235], v156 offset:20480
	ds_read_b128 v[236:239], v156 offset:21504
	ds_read_b128 v[240:243], v156 offset:22528
	ds_read_b128 v[244:247], v156 offset:23552
	s_add_u32 s60, s28, 0x80
	s_addc_u32 s61, s29, 0
	s_add_u32 s62, s30, 0x80
	s_addc_u32 s63, s31, 0
	global_load_lds_dwordx4 v132, s[28:29]
	s_add_i32 m0, s53, 0x2000
	s_add_u32 s54, s28, 0x40000
	s_addc_u32 s55, s29, 0
	s_add_i32 s53, s56, s39
	global_load_lds_dwordx4 v136, s[28:29]
	s_mov_b32 m0, s53
	s_nop 0
	global_load_lds_dwordx4 v132, s[54:55]
	s_add_i32 m0, s53, 0x2000
	s_nop 0
	global_load_lds_dwordx4 v136, s[54:55]
	s_mov_b32 m0, s40
	s_nop 0
	global_load_lds_dwordx4 v130, s[30:31]
	s_mov_b32 m0, s41
	s_nop 0
	global_load_lds_dwordx4 v134, s[30:31]
	s_waitcnt vmcnt(8)
	s_waitcnt lgkmcnt(0)
	s_barrier
	s_setprio 1
	s_waitcnt lgkmcnt(0)
	v_mfma_f32_16x16x32_bf16 v[62:65], v[142:145], v[182:185], v[62:65]
	v_mfma_f32_16x16x32_bf16 v[58:61], v[158:161], v[182:185], v[58:61]
	v_mfma_f32_16x16x32_bf16 v[46:49], v[142:145], v[206:209], v[46:49]
	v_mfma_f32_16x16x32_bf16 v[42:45], v[158:161], v[206:209], v[42:45]
	v_mfma_f32_16x16x32_bf16 v[30:33], v[142:145], v[232:235], v[30:33]
	v_mfma_f32_16x16x32_bf16 v[26:29], v[158:161], v[232:235], v[26:29]
	v_mfma_f32_16x16x32_bf16 v[14:17], v[142:145], v[240:243], v[14:17]
	v_mfma_f32_16x16x32_bf16 v[10:13], v[158:161], v[240:243], v[10:13]
	v_mfma_f32_16x16x32_bf16 v[62:65], v[146:149], v[202:205], v[62:65]
	v_mfma_f32_16x16x32_bf16 v[58:61], v[162:165], v[202:205], v[58:61]
	v_mfma_f32_16x16x32_bf16 v[46:49], v[146:149], v[210:213], v[46:49]
	v_mfma_f32_16x16x32_bf16 v[42:45], v[162:165], v[210:213], v[42:45]
	v_mfma_f32_16x16x32_bf16 v[30:33], v[146:149], v[236:239], v[30:33]
	v_mfma_f32_16x16x32_bf16 v[26:29], v[162:165], v[236:239], v[26:29]
	v_mfma_f32_16x16x32_bf16 v[14:17], v[146:149], v[244:247], v[14:17]
	v_mfma_f32_16x16x32_bf16 v[10:13], v[162:165], v[244:247], v[10:13]
	v_mfma_f32_16x16x32_bf16 v[54:57], v[166:169], v[182:185], v[54:57]
	v_mfma_f32_16x16x32_bf16 v[50:53], v[174:177], v[182:185], v[50:53]
	v_mfma_f32_16x16x32_bf16 v[38:41], v[166:169], v[206:209], v[38:41]
	v_mfma_f32_16x16x32_bf16 v[34:37], v[174:177], v[206:209], v[34:37]
	v_mfma_f32_16x16x32_bf16 v[22:25], v[166:169], v[232:235], v[22:25]
	v_mfma_f32_16x16x32_bf16 v[18:21], v[174:177], v[232:235], v[18:21]
	v_mfma_f32_16x16x32_bf16 v[6:9], v[166:169], v[240:243], v[6:9]
	v_mfma_f32_16x16x32_bf16 v[2:5], v[174:177], v[240:243], v[2:5]
	v_mfma_f32_16x16x32_bf16 v[54:57], v[170:173], v[202:205], v[54:57]
	v_mfma_f32_16x16x32_bf16 v[50:53], v[178:181], v[202:205], v[50:53]
	v_mfma_f32_16x16x32_bf16 v[38:41], v[170:173], v[210:213], v[38:41]
	v_mfma_f32_16x16x32_bf16 v[34:37], v[178:181], v[210:213], v[34:37]
	v_mfma_f32_16x16x32_bf16 v[22:25], v[170:173], v[236:239], v[22:25]
	v_mfma_f32_16x16x32_bf16 v[18:21], v[178:181], v[236:239], v[18:21]
	v_mfma_f32_16x16x32_bf16 v[6:9], v[170:173], v[244:247], v[6:9]
	v_mfma_f32_16x16x32_bf16 v[2:5], v[178:181], v[244:247], v[2:5]
	s_setprio 0
	s_barrier
; #define PG8_STAGE(bufoff, gbase, voff) do { _Pragma("unroll") for (int _i = 0; _i < 2; ++_i) \
;         __builtin_amdgcn_global_load_lds((const unsigned*)((const char*)(gbase) + (voff)[_i]), (PG8_LAS unsigned*)(lds + (bufoff) + ldsw + _i * 8192), 16, 0, 0); } while (0)
; #define PG8_LDA(dst, b, h) do { _Pragma("unroll") for (int m = 0; m < 4; ++m) _Pragma("unroll") for (int k = 0; k < 2; ++k) dst[m][k] = *(const PG8_LAS bf16x8*)(lds + PG8_SA(b, h) + aoff + m * 2048 + k * 1024); } while (0)
; #define PG8_LDB(dst, b, h) do { _Pragma("unroll") for (int n = 0; n < 2; ++n) _Pragma("unroll") for (int k = 0; k < 2; ++k) dst[n][k] = *(const PG8_LAS bf16x8*)(lds + PG8_SB(b, h) + boff + n * 2048 + k * 1024); } while (0)
; #define PG8_MMA(ai, bj, At, Bt) do { __builtin_amdgcn_s_setprio(1); _Pragma("unroll") for (int m = 0; m < 4; ++m) _Pragma("unroll") for (int n = 0; n < 2; ++n) _Pragma("unroll") for (int k = 0; k < 2; ++k) \
;         acc[ai][bj][m][n] = __builtin_amdgcn_mfma_f32_16x16x32_bf16(Bt[n][k], At[m][k], acc[ai][bj][m][n], 0, 0, 0); __builtin_amdgcn_s_setprio(0); } while (0)
; #define PG8_WAIT_V(n) asm volatile("s_waitcnt vmcnt(" #n ")" ::: "memory")
; #define PG8_WAIT_L(n) asm volatile("s_waitcnt lgkmcnt(" #n ")" ::: "memory")
; #define PG8_BAR __builtin_amdgcn_s_barrier()
; #define PG8_SCHED __builtin_amdgcn_sched_barrier(0)
; template <class Epi, class Sched, bool ALIGN_EPI = false, bool SP2 = false>
; __device__ __forceinline__ void gemm_phase(PG8_LAS unsigned char* lds, const Gemm g, const Sched& S, const Epi& E) {
;     ...
;             PG8_LDB(B0, 1, 0); PG8_LDB(B1, 1, 1); PG8_SCHED; PG8_LDA(At, 1, 0); PG8_STAGE(PG8_SA(0, 1), a2 + hstepA, voffA);
;             PG8_WAIT_V(8); PG8_WAIT_L(0); PG8_BAR; PG8_MMA(0, 0, At, B0); PG8_MMA(0, 1, At, B1); PG8_BAR; PG8_SCHED;
;             PG8_LDA(At, 1, 1); PG8_STAGE(PG8_SB(1, 0), b3, voffB); PG8_STAGE(PG8_SB(1, 1), b3 + hstepB, voffB); PG8_STAGE(PG8_SA(1, 0), a3, voffA);
;             PG8_WAIT_V(8); PG8_WAIT_L(0); PG8_BAR; PG8_MMA(1, 0, At, B0); PG8_MMA(1, 1, At, B1); PG8_BAR; PG8_SCHED;
	s_add_i32 s53, 0, 0x18000
	v_add_u32_e32 v157, s53, v153
	s_add_i32 s54, 0, 0x1c000
	ds_read_b128 v[142:145], v157
	ds_read_b128 v[146:149], v157 offset:1024
	ds_read_b128 v[158:161], v157 offset:2048
	ds_read_b128 v[162:165], v157 offset:3072
	v_add_u32_e32 v157, s54, v153
	ds_read_b128 v[166:169], v157
	ds_read_b128 v[170:173], v157 offset:1024
	ds_read_b128 v[174:177], v157 offset:2048
	ds_read_b128 v[178:181], v157 offset:3072
	s_add_u32 s30, s30, 0x40000
	s_addc_u32 s31, s31, 0
	s_mov_b32 m0, s42
	ds_read_b128 v[182:185], v156 offset:32768
	ds_read_b128 v[202:205], v156 offset:33792
	ds_read_b128 v[206:209], v156 offset:34816
	ds_read_b128 v[210:213], v156 offset:35840
	ds_read_b128 v[232:235], v156 offset:36864
	ds_read_b128 v[236:239], v156 offset:37888
	ds_read_b128 v[240:243], v156 offset:38912
	ds_read_b128 v[244:247], v156 offset:39936
	global_load_lds_dwordx4 v130, s[30:31]
	s_mov_b32 m0, s43
	s_nop 0
	global_load_lds_dwordx4 v134, s[30:31]
	s_waitcnt vmcnt(8)
	s_waitcnt lgkmcnt(0)
	s_barrier
	s_setprio 1
	s_waitcnt lgkmcnt(0)
	v_mfma_f32_16x16x32_bf16 v[126:129], v[142:145], v[182:185], v[126:129]
	v_mfma_f32_16x16x32_bf16 v[122:125], v[158:161], v[182:185], v[122:125]
	v_mfma_f32_16x16x32_bf16 v[110:113], v[142:145], v[206:209], v[110:113]
	v_mfma_f32_16x16x32_bf16 v[106:109], v[158:161], v[206:209], v[106:109]
	v_mfma_f32_16x16x32_bf16 v[94:97], v[142:145], v[232:235], v[94:97]
	v_mfma_f32_16x16x32_bf16 v[90:93], v[158:161], v[232:235], v[90:93]
	v_mfma_f32_16x16x32_bf16 v[78:81], v[142:145], v[240:243], v[78:81]
	v_mfma_f32_16x16x32_bf16 v[74:77], v[158:161], v[240:243], v[74:77]
	v_mfma_f32_16x16x32_bf16 v[126:129], v[146:149], v[202:205], v[126:129]
	v_mfma_f32_16x16x32_bf16 v[122:125], v[162:165], v[202:205], v[122:125]
	v_mfma_f32_16x16x32_bf16 v[110:113], v[146:149], v[210:213], v[110:113]
	v_mfma_f32_16x16x32_bf16 v[106:109], v[162:165], v[210:213], v[106:109]
	v_mfma_f32_16x16x32_bf16 v[94:97], v[146:149], v[236:239], v[94:97]
	v_mfma_f32_16x16x32_bf16 v[90:93], v[162:165], v[236:239], v[90:93]
	v_mfma_f32_16x16x32_bf16 v[78:81], v[146:149], v[244:247], v[78:81]
	v_mfma_f32_16x16x32_bf16 v[74:77], v[162:165], v[244:247], v[74:77]
	v_mfma_f32_16x16x32_bf16 v[118:121], v[166:169], v[182:185], v[118:121]
	v_mfma_f32_16x16x32_bf16 v[114:117], v[174:177], v[182:185], v[114:117]
	v_mfma_f32_16x16x32_bf16 v[102:105], v[166:169], v[206:209], v[102:105]
	v_mfma_f32_16x16x32_bf16 v[98:101], v[174:177], v[206:209], v[98:101]
	v_mfma_f32_16x16x32_bf16 v[86:89], v[166:169], v[232:235], v[86:89]
	v_mfma_f32_16x16x32_bf16 v[82:85], v[174:177], v[232:235], v[82:85]
	v_mfma_f32_16x16x32_bf16 v[70:73], v[166:169], v[240:243], v[70:73]
	v_mfma_f32_16x16x32_bf16 v[66:69], v[174:177], v[240:243], v[66:69]
	v_mfma_f32_16x16x32_bf16 v[118:121], v[170:173], v[202:205], v[118:121]
	v_mfma_f32_16x16x32_bf16 v[114:117], v[178:181], v[202:205], v[114:117]
	v_mfma_f32_16x16x32_bf16 v[102:105], v[170:173], v[210:213], v[102:105]
	v_mfma_f32_16x16x32_bf16 v[98:101], v[178:181], v[210:213], v[98:101]
	v_mfma_f32_16x16x32_bf16 v[86:89], v[170:173], v[236:239], v[86:89]
	v_mfma_f32_16x16x32_bf16 v[82:85], v[178:181], v[236:239], v[82:85]
	v_mfma_f32_16x16x32_bf16 v[70:73], v[170:173], v[244:247], v[70:73]
	v_mfma_f32_16x16x32_bf16 v[66:69], v[178:181], v[244:247], v[66:69]
	s_setprio 0
	s_barrier
	s_add_i32 s30, s53, s39
	s_mov_b32 m0, s30
	ds_read_b128 v[182:185], v156 offset:49152
	ds_read_b128 v[202:205], v156 offset:50176
	ds_read_b128 v[206:209], v156 offset:51200
	ds_read_b128 v[210:213], v156 offset:52224
	ds_read_b128 v[232:235], v156 offset:53248
	ds_read_b128 v[236:239], v156 offset:54272
	ds_read_b128 v[240:243], v156 offset:55296
	ds_read_b128 v[244:247], v156 offset:56320
	global_load_lds_dwordx4 v132, s[60:61]
	s_add_i32 m0, s30, 0x2000
	s_add_u32 s28, s28, 0x40080
	s_addc_u32 s29, s29, 0
	s_add_i32 s30, s54, s39
	global_load_lds_dwordx4 v136, s[60:61]
	s_mov_b32 m0, s30
	s_nop 0
	global_load_lds_dwordx4 v132, s[28:29]
	s_add_i32 m0, s30, 0x2000
	s_nop 0
	global_load_lds_dwordx4 v136, s[28:29]
	s_mov_b32 m0, s45
	s_nop 0
	global_load_lds_dwordx4 v130, s[62:63]
	s_mov_b32 m0, s46
	s_nop 0
	global_load_lds_dwordx4 v134, s[62:63]
	s_waitcnt vmcnt(8)
	s_waitcnt lgkmcnt(0)
	s_barrier
	s_setprio 1
	s_waitcnt lgkmcnt(0)
	v_mfma_f32_16x16x32_bf16 v[62:65], v[142:145], v[182:185], v[62:65]
	v_mfma_f32_16x16x32_bf16 v[58:61], v[158:161], v[182:185], v[58:61]
	v_mfma_f32_16x16x32_bf16 v[46:49], v[142:145], v[206:209], v[46:49]
	v_mfma_f32_16x16x32_bf16 v[42:45], v[158:161], v[206:209], v[42:45]
	v_mfma_f32_16x16x32_bf16 v[30:33], v[142:145], v[232:235], v[30:33]
	v_mfma_f32_16x16x32_bf16 v[26:29], v[158:161], v[232:235], v[26:29]
	v_mfma_f32_16x16x32_bf16 v[14:17], v[142:145], v[240:243], v[14:17]
	v_mfma_f32_16x16x32_bf16 v[10:13], v[158:161], v[240:243], v[10:13]
	v_mfma_f32_16x16x32_bf16 v[62:65], v[146:149], v[202:205], v[62:65]
	v_mfma_f32_16x16x32_bf16 v[58:61], v[162:165], v[202:205], v[58:61]
	v_mfma_f32_16x16x32_bf16 v[46:49], v[146:149], v[210:213], v[46:49]
	v_mfma_f32_16x16x32_bf16 v[42:45], v[162:165], v[210:213], v[42:45]
	v_mfma_f32_16x16x32_bf16 v[30:33], v[146:149], v[236:239], v[30:33]
	v_mfma_f32_16x16x32_bf16 v[26:29], v[162:165], v[236:239], v[26:29]
	v_mfma_f32_16x16x32_bf16 v[14:17], v[146:149], v[244:247], v[14:17]
	v_mfma_f32_16x16x32_bf16 v[10:13], v[162:165], v[244:247], v[10:13]
	v_mfma_f32_16x16x32_bf16 v[54:57], v[166:169], v[182:185], v[54:57]
	v_mfma_f32_16x16x32_bf16 v[50:53], v[174:177], v[182:185], v[50:53]
	v_mfma_f32_16x16x32_bf16 v[38:41], v[166:169], v[206:209], v[38:41]
	v_mfma_f32_16x16x32_bf16 v[34:37], v[174:177], v[206:209], v[34:37]
	v_mfma_f32_16x16x32_bf16 v[22:25], v[166:169], v[232:235], v[22:25]
	v_mfma_f32_16x16x32_bf16 v[18:21], v[174:177], v[232:235], v[18:21]
	v_mfma_f32_16x16x32_bf16 v[6:9], v[166:169], v[240:243], v[6:9]
	v_mfma_f32_16x16x32_bf16 v[2:5], v[174:177], v[240:243], v[2:5]
	v_mfma_f32_16x16x32_bf16 v[54:57], v[170:173], v[202:205], v[54:57]
	v_mfma_f32_16x16x32_bf16 v[50:53], v[178:181], v[202:205], v[50:53]
	v_mfma_f32_16x16x32_bf16 v[38:41], v[170:173], v[210:213], v[38:41]
	v_mfma_f32_16x16x32_bf16 v[34:37], v[178:181], v[210:213], v[34:37]
	v_mfma_f32_16x16x32_bf16 v[22:25], v[170:173], v[236:239], v[22:25]
	v_mfma_f32_16x16x32_bf16 v[18:21], v[178:181], v[236:239], v[18:21]
	v_mfma_f32_16x16x32_bf16 v[6:9], v[170:173], v[244:247], v[6:9]
	v_mfma_f32_16x16x32_bf16 v[2:5], v[178:181], v[244:247], v[2:5]
	s_setprio 0
	s_barrier
	s_add_i32 s52, s52, 2
	s_add_u32 s26, s26, 0x100
	s_addc_u32 s27, s27, 0
	s_add_u32 s50, s50, 0x100
	s_addc_u32 s51, s51, 0
	s_cmp_gt_u32 s52, 13
	s_cbranch_scc0 .LBB0_254
	s_and_b64 vcc, exec, s[16:17]
	s_cbranch_vccz .LBB0_257
	s_barrier

; #define PG8_STAGE(bufoff, gbase, voff) do { _Pragma("unroll") for (int _i = 0; _i < 2; ++_i) \
;         __builtin_amdgcn_global_load_lds((const unsigned*)((const char*)(gbase) + (voff)[_i]), (PG8_LAS unsigned*)(lds + (bufoff) + ldsw + _i * 8192), 16, 0, 0); } while (0)
; #define PG8_LDA(dst, b, h) do { _Pragma("unroll") for (int m = 0; m < 4; ++m) _Pragma("unroll") for (int k = 0; k < 2; ++k) dst[m][k] = *(const PG8_LAS bf16x8*)(lds + PG8_SA(b, h) + aoff + m * 2048 + k * 1024); } while (0)
; #define PG8_LDB(dst, b, h) do { _Pragma("unroll") for (int n = 0; n < 2; ++n) _Pragma("unroll") for (int k = 0; k < 2; ++k) dst[n][k] = *(const PG8_LAS bf16x8*)(lds + PG8_SB(b, h) + boff + n * 2048 + k * 1024); } while (0)
; template <class Epi, class Sched, bool ALIGN_EPI = false, bool SP2 = false>
; __device__ __forceinline__ void gemm_phase(PG8_LAS unsigned char* lds, const Gemm g, const Sched& S, const Epi& E) {
;     ...
;         for (int t = 0; t < nt; t += 2) {
;             const bool last = (t == nt - 2);
;             const char* a1 = cA + (size_t)(t + 1) * kstep;
;             const char* a2 = last ? nA : cA + (size_t)(t + 2) * kstep; const char* b2 = last ? nB : cB + (size_t)(t + 2) * kstep;
;             const char* a3 = a2 + kstep; const char* b3 = b2 + kstep;
;             if (last && has_next) S.a_ready(nxt);
;             if constexpr (SP2) {
;             PG8_LDB(B0, 0, 0); PG8_LDB(B1, 0, 1); PG8_SCHED; PG8_LDA(At, 0, 0); PG8_STAGE(PG8_SA(1, 1), a1 + hstepA, voffA);
;             PG8_WAIT_V(8); PG8_WAIT_L(0); PG8_BAR; PG8_MMA(0, 0, At, B0); PG8_MMA(0, 1, At, B1); PG8_BAR; PG8_SCHED;
;             PG8_LDA(At, 0, 1); PG8_STAGE(PG8_SB(0, 0), b2, voffB); PG8_STAGE(PG8_SB(0, 1), b2 + hstepB, voffB); PG8_STAGE(PG8_SA(0, 0), a2, voffA);
;             PG8_WAIT_V(8); PG8_WAIT_L(0); PG8_BAR; PG8_MMA(1, 0, At, B0); PG8_MMA(1, 1, At, B1); PG8_BAR; PG8_SCHED;
;             PG8_LDB(B0, 1, 0); PG8_LDB(B1, 1, 1); PG8_SCHED; PG8_LDA(At, 1, 0); PG8_STAGE(PG8_SA(0, 1), a2 + hstepA, voffA);
;             PG8_WAIT_V(8); PG8_WAIT_L(0); PG8_BAR; PG8_MMA(0, 0, At, B0); PG8_MMA(0, 1, At, B1); PG8_BAR; PG8_SCHED;
;             PG8_LDA(At, 1, 1); PG8_STAGE(PG8_SB(1, 0), b3, voffB); PG8_STAGE(PG8_SB(1, 1), b3 + hstepB, voffB); PG8_STAGE(PG8_SA(1, 0), a3, voffA);
;             PG8_WAIT_V(8); PG8_WAIT_L(0); PG8_BAR; PG8_MMA(1, 0, At, B0); PG8_MMA(1, 1, At, B1); PG8_BAR; PG8_SCHED;
.LBB0_530:
	s_add_u32 s12, s1, s8
	s_addc_u32 s13, s28, s9
	s_add_u32 s12, s12, 0xfe00100
	s_addc_u32 s13, s13, 0
	s_add_u32 s34, s29, s8
	s_addc_u32 s35, s30, s9
	s_add_i32 s36, 0, 0x10000
	s_cmpk_eq_i32 s8, 0x700
	s_cselect_b32 s15, s7, s13
	s_cselect_b32 s14, s6, s12
	v_add_u32_e32 v145, s36, v143
	s_cselect_b32 s13, s5, s35
	s_cselect_b32 s12, s4, s34
	s_add_i32 s37, 0, 0x14000
	ds_read_b128 v[146:149], v145
	ds_read_b128 v[150:153], v145 offset:1024
	ds_read_b128 v[154:157], v145 offset:2048
	ds_read_b128 v[158:161], v145 offset:3072
	v_add_u32_e32 v145, s37, v143
	ds_read_b128 v[162:165], v145
	ds_read_b128 v[166:169], v145 offset:1024
	ds_read_b128 v[170:173], v145 offset:2048
	ds_read_b128 v[174:177], v145 offset:3072
	v_lshl_add_u64 v[186:187], v[138:139], 0, s[8:9]
	s_add_i32 m0, s21, 0xc000
	ds_read_b128 v[178:181], v144
	ds_read_b128 v[182:185], v144 offset:1024
	ds_read_b128 v[202:205], v144 offset:2048
	ds_read_b128 v[206:209], v144 offset:3072
	ds_read_b128 v[210:213], v144 offset:4096
	ds_read_b128 v[232:235], v144 offset:5120
	ds_read_b128 v[236:239], v144 offset:6144
	ds_read_b128 v[240:243], v144 offset:7168
	global_load_lds_dwordx4 v[186:187], off
	v_lshl_add_u64 v[186:187], v[140:141], 0, s[8:9]
	s_add_i32 m0, s21, 0xe000
	s_nop 0
	global_load_lds_dwordx4 v[186:187], off
	s_waitcnt vmcnt(8)
	s_waitcnt lgkmcnt(0)
	s_barrier
	s_setprio 1
	s_waitcnt lgkmcnt(0)
	v_mfma_f32_16x16x32_bf16 v[126:129], v[146:149], v[178:181], v[126:129]
	v_mfma_f32_16x16x32_bf16 v[122:125], v[154:157], v[178:181], v[122:125]
	v_mfma_f32_16x16x32_bf16 v[118:121], v[146:149], v[202:205], v[118:121]
	v_mfma_f32_16x16x32_bf16 v[114:117], v[154:157], v[202:205], v[114:117]
	v_mfma_f32_16x16x32_bf16 v[110:113], v[146:149], v[210:213], v[110:113]
	v_mfma_f32_16x16x32_bf16 v[106:109], v[154:157], v[210:213], v[106:109]
	v_mfma_f32_16x16x32_bf16 v[102:105], v[146:149], v[236:239], v[102:105]
	v_mfma_f32_16x16x32_bf16 v[98:101], v[154:157], v[236:239], v[98:101]
	v_mfma_f32_16x16x32_bf16 v[126:129], v[150:153], v[182:185], v[126:129]
	v_mfma_f32_16x16x32_bf16 v[122:125], v[158:161], v[182:185], v[122:125]
	v_mfma_f32_16x16x32_bf16 v[118:121], v[150:153], v[206:209], v[118:121]
	v_mfma_f32_16x16x32_bf16 v[114:117], v[158:161], v[206:209], v[114:117]
	v_mfma_f32_16x16x32_bf16 v[110:113], v[150:153], v[232:235], v[110:113]
	v_mfma_f32_16x16x32_bf16 v[106:109], v[158:161], v[232:235], v[106:109]
	v_mfma_f32_16x16x32_bf16 v[102:105], v[150:153], v[240:243], v[102:105]
	v_mfma_f32_16x16x32_bf16 v[98:101], v[158:161], v[240:243], v[98:101]
	v_mfma_f32_16x16x32_bf16 v[94:97], v[162:165], v[178:181], v[94:97]
	v_mfma_f32_16x16x32_bf16 v[86:89], v[170:173], v[178:181], v[86:89]
	v_mfma_f32_16x16x32_bf16 v[78:81], v[162:165], v[202:205], v[78:81]
	v_mfma_f32_16x16x32_bf16 v[74:77], v[170:173], v[202:205], v[74:77]
	v_mfma_f32_16x16x32_bf16 v[70:73], v[162:165], v[210:213], v[70:73]
	v_mfma_f32_16x16x32_bf16 v[62:65], v[170:173], v[210:213], v[62:65]
	v_mfma_f32_16x16x32_bf16 v[54:57], v[162:165], v[236:239], v[54:57]
	v_mfma_f32_16x16x32_bf16 v[50:53], v[170:173], v[236:239], v[50:53]
	v_mfma_f32_16x16x32_bf16 v[94:97], v[166:169], v[182:185], v[94:97]
	v_mfma_f32_16x16x32_bf16 v[86:89], v[174:177], v[182:185], v[86:89]
	v_mfma_f32_16x16x32_bf16 v[78:81], v[166:169], v[206:209], v[78:81]
	v_mfma_f32_16x16x32_bf16 v[74:77], v[174:177], v[206:209], v[74:77]
	v_mfma_f32_16x16x32_bf16 v[70:73], v[166:169], v[232:235], v[70:73]
	v_mfma_f32_16x16x32_bf16 v[62:65], v[174:177], v[232:235], v[62:65]
	v_mfma_f32_16x16x32_bf16 v[54:57], v[166:169], v[240:243], v[54:57]
	v_mfma_f32_16x16x32_bf16 v[50:53], v[174:177], v[240:243], v[50:53]
	s_setprio 0
	s_barrier
	s_add_i32 s34, s36, s20
	s_mov_b32 m0, s34
	ds_read_b128 v[178:181], v144 offset:16384
	ds_read_b128 v[182:185], v144 offset:17408
	ds_read_b128 v[202:205], v144 offset:18432
	ds_read_b128 v[206:209], v144 offset:19456
	ds_read_b128 v[210:213], v144 offset:20480
	ds_read_b128 v[232:235], v144 offset:21504
	ds_read_b128 v[236:239], v144 offset:22528
	ds_read_b128 v[240:243], v144 offset:23552
	s_add_u32 s60, s12, 0x80
	s_addc_u32 s61, s13, 0
	s_add_u32 s62, s14, 0x80
	s_addc_u32 s63, s15, 0
	global_load_lds_dwordx4 v134, s[12:13]
	s_add_i32 m0, s34, 0x2000
	s_add_u32 s34, s12, 0x80000
	s_addc_u32 s35, s13, 0
	s_add_i32 s36, s37, s20
	global_load_lds_dwordx4 v130, s[12:13]
	s_mov_b32 m0, s36
	s_nop 0
	global_load_lds_dwordx4 v134, s[34:35]
	s_add_i32 m0, s36, 0x2000
	s_nop 0
	global_load_lds_dwordx4 v130, s[34:35]
	s_mov_b32 m0, s21
	s_nop 0
	global_load_lds_dwordx4 v136, s[14:15]
	s_mov_b32 m0, s22
	s_nop 0
	global_load_lds_dwordx4 v132, s[14:15]
	s_waitcnt vmcnt(8)
	s_waitcnt lgkmcnt(0)
	s_barrier
; #define PG8_STAGE(bufoff, gbase, voff) do { _Pragma("unroll") for (int _i = 0; _i < 2; ++_i) \
;         __builtin_amdgcn_global_load_lds((const unsigned*)((const char*)(gbase) + (voff)[_i]), (PG8_LAS unsigned*)(lds + (bufoff) + ldsw + _i * 8192), 16, 0, 0); } while (0)
; #define PG8_LDA(dst, b, h) do { _Pragma("unroll") for (int m = 0; m < 4; ++m) _Pragma("unroll") for (int k = 0; k < 2; ++k) dst[m][k] = *(const PG8_LAS bf16x8*)(lds + PG8_SA(b, h) + aoff + m * 2048 + k * 1024); } while (0)
; #define PG8_LDB(dst, b, h) do { _Pragma("unroll") for (int n = 0; n < 2; ++n) _Pragma("unroll") for (int k = 0; k < 2; ++k) dst[n][k] = *(const PG8_LAS bf16x8*)(lds + PG8_SB(b, h) + boff + n * 2048 + k * 1024); } while (0)
; #define PG8_MMA(ai, bj, At, Bt) do { __builtin_amdgcn_s_setprio(1); _Pragma("unroll") for (int m = 0; m < 4; ++m) _Pragma("unroll") for (int n = 0; n < 2; ++n) _Pragma("unroll") for (int k = 0; k < 2; ++k) \
;         acc[ai][bj][m][n] = __builtin_amdgcn_mfma_f32_16x16x32_bf16(Bt[n][k], At[m][k], acc[ai][bj][m][n], 0, 0, 0); __builtin_amdgcn_s_setprio(0); } while (0)
; #define PG8_WAIT_V(n) asm volatile("s_waitcnt vmcnt(" #n ")" ::: "memory")
; template <class Epi, class Sched, bool ALIGN_EPI = false, bool SP2 = false>
; __device__ __forceinline__ void gemm_phase(PG8_LAS unsigned char* lds, const Gemm g, const Sched& S, const Epi& E) {
;     ...
;             PG8_LDB(B0, 0, 0); PG8_LDB(B1, 0, 1); PG8_SCHED; PG8_LDA(At, 0, 0); PG8_STAGE(PG8_SA(1, 1), a1 + hstepA, voffA);
;             PG8_WAIT_V(8); PG8_WAIT_L(0); PG8_BAR; PG8_MMA(0, 0, At, B0); PG8_MMA(0, 1, At, B1); PG8_BAR; PG8_SCHED;
;             PG8_LDA(At, 0, 1); PG8_STAGE(PG8_SB(0, 0), b2, voffB); PG8_STAGE(PG8_SB(0, 1), b2 + hstepB, voffB); PG8_STAGE(PG8_SA(0, 0), a2, voffA);
;             PG8_WAIT_V(8); PG8_WAIT_L(0); PG8_BAR; PG8_MMA(1, 0, At, B0); PG8_MMA(1, 1, At, B1); PG8_BAR; PG8_SCHED;
;             PG8_LDB(B0, 1, 0); PG8_LDB(B1, 1, 1); PG8_SCHED; PG8_LDA(At, 1, 0); PG8_STAGE(PG8_SA(0, 1), a2 + hstepA, voffA);
;             PG8_WAIT_V(8); PG8_WAIT_L(0); PG8_BAR; PG8_MMA(0, 0, At, B0); PG8_MMA(0, 1, At, B1); PG8_BAR; PG8_SCHED;
;             PG8_LDA(At, 1, 1); PG8_STAGE(PG8_SB(1, 0), b3, voffB); PG8_STAGE(PG8_SB(1, 1), b3 + hstepB, voffB); PG8_STAGE(PG8_SA(1, 0), a3, voffA);
;             PG8_WAIT_V(8); PG8_WAIT_L(0); PG8_BAR; PG8_MMA(1, 0, At, B0); PG8_MMA(1, 1, At, B1); PG8_BAR; PG8_SCHED;
	s_setprio 1
	s_waitcnt lgkmcnt(0)
	v_mfma_f32_16x16x32_bf16 v[90:93], v[146:149], v[178:181], v[90:93]
	v_mfma_f32_16x16x32_bf16 v[82:85], v[154:157], v[178:181], v[82:85]
	v_mfma_f32_16x16x32_bf16 v[66:69], v[146:149], v[202:205], v[66:69]
	v_mfma_f32_16x16x32_bf16 v[58:61], v[154:157], v[202:205], v[58:61]
	v_mfma_f32_16x16x32_bf16 v[46:49], v[146:149], v[210:213], v[46:49]
	v_mfma_f32_16x16x32_bf16 v[42:45], v[154:157], v[210:213], v[42:45]
	v_mfma_f32_16x16x32_bf16 v[38:41], v[146:149], v[236:239], v[38:41]
	v_mfma_f32_16x16x32_bf16 v[34:37], v[154:157], v[236:239], v[34:37]
	v_mfma_f32_16x16x32_bf16 v[90:93], v[150:153], v[182:185], v[90:93]
	v_mfma_f32_16x16x32_bf16 v[82:85], v[158:161], v[182:185], v[82:85]
	v_mfma_f32_16x16x32_bf16 v[66:69], v[150:153], v[206:209], v[66:69]
	v_mfma_f32_16x16x32_bf16 v[58:61], v[158:161], v[206:209], v[58:61]
	v_mfma_f32_16x16x32_bf16 v[46:49], v[150:153], v[232:235], v[46:49]
	v_mfma_f32_16x16x32_bf16 v[42:45], v[158:161], v[232:235], v[42:45]
	v_mfma_f32_16x16x32_bf16 v[38:41], v[150:153], v[240:243], v[38:41]
	v_mfma_f32_16x16x32_bf16 v[34:37], v[158:161], v[240:243], v[34:37]
	v_mfma_f32_16x16x32_bf16 v[30:33], v[162:165], v[178:181], v[30:33]
	v_mfma_f32_16x16x32_bf16 v[26:29], v[170:173], v[178:181], v[26:29]
	v_mfma_f32_16x16x32_bf16 v[22:25], v[162:165], v[202:205], v[22:25]
	v_mfma_f32_16x16x32_bf16 v[18:21], v[170:173], v[202:205], v[18:21]
	v_mfma_f32_16x16x32_bf16 v[14:17], v[162:165], v[210:213], v[14:17]
	v_mfma_f32_16x16x32_bf16 v[10:13], v[170:173], v[210:213], v[10:13]
	v_mfma_f32_16x16x32_bf16 v[6:9], v[162:165], v[236:239], v[6:9]
	v_mfma_f32_16x16x32_bf16 v[2:5], v[170:173], v[236:239], v[2:5]
	v_mfma_f32_16x16x32_bf16 v[30:33], v[166:169], v[182:185], v[30:33]
	v_mfma_f32_16x16x32_bf16 v[26:29], v[174:177], v[182:185], v[26:29]
	v_mfma_f32_16x16x32_bf16 v[22:25], v[166:169], v[206:209], v[22:25]
	v_mfma_f32_16x16x32_bf16 v[18:21], v[174:177], v[206:209], v[18:21]
	v_mfma_f32_16x16x32_bf16 v[14:17], v[166:169], v[232:235], v[14:17]
	v_mfma_f32_16x16x32_bf16 v[10:13], v[174:177], v[232:235], v[10:13]
	v_mfma_f32_16x16x32_bf16 v[6:9], v[166:169], v[240:243], v[6:9]
	v_mfma_f32_16x16x32_bf16 v[2:5], v[174:177], v[240:243], v[2:5]
	s_setprio 0
	s_barrier
	s_add_i32 s34, 0, 0x18000
	v_add_u32_e32 v145, s34, v143
	s_add_i32 s35, 0, 0x1c000
	ds_read_b128 v[146:149], v145
	ds_read_b128 v[150:153], v145 offset:1024
	ds_read_b128 v[154:157], v145 offset:2048
	ds_read_b128 v[158:161], v145 offset:3072
	v_add_u32_e32 v145, s35, v143
	ds_read_b128 v[162:165], v145
	ds_read_b128 v[166:169], v145 offset:1024
	ds_read_b128 v[170:173], v145 offset:2048
	ds_read_b128 v[174:177], v145 offset:3072
	s_add_u32 s14, s14, 0x40000
	s_addc_u32 s15, s15, 0
	s_mov_b32 m0, s23
	ds_read_b128 v[178:181], v144 offset:32768
	ds_read_b128 v[182:185], v144 offset:33792
	ds_read_b128 v[202:205], v144 offset:34816
	ds_read_b128 v[206:209], v144 offset:35840
	ds_read_b128 v[210:213], v144 offset:36864
	ds_read_b128 v[232:235], v144 offset:37888
	ds_read_b128 v[236:239], v144 offset:38912
	ds_read_b128 v[240:243], v144 offset:39936
	global_load_lds_dwordx4 v136, s[14:15]
	s_mov_b32 m0, s24
	s_nop 0
	global_load_lds_dwordx4 v132, s[14:15]
	s_waitcnt vmcnt(8)
	s_waitcnt lgkmcnt(0)
	s_barrier
	s_setprio 1
	s_waitcnt lgkmcnt(0)
	v_mfma_f32_16x16x32_bf16 v[126:129], v[146:149], v[178:181], v[126:129]
	v_mfma_f32_16x16x32_bf16 v[122:125], v[154:157], v[178:181], v[122:125]
	v_mfma_f32_16x16x32_bf16 v[118:121], v[146:149], v[202:205], v[118:121]
	v_mfma_f32_16x16x32_bf16 v[114:117], v[154:157], v[202:205], v[114:117]
	v_mfma_f32_16x16x32_bf16 v[110:113], v[146:149], v[210:213], v[110:113]
	v_mfma_f32_16x16x32_bf16 v[106:109], v[154:157], v[210:213], v[106:109]
	v_mfma_f32_16x16x32_bf16 v[102:105], v[146:149], v[236:239], v[102:105]
	v_mfma_f32_16x16x32_bf16 v[98:101], v[154:157], v[236:239], v[98:101]
	v_mfma_f32_16x16x32_bf16 v[126:129], v[150:153], v[182:185], v[126:129]
	v_mfma_f32_16x16x32_bf16 v[122:125], v[158:161], v[182:185], v[122:125]
	v_mfma_f32_16x16x32_bf16 v[118:121], v[150:153], v[206:209], v[118:121]
	v_mfma_f32_16x16x32_bf16 v[114:117], v[158:161], v[206:209], v[114:117]
	v_mfma_f32_16x16x32_bf16 v[110:113], v[150:153], v[232:235], v[110:113]
	v_mfma_f32_16x16x32_bf16 v[106:109], v[158:161], v[232:235], v[106:109]
	v_mfma_f32_16x16x32_bf16 v[102:105], v[150:153], v[240:243], v[102:105]
	v_mfma_f32_16x16x32_bf16 v[98:101], v[158:161], v[240:243], v[98:101]
	v_mfma_f32_16x16x32_bf16 v[94:97], v[162:165], v[178:181], v[94:97]
	v_mfma_f32_16x16x32_bf16 v[86:89], v[170:173], v[178:181], v[86:89]
	v_mfma_f32_16x16x32_bf16 v[78:81], v[162:165], v[202:205], v[78:81]
	v_mfma_f32_16x16x32_bf16 v[74:77], v[170:173], v[202:205], v[74:77]
	v_mfma_f32_16x16x32_bf16 v[70:73], v[162:165], v[210:213], v[70:73]
	v_mfma_f32_16x16x32_bf16 v[62:65], v[170:173], v[210:213], v[62:65]
	v_mfma_f32_16x16x32_bf16 v[54:57], v[162:165], v[236:239], v[54:57]
	v_mfma_f32_16x16x32_bf16 v[50:53], v[170:173], v[236:239], v[50:53]
	v_mfma_f32_16x16x32_bf16 v[94:97], v[166:169], v[182:185], v[94:97]
	v_mfma_f32_16x16x32_bf16 v[86:89], v[174:177], v[182:185], v[86:89]
	v_mfma_f32_16x16x32_bf16 v[78:81], v[166:169], v[206:209], v[78:81]
	v_mfma_f32_16x16x32_bf16 v[74:77], v[174:177], v[206:209], v[74:77]
	v_mfma_f32_16x16x32_bf16 v[70:73], v[166:169], v[232:235], v[70:73]
	v_mfma_f32_16x16x32_bf16 v[62:65], v[174:177], v[232:235], v[62:65]
	v_mfma_f32_16x16x32_bf16 v[54:57], v[166:169], v[240:243], v[54:57]
	v_mfma_f32_16x16x32_bf16 v[50:53], v[174:177], v[240:243], v[50:53]
	s_setprio 0
	s_barrier
; #define PG8_STAGE(bufoff, gbase, voff) do { _Pragma("unroll") for (int _i = 0; _i < 2; ++_i) \
;         __builtin_amdgcn_global_load_lds((const unsigned*)((const char*)(gbase) + (voff)[_i]), (PG8_LAS unsigned*)(lds + (bufoff) + ldsw + _i * 8192), 16, 0, 0); } while (0)
; #define PG8_LDA(dst, b, h) do { _Pragma("unroll") for (int m = 0; m < 4; ++m) _Pragma("unroll") for (int k = 0; k < 2; ++k) dst[m][k] = *(const PG8_LAS bf16x8*)(lds + PG8_SA(b, h) + aoff + m * 2048 + k * 1024); } while (0)
; #define PG8_MMA(ai, bj, At, Bt) do { __builtin_amdgcn_s_setprio(1); _Pragma("unroll") for (int m = 0; m < 4; ++m) _Pragma("unroll") for (int n = 0; n < 2; ++n) _Pragma("unroll") for (int k = 0; k < 2; ++k) \
;         acc[ai][bj][m][n] = __builtin_amdgcn_mfma_f32_16x16x32_bf16(Bt[n][k], At[m][k], acc[ai][bj][m][n], 0, 0, 0); __builtin_amdgcn_s_setprio(0); } while (0)
; #define PG8_WAIT_V(n) asm volatile("s_waitcnt vmcnt(" #n ")" ::: "memory")
; #define PG8_WAIT_L(n) asm volatile("s_waitcnt lgkmcnt(" #n ")" ::: "memory")
; #define PG8_BAR __builtin_amdgcn_s_barrier()
; #define PG8_SCHED __builtin_amdgcn_sched_barrier(0)
; template <class Epi, class Sched, bool ALIGN_EPI = false, bool SP2 = false>
; __device__ __forceinline__ void gemm_phase(PG8_LAS unsigned char* lds, const Gemm g, const Sched& S, const Epi& E) {
;     ...
;             PG8_LDA(At, 1, 1); PG8_STAGE(PG8_SB(1, 0), b3, voffB); PG8_STAGE(PG8_SB(1, 1), b3 + hstepB, voffB); PG8_STAGE(PG8_SA(1, 0), a3, voffA);
;             PG8_WAIT_V(8); PG8_WAIT_L(0); PG8_BAR; PG8_MMA(1, 0, At, B0); PG8_MMA(1, 1, At, B1); PG8_BAR; PG8_SCHED;
;     ...
;         if constexpr (ALIGN_EPI) { if (wr == 0) PG8_BAR; }
	s_add_i32 s14, s34, s20
	s_mov_b32 m0, s14
	ds_read_b128 v[178:181], v144 offset:49152
	ds_read_b128 v[182:185], v144 offset:50176
	ds_read_b128 v[202:205], v144 offset:51200
	ds_read_b128 v[206:209], v144 offset:52224
	ds_read_b128 v[210:213], v144 offset:53248
	ds_read_b128 v[232:235], v144 offset:54272
	ds_read_b128 v[236:239], v144 offset:55296
	ds_read_b128 v[240:243], v144 offset:56320
	global_load_lds_dwordx4 v134, s[60:61]
	s_add_i32 m0, s14, 0x2000
	s_add_u32 s12, s12, 0x80080
	s_addc_u32 s13, s13, 0
	s_add_i32 s14, s35, s20
	global_load_lds_dwordx4 v130, s[60:61]
	s_mov_b32 m0, s14
	s_nop 0
	global_load_lds_dwordx4 v134, s[12:13]
	s_add_i32 m0, s14, 0x2000
	s_nop 0
	global_load_lds_dwordx4 v130, s[12:13]
	s_mov_b32 m0, s26
	s_nop 0
	global_load_lds_dwordx4 v136, s[62:63]
	s_mov_b32 m0, s27
	s_nop 0
	global_load_lds_dwordx4 v132, s[62:63]
	s_waitcnt vmcnt(8)
	s_waitcnt lgkmcnt(0)
	s_barrier
	s_setprio 1
	s_waitcnt lgkmcnt(0)
	v_mfma_f32_16x16x32_bf16 v[90:93], v[146:149], v[178:181], v[90:93]
	v_mfma_f32_16x16x32_bf16 v[82:85], v[154:157], v[178:181], v[82:85]
	v_mfma_f32_16x16x32_bf16 v[66:69], v[146:149], v[202:205], v[66:69]
	v_mfma_f32_16x16x32_bf16 v[58:61], v[154:157], v[202:205], v[58:61]
	v_mfma_f32_16x16x32_bf16 v[46:49], v[146:149], v[210:213], v[46:49]
	v_mfma_f32_16x16x32_bf16 v[42:45], v[154:157], v[210:213], v[42:45]
	v_mfma_f32_16x16x32_bf16 v[38:41], v[146:149], v[236:239], v[38:41]
	v_mfma_f32_16x16x32_bf16 v[34:37], v[154:157], v[236:239], v[34:37]
	v_mfma_f32_16x16x32_bf16 v[90:93], v[150:153], v[182:185], v[90:93]
	v_mfma_f32_16x16x32_bf16 v[82:85], v[158:161], v[182:185], v[82:85]
	v_mfma_f32_16x16x32_bf16 v[66:69], v[150:153], v[206:209], v[66:69]
	v_mfma_f32_16x16x32_bf16 v[58:61], v[158:161], v[206:209], v[58:61]
	v_mfma_f32_16x16x32_bf16 v[46:49], v[150:153], v[232:235], v[46:49]
	v_mfma_f32_16x16x32_bf16 v[42:45], v[158:161], v[232:235], v[42:45]
	v_mfma_f32_16x16x32_bf16 v[38:41], v[150:153], v[240:243], v[38:41]
	v_mfma_f32_16x16x32_bf16 v[34:37], v[158:161], v[240:243], v[34:37]
	v_mfma_f32_16x16x32_bf16 v[30:33], v[162:165], v[178:181], v[30:33]
	v_mfma_f32_16x16x32_bf16 v[26:29], v[170:173], v[178:181], v[26:29]
	v_mfma_f32_16x16x32_bf16 v[22:25], v[162:165], v[202:205], v[22:25]
	v_mfma_f32_16x16x32_bf16 v[18:21], v[170:173], v[202:205], v[18:21]
	v_mfma_f32_16x16x32_bf16 v[14:17], v[162:165], v[210:213], v[14:17]
	v_mfma_f32_16x16x32_bf16 v[10:13], v[170:173], v[210:213], v[10:13]
	v_mfma_f32_16x16x32_bf16 v[6:9], v[162:165], v[236:239], v[6:9]
	v_mfma_f32_16x16x32_bf16 v[2:5], v[170:173], v[236:239], v[2:5]
	v_mfma_f32_16x16x32_bf16 v[30:33], v[166:169], v[182:185], v[30:33]
	v_mfma_f32_16x16x32_bf16 v[26:29], v[174:177], v[182:185], v[26:29]
	v_mfma_f32_16x16x32_bf16 v[22:25], v[166:169], v[206:209], v[22:25]
	v_mfma_f32_16x16x32_bf16 v[18:21], v[174:177], v[206:209], v[18:21]
	v_mfma_f32_16x16x32_bf16 v[14:17], v[166:169], v[232:235], v[14:17]
	v_mfma_f32_16x16x32_bf16 v[10:13], v[174:177], v[232:235], v[10:13]
	v_mfma_f32_16x16x32_bf16 v[6:9], v[166:169], v[240:243], v[6:9]
	v_mfma_f32_16x16x32_bf16 v[2:5], v[174:177], v[240:243], v[2:5]
	s_setprio 0
	s_barrier
	s_add_i32 s31, s31, 2
	s_add_u32 s8, s8, 0x100
	s_addc_u32 s9, s9, 0
	s_cmp_gt_u32 s31, 13
	s_cbranch_scc0 .LBB0_530
	s_cmpk_lt_u32 s19, 0x100
	s_cbranch_scc0 .LBB0_533
	s_barrier

; #define PG8_STAGE(bufoff, gbase, voff) do { _Pragma("unroll") for (int _i = 0; _i < 2; ++_i) \
;         __builtin_amdgcn_global_load_lds((const unsigned*)((const char*)(gbase) + (voff)[_i]), (PG8_LAS unsigned*)(lds + (bufoff) + ldsw + _i * 8192), 16, 0, 0); } while (0)
; #define PG8_LDA(dst, b, h) do { _Pragma("unroll") for (int m = 0; m < 4; ++m) _Pragma("unroll") for (int k = 0; k < 2; ++k) dst[m][k] = *(const PG8_LAS bf16x8*)(lds + PG8_SA(b, h) + aoff + m * 2048 + k * 1024); } while (0)
; #define PG8_LDB(dst, b, h) do { _Pragma("unroll") for (int n = 0; n < 2; ++n) _Pragma("unroll") for (int k = 0; k < 2; ++k) dst[n][k] = *(const PG8_LAS bf16x8*)(lds + PG8_SB(b, h) + boff + n * 2048 + k * 1024); } while (0)
; template <class Epi, class Sched, bool ALIGN_EPI = false, bool SP2 = false>
; __device__ __forceinline__ void gemm_phase(PG8_LAS unsigned char* lds, const Gemm g, const Sched& S, const Epi& E) {
;     ...
;         for (int t = 0; t < nt; t += 2) {
;             const bool last = (t == nt - 2);
;             const char* a1 = cA + (size_t)(t + 1) * kstep;
;             const char* a2 = last ? nA : cA + (size_t)(t + 2) * kstep; const char* b2 = last ? nB : cB + (size_t)(t + 2) * kstep;
;             const char* a3 = a2 + kstep; const char* b3 = b2 + kstep;
;             if (last && has_next) S.a_ready(nxt);
;             if constexpr (SP2) {
;             PG8_LDB(B0, 0, 0); PG8_LDB(B1, 0, 1); PG8_SCHED; PG8_LDA(At, 0, 0); PG8_STAGE(PG8_SA(1, 1), a1 + hstepA, voffA);
;             PG8_WAIT_V(8); PG8_WAIT_L(0); PG8_BAR; PG8_MMA(0, 0, At, B0); PG8_MMA(0, 1, At, B1); PG8_BAR; PG8_SCHED;
;             PG8_LDA(At, 0, 1); PG8_STAGE(PG8_SB(0, 0), b2, voffB); PG8_STAGE(PG8_SB(0, 1), b2 + hstepB, voffB); PG8_STAGE(PG8_SA(0, 0), a2, voffA);
;             PG8_WAIT_V(8); PG8_WAIT_L(0); PG8_BAR; PG8_MMA(1, 0, At, B0); PG8_MMA(1, 1, At, B1); PG8_BAR; PG8_SCHED;
;             PG8_LDB(B0, 1, 0); PG8_LDB(B1, 1, 1); PG8_SCHED; PG8_LDA(At, 1, 0); PG8_STAGE(PG8_SA(0, 1), a2 + hstepA, voffA);
;             PG8_WAIT_V(8); PG8_WAIT_L(0); PG8_BAR; PG8_MMA(0, 0, At, B0); PG8_MMA(0, 1, At, B1); PG8_BAR; PG8_SCHED;
;             PG8_LDA(At, 1, 1); PG8_STAGE(PG8_SB(1, 0), b3, voffB); PG8_STAGE(PG8_SB(1, 1), b3 + hstepB, voffB); PG8_STAGE(PG8_SA(1, 0), a3, voffA);
;             PG8_WAIT_V(8); PG8_WAIT_L(0); PG8_BAR; PG8_MMA(1, 0, At, B0); PG8_MMA(1, 1, At, B1); PG8_BAR; PG8_SCHED;
.LBB0_1160:
	s_add_u32 s24, s22, 0x100
	s_addc_u32 s25, s23, 0
	s_add_i32 s57, 0, 0x10000
	s_cmp_eq_u32 s56, 4
	s_cselect_b32 s29, s17, s25
	s_cselect_b32 s28, s16, s24
	v_add_u32_e32 v145, s57, v142
	s_cselect_b32 s27, s52, s55
	s_cselect_b32 s26, s53, s54
	s_add_i32 s58, 0, 0x14000
	ds_read_b128 v[146:149], v145
	ds_read_b128 v[150:153], v145 offset:1024
	ds_read_b128 v[154:157], v145 offset:2048
	ds_read_b128 v[158:161], v145 offset:3072
	v_add_u32_e32 v145, s58, v142
	ds_read_b128 v[162:165], v145
	ds_read_b128 v[166:169], v145 offset:1024
	ds_read_b128 v[170:173], v145 offset:2048
	ds_read_b128 v[174:177], v145 offset:3072
	s_add_i32 m0, s39, 0xc000
	ds_read_b128 v[178:181], v143
	ds_read_b128 v[182:185], v143 offset:1024
	ds_read_b128 v[202:205], v143 offset:2048
	ds_read_b128 v[206:209], v143 offset:3072
	ds_read_b128 v[210:213], v143 offset:4096
	ds_read_b128 v[232:235], v143 offset:5120
	ds_read_b128 v[236:239], v143 offset:6144
	ds_read_b128 v[240:243], v143 offset:7168
	global_load_lds_dwordx4 v138, s[22:23]
	s_add_i32 m0, s39, 0xe000
	s_nop 0
	global_load_lds_dwordx4 v140, s[22:23]
	s_waitcnt vmcnt(8)
	s_waitcnt lgkmcnt(0)
	s_barrier
	s_setprio 1
	s_waitcnt lgkmcnt(0)
	v_mfma_f32_16x16x32_bf16 v[126:129], v[146:149], v[178:181], v[126:129]
	v_mfma_f32_16x16x32_bf16 v[122:125], v[154:157], v[178:181], v[122:125]
	v_mfma_f32_16x16x32_bf16 v[118:121], v[146:149], v[202:205], v[118:121]
	v_mfma_f32_16x16x32_bf16 v[114:117], v[154:157], v[202:205], v[114:117]
	v_mfma_f32_16x16x32_bf16 v[110:113], v[146:149], v[210:213], v[110:113]
	v_mfma_f32_16x16x32_bf16 v[106:109], v[154:157], v[210:213], v[106:109]
	v_mfma_f32_16x16x32_bf16 v[102:105], v[146:149], v[236:239], v[102:105]
	v_mfma_f32_16x16x32_bf16 v[98:101], v[154:157], v[236:239], v[98:101]
	v_mfma_f32_16x16x32_bf16 v[126:129], v[150:153], v[182:185], v[126:129]
	v_mfma_f32_16x16x32_bf16 v[122:125], v[158:161], v[182:185], v[122:125]
	v_mfma_f32_16x16x32_bf16 v[118:121], v[150:153], v[206:209], v[118:121]
	v_mfma_f32_16x16x32_bf16 v[114:117], v[158:161], v[206:209], v[114:117]
	v_mfma_f32_16x16x32_bf16 v[110:113], v[150:153], v[232:235], v[110:113]
	v_mfma_f32_16x16x32_bf16 v[106:109], v[158:161], v[232:235], v[106:109]
	v_mfma_f32_16x16x32_bf16 v[102:105], v[150:153], v[240:243], v[102:105]
	v_mfma_f32_16x16x32_bf16 v[98:101], v[158:161], v[240:243], v[98:101]
	v_mfma_f32_16x16x32_bf16 v[78:81], v[162:165], v[178:181], v[78:81]
	v_mfma_f32_16x16x32_bf16 v[70:73], v[170:173], v[178:181], v[70:73]
	v_mfma_f32_16x16x32_bf16 v[62:65], v[162:165], v[202:205], v[62:65]
	v_mfma_f32_16x16x32_bf16 v[54:57], v[170:173], v[202:205], v[54:57]
	v_mfma_f32_16x16x32_bf16 v[46:49], v[162:165], v[210:213], v[46:49]
	v_mfma_f32_16x16x32_bf16 v[42:45], v[170:173], v[210:213], v[42:45]
	v_mfma_f32_16x16x32_bf16 v[38:41], v[162:165], v[236:239], v[38:41]
	v_mfma_f32_16x16x32_bf16 v[34:37], v[170:173], v[236:239], v[34:37]
	v_mfma_f32_16x16x32_bf16 v[78:81], v[166:169], v[182:185], v[78:81]
	v_mfma_f32_16x16x32_bf16 v[70:73], v[174:177], v[182:185], v[70:73]
	v_mfma_f32_16x16x32_bf16 v[62:65], v[166:169], v[206:209], v[62:65]
	v_mfma_f32_16x16x32_bf16 v[54:57], v[174:177], v[206:209], v[54:57]
	v_mfma_f32_16x16x32_bf16 v[46:49], v[166:169], v[232:235], v[46:49]
	v_mfma_f32_16x16x32_bf16 v[42:45], v[174:177], v[232:235], v[42:45]
	v_mfma_f32_16x16x32_bf16 v[38:41], v[166:169], v[240:243], v[38:41]
	v_mfma_f32_16x16x32_bf16 v[34:37], v[174:177], v[240:243], v[34:37]
	s_setprio 0
	s_barrier
	s_add_i32 s22, s57, s38
	s_mov_b32 m0, s22
	ds_read_b128 v[178:181], v143 offset:16384
	ds_read_b128 v[182:185], v143 offset:17408
	ds_read_b128 v[202:205], v143 offset:18432
	ds_read_b128 v[206:209], v143 offset:19456
	ds_read_b128 v[210:213], v143 offset:20480
	ds_read_b128 v[232:235], v143 offset:21504
	ds_read_b128 v[236:239], v143 offset:22528
	ds_read_b128 v[240:243], v143 offset:23552
	s_add_u32 s60, s26, 0x80
	s_addc_u32 s61, s27, 0
	s_add_u32 s62, s28, 0x80
	s_addc_u32 s63, s29, 0
	global_load_lds_dwordx4 v134, s[26:27]
	s_add_i32 m0, s22, 0x2000
	s_add_u32 s22, s26, 0x20000
	s_addc_u32 s23, s27, 0
	s_add_i32 s57, s58, s38
	global_load_lds_dwordx4 v130, s[26:27]
	s_mov_b32 m0, s57
	s_nop 0
	global_load_lds_dwordx4 v134, s[22:23]
	s_add_i32 m0, s57, 0x2000
	s_nop 0
	global_load_lds_dwordx4 v130, s[22:23]
	s_mov_b32 m0, s39
	s_nop 0
	global_load_lds_dwordx4 v136, s[28:29]
	s_mov_b32 m0, s40
	s_nop 0
	global_load_lds_dwordx4 v132, s[28:29]
	s_waitcnt vmcnt(8)
	s_waitcnt lgkmcnt(0)
	s_barrier
	s_setprio 1
	s_waitcnt lgkmcnt(0)
	v_mfma_f32_16x16x32_bf16 v[94:97], v[146:149], v[178:181], v[94:97]
	v_mfma_f32_16x16x32_bf16 v[90:93], v[154:157], v[178:181], v[90:93]
	v_mfma_f32_16x16x32_bf16 v[86:89], v[146:149], v[202:205], v[86:89]
	v_mfma_f32_16x16x32_bf16 v[82:85], v[154:157], v[202:205], v[82:85]
	v_mfma_f32_16x16x32_bf16 v[74:77], v[146:149], v[210:213], v[74:77]
	v_mfma_f32_16x16x32_bf16 v[66:69], v[154:157], v[210:213], v[66:69]
	v_mfma_f32_16x16x32_bf16 v[58:61], v[146:149], v[236:239], v[58:61]
	v_mfma_f32_16x16x32_bf16 v[50:53], v[154:157], v[236:239], v[50:53]
	v_mfma_f32_16x16x32_bf16 v[94:97], v[150:153], v[182:185], v[94:97]
	v_mfma_f32_16x16x32_bf16 v[90:93], v[158:161], v[182:185], v[90:93]
	v_mfma_f32_16x16x32_bf16 v[86:89], v[150:153], v[206:209], v[86:89]
	v_mfma_f32_16x16x32_bf16 v[82:85], v[158:161], v[206:209], v[82:85]
	v_mfma_f32_16x16x32_bf16 v[74:77], v[150:153], v[232:235], v[74:77]
	v_mfma_f32_16x16x32_bf16 v[66:69], v[158:161], v[232:235], v[66:69]
	v_mfma_f32_16x16x32_bf16 v[58:61], v[150:153], v[240:243], v[58:61]
	v_mfma_f32_16x16x32_bf16 v[50:53], v[158:161], v[240:243], v[50:53]
	v_mfma_f32_16x16x32_bf16 v[30:33], v[162:165], v[178:181], v[30:33]
	v_mfma_f32_16x16x32_bf16 v[26:29], v[170:173], v[178:181], v[26:29]
	v_mfma_f32_16x16x32_bf16 v[22:25], v[162:165], v[202:205], v[22:25]
	v_mfma_f32_16x16x32_bf16 v[18:21], v[170:173], v[202:205], v[18:21]
	v_mfma_f32_16x16x32_bf16 v[14:17], v[162:165], v[210:213], v[14:17]
	v_mfma_f32_16x16x32_bf16 v[10:13], v[170:173], v[210:213], v[10:13]
	v_mfma_f32_16x16x32_bf16 v[6:9], v[162:165], v[236:239], v[6:9]
	v_mfma_f32_16x16x32_bf16 v[2:5], v[170:173], v[236:239], v[2:5]
	v_mfma_f32_16x16x32_bf16 v[30:33], v[166:169], v[182:185], v[30:33]
	v_mfma_f32_16x16x32_bf16 v[26:29], v[174:177], v[182:185], v[26:29]
	v_mfma_f32_16x16x32_bf16 v[22:25], v[166:169], v[206:209], v[22:25]
	v_mfma_f32_16x16x32_bf16 v[18:21], v[174:177], v[206:209], v[18:21]
	v_mfma_f32_16x16x32_bf16 v[14:17], v[166:169], v[232:235], v[14:17]
	v_mfma_f32_16x16x32_bf16 v[10:13], v[174:177], v[232:235], v[10:13]
	v_mfma_f32_16x16x32_bf16 v[6:9], v[166:169], v[240:243], v[6:9]
	v_mfma_f32_16x16x32_bf16 v[2:5], v[174:177], v[240:243], v[2:5]
	s_setprio 0
	s_barrier
; #define PG8_STAGE(bufoff, gbase, voff) do { _Pragma("unroll") for (int _i = 0; _i < 2; ++_i) \
;         __builtin_amdgcn_global_load_lds((const unsigned*)((const char*)(gbase) + (voff)[_i]), (PG8_LAS unsigned*)(lds + (bufoff) + ldsw + _i * 8192), 16, 0, 0); } while (0)
; #define PG8_LDA(dst, b, h) do { _Pragma("unroll") for (int m = 0; m < 4; ++m) _Pragma("unroll") for (int k = 0; k < 2; ++k) dst[m][k] = *(const PG8_LAS bf16x8*)(lds + PG8_SA(b, h) + aoff + m * 2048 + k * 1024); } while (0)
; #define PG8_LDB(dst, b, h) do { _Pragma("unroll") for (int n = 0; n < 2; ++n) _Pragma("unroll") for (int k = 0; k < 2; ++k) dst[n][k] = *(const PG8_LAS bf16x8*)(lds + PG8_SB(b, h) + boff + n * 2048 + k * 1024); } while (0)
; #define PG8_MMA(ai, bj, At, Bt) do { __builtin_amdgcn_s_setprio(1); _Pragma("unroll") for (int m = 0; m < 4; ++m) _Pragma("unroll") for (int n = 0; n < 2; ++n) _Pragma("unroll") for (int k = 0; k < 2; ++k) \
;         acc[ai][bj][m][n] = __builtin_amdgcn_mfma_f32_16x16x32_bf16(Bt[n][k], At[m][k], acc[ai][bj][m][n], 0, 0, 0); __builtin_amdgcn_s_setprio(0); } while (0)
; #define PG8_WAIT_V(n) asm volatile("s_waitcnt vmcnt(" #n ")" ::: "memory")
; template <class Epi, class Sched, bool ALIGN_EPI = false, bool SP2 = false>
; __device__ __forceinline__ void gemm_phase(PG8_LAS unsigned char* lds, const Gemm g, const Sched& S, const Epi& E) {
;     ...
;             PG8_LDB(B0, 0, 0); PG8_LDB(B1, 0, 1); PG8_SCHED; PG8_LDA(At, 0, 0); PG8_STAGE(PG8_SA(1, 1), a1 + hstepA, voffA);
;             PG8_WAIT_V(8); PG8_WAIT_L(0); PG8_BAR; PG8_MMA(0, 0, At, B0); PG8_MMA(0, 1, At, B1); PG8_BAR; PG8_SCHED;
;             PG8_LDA(At, 0, 1); PG8_STAGE(PG8_SB(0, 0), b2, voffB); PG8_STAGE(PG8_SB(0, 1), b2 + hstepB, voffB); PG8_STAGE(PG8_SA(0, 0), a2, voffA);
;             PG8_WAIT_V(8); PG8_WAIT_L(0); PG8_BAR; PG8_MMA(1, 0, At, B0); PG8_MMA(1, 1, At, B1); PG8_BAR; PG8_SCHED;
;             PG8_LDB(B0, 1, 0); PG8_LDB(B1, 1, 1); PG8_SCHED; PG8_LDA(At, 1, 0); PG8_STAGE(PG8_SA(0, 1), a2 + hstepA, voffA);
;             PG8_WAIT_V(8); PG8_WAIT_L(0); PG8_BAR; PG8_MMA(0, 0, At, B0); PG8_MMA(0, 1, At, B1); PG8_BAR; PG8_SCHED;
;             PG8_LDA(At, 1, 1); PG8_STAGE(PG8_SB(1, 0), b3, voffB); PG8_STAGE(PG8_SB(1, 1), b3 + hstepB, voffB); PG8_STAGE(PG8_SA(1, 0), a3, voffA);
;             PG8_WAIT_V(8); PG8_WAIT_L(0); PG8_BAR; PG8_MMA(1, 0, At, B0); PG8_MMA(1, 1, At, B1); PG8_BAR; PG8_SCHED;
	s_add_i32 s57, 0, 0x18000
	v_add_u32_e32 v145, s57, v142
	s_add_i32 s58, 0, 0x1c000
	ds_read_b128 v[146:149], v145
	ds_read_b128 v[150:153], v145 offset:1024
	ds_read_b128 v[154:157], v145 offset:2048
	ds_read_b128 v[158:161], v145 offset:3072
	v_add_u32_e32 v145, s58, v142
	ds_read_b128 v[162:165], v145
	ds_read_b128 v[166:169], v145 offset:1024
	ds_read_b128 v[170:173], v145 offset:2048
	ds_read_b128 v[174:177], v145 offset:3072
	s_add_u32 s22, s28, 0x30000
	s_addc_u32 s23, s29, 0
	s_mov_b32 m0, s41
	ds_read_b128 v[178:181], v143 offset:32768
	ds_read_b128 v[182:185], v143 offset:33792
	ds_read_b128 v[202:205], v143 offset:34816
	ds_read_b128 v[206:209], v143 offset:35840
	ds_read_b128 v[210:213], v143 offset:36864
	ds_read_b128 v[232:235], v143 offset:37888
	ds_read_b128 v[236:239], v143 offset:38912
	ds_read_b128 v[240:243], v143 offset:39936
	global_load_lds_dwordx4 v136, s[22:23]
	s_mov_b32 m0, s42
	s_nop 0
	global_load_lds_dwordx4 v132, s[22:23]
	s_waitcnt vmcnt(8)
	s_waitcnt lgkmcnt(0)
	s_barrier
	s_setprio 1
	s_waitcnt lgkmcnt(0)
	v_mfma_f32_16x16x32_bf16 v[126:129], v[146:149], v[178:181], v[126:129]
	v_mfma_f32_16x16x32_bf16 v[122:125], v[154:157], v[178:181], v[122:125]
	v_mfma_f32_16x16x32_bf16 v[118:121], v[146:149], v[202:205], v[118:121]
	v_mfma_f32_16x16x32_bf16 v[114:117], v[154:157], v[202:205], v[114:117]
	v_mfma_f32_16x16x32_bf16 v[110:113], v[146:149], v[210:213], v[110:113]
	v_mfma_f32_16x16x32_bf16 v[106:109], v[154:157], v[210:213], v[106:109]
	v_mfma_f32_16x16x32_bf16 v[102:105], v[146:149], v[236:239], v[102:105]
	v_mfma_f32_16x16x32_bf16 v[98:101], v[154:157], v[236:239], v[98:101]
	v_mfma_f32_16x16x32_bf16 v[126:129], v[150:153], v[182:185], v[126:129]
	v_mfma_f32_16x16x32_bf16 v[122:125], v[158:161], v[182:185], v[122:125]
	v_mfma_f32_16x16x32_bf16 v[118:121], v[150:153], v[206:209], v[118:121]
	v_mfma_f32_16x16x32_bf16 v[114:117], v[158:161], v[206:209], v[114:117]
	v_mfma_f32_16x16x32_bf16 v[110:113], v[150:153], v[232:235], v[110:113]
	v_mfma_f32_16x16x32_bf16 v[106:109], v[158:161], v[232:235], v[106:109]
	v_mfma_f32_16x16x32_bf16 v[102:105], v[150:153], v[240:243], v[102:105]
	v_mfma_f32_16x16x32_bf16 v[98:101], v[158:161], v[240:243], v[98:101]
	v_mfma_f32_16x16x32_bf16 v[78:81], v[162:165], v[178:181], v[78:81]
	v_mfma_f32_16x16x32_bf16 v[70:73], v[170:173], v[178:181], v[70:73]
	v_mfma_f32_16x16x32_bf16 v[62:65], v[162:165], v[202:205], v[62:65]
	v_mfma_f32_16x16x32_bf16 v[54:57], v[170:173], v[202:205], v[54:57]
	v_mfma_f32_16x16x32_bf16 v[46:49], v[162:165], v[210:213], v[46:49]
	v_mfma_f32_16x16x32_bf16 v[42:45], v[170:173], v[210:213], v[42:45]
	v_mfma_f32_16x16x32_bf16 v[38:41], v[162:165], v[236:239], v[38:41]
	v_mfma_f32_16x16x32_bf16 v[34:37], v[170:173], v[236:239], v[34:37]
	v_mfma_f32_16x16x32_bf16 v[78:81], v[166:169], v[182:185], v[78:81]
	v_mfma_f32_16x16x32_bf16 v[70:73], v[174:177], v[182:185], v[70:73]
	v_mfma_f32_16x16x32_bf16 v[62:65], v[166:169], v[206:209], v[62:65]
	v_mfma_f32_16x16x32_bf16 v[54:57], v[174:177], v[206:209], v[54:57]
	v_mfma_f32_16x16x32_bf16 v[46:49], v[166:169], v[232:235], v[46:49]
	v_mfma_f32_16x16x32_bf16 v[42:45], v[174:177], v[232:235], v[42:45]
	v_mfma_f32_16x16x32_bf16 v[38:41], v[166:169], v[240:243], v[38:41]
	v_mfma_f32_16x16x32_bf16 v[34:37], v[174:177], v[240:243], v[34:37]
	s_setprio 0
	s_barrier
	s_add_i32 s22, s57, s38
	s_mov_b32 m0, s22
	ds_read_b128 v[178:181], v143 offset:49152
	ds_read_b128 v[182:185], v143 offset:50176
	ds_read_b128 v[202:205], v143 offset:51200
	ds_read_b128 v[206:209], v143 offset:52224
	ds_read_b128 v[210:213], v143 offset:53248
	ds_read_b128 v[232:235], v143 offset:54272
	ds_read_b128 v[236:239], v143 offset:55296
	ds_read_b128 v[240:243], v143 offset:56320
	global_load_lds_dwordx4 v134, s[60:61]
	s_add_i32 m0, s22, 0x2000
	s_add_u32 s22, s26, 0x20080
	s_addc_u32 s23, s27, 0
	s_add_i32 s26, s58, s38
	global_load_lds_dwordx4 v130, s[60:61]
	s_mov_b32 m0, s26
	s_nop 0
	global_load_lds_dwordx4 v134, s[22:23]
	s_add_i32 m0, s26, 0x2000
	s_nop 0
	global_load_lds_dwordx4 v130, s[22:23]
	s_mov_b32 m0, s43
	s_nop 0
	global_load_lds_dwordx4 v136, s[62:63]
	s_mov_b32 m0, s46
	s_nop 0
	global_load_lds_dwordx4 v132, s[62:63]
	s_waitcnt vmcnt(8)
	s_waitcnt lgkmcnt(0)
	s_barrier
	s_setprio 1
	s_waitcnt lgkmcnt(0)
	v_mfma_f32_16x16x32_bf16 v[94:97], v[146:149], v[178:181], v[94:97]
	v_mfma_f32_16x16x32_bf16 v[90:93], v[154:157], v[178:181], v[90:93]
	v_mfma_f32_16x16x32_bf16 v[86:89], v[146:149], v[202:205], v[86:89]
	v_mfma_f32_16x16x32_bf16 v[82:85], v[154:157], v[202:205], v[82:85]
	v_mfma_f32_16x16x32_bf16 v[74:77], v[146:149], v[210:213], v[74:77]
	v_mfma_f32_16x16x32_bf16 v[66:69], v[154:157], v[210:213], v[66:69]
	v_mfma_f32_16x16x32_bf16 v[58:61], v[146:149], v[236:239], v[58:61]
	v_mfma_f32_16x16x32_bf16 v[50:53], v[154:157], v[236:239], v[50:53]
	v_mfma_f32_16x16x32_bf16 v[94:97], v[150:153], v[182:185], v[94:97]
	v_mfma_f32_16x16x32_bf16 v[90:93], v[158:161], v[182:185], v[90:93]
	v_mfma_f32_16x16x32_bf16 v[86:89], v[150:153], v[206:209], v[86:89]
	v_mfma_f32_16x16x32_bf16 v[82:85], v[158:161], v[206:209], v[82:85]
	v_mfma_f32_16x16x32_bf16 v[74:77], v[150:153], v[232:235], v[74:77]
	v_mfma_f32_16x16x32_bf16 v[66:69], v[158:161], v[232:235], v[66:69]
	v_mfma_f32_16x16x32_bf16 v[58:61], v[150:153], v[240:243], v[58:61]
	v_mfma_f32_16x16x32_bf16 v[50:53], v[158:161], v[240:243], v[50:53]
	v_mfma_f32_16x16x32_bf16 v[30:33], v[162:165], v[178:181], v[30:33]
	v_mfma_f32_16x16x32_bf16 v[26:29], v[170:173], v[178:181], v[26:29]
	v_mfma_f32_16x16x32_bf16 v[22:25], v[162:165], v[202:205], v[22:25]
	v_mfma_f32_16x16x32_bf16 v[18:21], v[170:173], v[202:205], v[18:21]
	v_mfma_f32_16x16x32_bf16 v[14:17], v[162:165], v[210:213], v[14:17]
	v_mfma_f32_16x16x32_bf16 v[10:13], v[170:173], v[210:213], v[10:13]
	v_mfma_f32_16x16x32_bf16 v[6:9], v[162:165], v[236:239], v[6:9]
	v_mfma_f32_16x16x32_bf16 v[2:5], v[170:173], v[236:239], v[2:5]
	v_mfma_f32_16x16x32_bf16 v[30:33], v[166:169], v[182:185], v[30:33]
	v_mfma_f32_16x16x32_bf16 v[26:29], v[174:177], v[182:185], v[26:29]
	v_mfma_f32_16x16x32_bf16 v[22:25], v[166:169], v[206:209], v[22:25]
	v_mfma_f32_16x16x32_bf16 v[18:21], v[174:177], v[206:209], v[18:21]
	v_mfma_f32_16x16x32_bf16 v[14:17], v[166:169], v[232:235], v[14:17]
	v_mfma_f32_16x16x32_bf16 v[10:13], v[174:177], v[232:235], v[10:13]
	v_mfma_f32_16x16x32_bf16 v[6:9], v[166:169], v[240:243], v[6:9]
	v_mfma_f32_16x16x32_bf16 v[2:5], v[174:177], v[240:243], v[2:5]
	s_setprio 0
	s_barrier
	s_add_i32 s56, s56, 2
	s_add_u32 s54, s54, 0x100
	s_addc_u32 s55, s55, 0
	s_cmp_gt_u32 s56, 5
	s_mov_b64 s[22:23], s[24:25]
	s_cbranch_scc0 .LBB0_1160
	s_and_b64 vcc, exec, s[8:9]
	s_cbranch_vccz .LBB0_1163
	s_barrier

; #define PG8_STAGE(bufoff, gbase, voff) do { _Pragma("unroll") for (int _i = 0; _i < 2; ++_i) \
;         __builtin_amdgcn_global_load_lds((const unsigned*)((const char*)(gbase) + (voff)[_i]), (PG8_LAS unsigned*)(lds + (bufoff) + ldsw + _i * 8192), 16, 0, 0); } while (0)
; #define PG8_LDA(dst, b, h) do { _Pragma("unroll") for (int m = 0; m < 4; ++m) _Pragma("unroll") for (int k = 0; k < 2; ++k) dst[m][k] = *(const PG8_LAS bf16x8*)(lds + PG8_SA(b, h) + aoff + m * 2048 + k * 1024); } while (0)
; #define PG8_LDB(dst, b, h) do { _Pragma("unroll") for (int n = 0; n < 2; ++n) _Pragma("unroll") for (int k = 0; k < 2; ++k) dst[n][k] = *(const PG8_LAS bf16x8*)(lds + PG8_SB(b, h) + boff + n * 2048 + k * 1024); } while (0)
; template <class Epi, class Sched, bool ALIGN_EPI = false, bool SP2 = false>
; __device__ __forceinline__ void gemm_phase(PG8_LAS unsigned char* lds, const Gemm g, const Sched& S, const Epi& E) {
;     ...
;         for (int t = 0; t < nt; t += 2) {
;             const bool last = (t == nt - 2);
;             const char* a1 = cA + (size_t)(t + 1) * kstep;
;             const char* a2 = last ? nA : cA + (size_t)(t + 2) * kstep; const char* b2 = last ? nB : cB + (size_t)(t + 2) * kstep;
;             const char* a3 = a2 + kstep; const char* b3 = b2 + kstep;
;             if (last && has_next) S.a_ready(nxt);
;             if constexpr (SP2) {
;             PG8_LDB(B0, 0, 0); PG8_LDB(B1, 0, 1); PG8_SCHED; PG8_LDA(At, 0, 0); PG8_STAGE(PG8_SA(1, 1), a1 + hstepA, voffA);
;             PG8_WAIT_V(8); PG8_WAIT_L(0); PG8_BAR; PG8_MMA(0, 0, At, B0); PG8_MMA(0, 1, At, B1); PG8_BAR; PG8_SCHED;
;             PG8_LDA(At, 0, 1); PG8_STAGE(PG8_SB(0, 0), b2, voffB); PG8_STAGE(PG8_SB(0, 1), b2 + hstepB, voffB); PG8_STAGE(PG8_SA(0, 0), a2, voffA);
;             PG8_WAIT_V(8); PG8_WAIT_L(0); PG8_BAR; PG8_MMA(1, 0, At, B0); PG8_MMA(1, 1, At, B1); PG8_BAR; PG8_SCHED;
;             PG8_LDB(B0, 1, 0); PG8_LDB(B1, 1, 1); PG8_SCHED; PG8_LDA(At, 1, 0); PG8_STAGE(PG8_SA(0, 1), a2 + hstepA, voffA);
;             PG8_WAIT_V(8); PG8_WAIT_L(0); PG8_BAR; PG8_MMA(0, 0, At, B0); PG8_MMA(0, 1, At, B1); PG8_BAR; PG8_SCHED;
;             PG8_LDA(At, 1, 1); PG8_STAGE(PG8_SB(1, 0), b3, voffB); PG8_STAGE(PG8_SB(1, 1), b3 + hstepB, voffB); PG8_STAGE(PG8_SA(1, 0), a3, voffA);
;             PG8_WAIT_V(8); PG8_WAIT_L(0); PG8_BAR; PG8_MMA(1, 0, At, B0); PG8_MMA(1, 1, At, B1); PG8_BAR; PG8_SCHED;
.LBB0_1176:
	s_add_u32 s35, s26, s34
	s_addc_u32 s40, s27, 0
	s_add_u32 s38, s35, 0x100
	s_addc_u32 s39, s40, 0
	s_and_b64 s[36:37], s[30:31], exec
	s_cselect_b32 s37, s19, s39
	s_cselect_b32 s36, s18, s38
	s_add_u32 s34, s24, s34
	s_addc_u32 s38, s25, 0
	s_add_u32 s34, s34, 0x100
	s_addc_u32 s38, s38, 0
	s_add_i32 s72, 0, 0x10000
	s_and_b64 s[30:31], s[30:31], exec
	s_cselect_b32 s39, s61, s38
	s_cselect_b32 s38, s62, s34
	s_add_i32 s31, 0, 0x14000
	s_add_u32 s42, s35, 0x30080
	s_addc_u32 s43, s40, 0
	s_add_i32 s71, s72, s50
	s_add_i32 m0, s51, 0xc000
	s_add_i32 s74, s51, 0xe000
	s_add_i32 s67, s71, 0x2000
	v_add_u32_e32 v141, s72, v138
	s_add_u32 s40, s38, 0x10000
	ds_read_b128 v[142:145], v141
	ds_read_b128 v[146:149], v141 offset:1024
	ds_read_b128 v[150:153], v141 offset:2048
	ds_read_b128 v[154:157], v141 offset:3072
	v_add_u32_e32 v141, s31, v138
	s_addc_u32 s41, s39, 0
	s_add_i32 s69, s31, s50
	ds_read_b128 v[158:161], v141
	ds_read_b128 v[162:165], v141 offset:1024
	ds_read_b128 v[166:169], v141 offset:2048
	ds_read_b128 v[170:173], v141 offset:3072
	s_add_i32 s68, s69, 0x2000
	s_add_i32 s66, 0, 0x18000
	s_add_i32 s65, 0, 0x1c000
	s_add_u32 s34, s36, 0x30000
	s_addc_u32 s35, s37, 0
	s_add_i32 s64, s66, s50
	s_add_i32 s63, s64, 0x2000
	s_add_u32 s30, s38, 0x10080
	s_addc_u32 s31, s39, 0
	s_add_i32 s73, s65, s50
	s_add_i32 s72, s73, 0x2000
	v_lshl_add_u64 v[186:187], s[42:43], 0, v[136:137]
	ds_read_b128 v[174:177], v140
	ds_read_b128 v[178:181], v140 offset:1024
	ds_read_b128 v[182:185], v140 offset:2048
	ds_read_b128 v[202:205], v140 offset:3072
	ds_read_b128 v[206:209], v140 offset:4096
	ds_read_b128 v[210:213], v140 offset:5120
	ds_read_b128 v[232:235], v140 offset:6144
	ds_read_b128 v[236:239], v140 offset:7168
	global_load_lds_dwordx4 v[186:187], off
	v_lshl_add_u64 v[186:187], s[42:43], 0, v[132:133]
	s_mov_b32 m0, s74
	s_nop 0
	global_load_lds_dwordx4 v[186:187], off
	s_waitcnt vmcnt(8)
	s_waitcnt lgkmcnt(0)
	s_barrier
	s_setprio 1
	s_waitcnt lgkmcnt(0)
	v_mfma_f32_16x16x32_bf16 v[126:129], v[142:145], v[174:177], v[126:129]
	v_mfma_f32_16x16x32_bf16 v[122:125], v[150:153], v[174:177], v[122:125]
	v_mfma_f32_16x16x32_bf16 v[118:121], v[142:145], v[182:185], v[118:121]
	v_mfma_f32_16x16x32_bf16 v[114:117], v[150:153], v[182:185], v[114:117]
	v_mfma_f32_16x16x32_bf16 v[110:113], v[142:145], v[206:209], v[110:113]
	v_mfma_f32_16x16x32_bf16 v[106:109], v[150:153], v[206:209], v[106:109]
	v_mfma_f32_16x16x32_bf16 v[102:105], v[142:145], v[232:235], v[102:105]
	v_mfma_f32_16x16x32_bf16 v[98:101], v[150:153], v[232:235], v[98:101]
	v_mfma_f32_16x16x32_bf16 v[126:129], v[146:149], v[178:181], v[126:129]
	v_mfma_f32_16x16x32_bf16 v[122:125], v[154:157], v[178:181], v[122:125]
	v_mfma_f32_16x16x32_bf16 v[118:121], v[146:149], v[202:205], v[118:121]
	v_mfma_f32_16x16x32_bf16 v[114:117], v[154:157], v[202:205], v[114:117]
	v_mfma_f32_16x16x32_bf16 v[110:113], v[146:149], v[210:213], v[110:113]
	v_mfma_f32_16x16x32_bf16 v[106:109], v[154:157], v[210:213], v[106:109]
	v_mfma_f32_16x16x32_bf16 v[102:105], v[146:149], v[236:239], v[102:105]
	v_mfma_f32_16x16x32_bf16 v[98:101], v[154:157], v[236:239], v[98:101]
	v_mfma_f32_16x16x32_bf16 v[78:81], v[158:161], v[174:177], v[78:81]
	v_mfma_f32_16x16x32_bf16 v[70:73], v[166:169], v[174:177], v[70:73]
	v_mfma_f32_16x16x32_bf16 v[62:65], v[158:161], v[182:185], v[62:65]
	v_mfma_f32_16x16x32_bf16 v[54:57], v[166:169], v[182:185], v[54:57]
	v_mfma_f32_16x16x32_bf16 v[46:49], v[158:161], v[206:209], v[46:49]
	v_mfma_f32_16x16x32_bf16 v[42:45], v[166:169], v[206:209], v[42:45]
	v_mfma_f32_16x16x32_bf16 v[38:41], v[158:161], v[232:235], v[38:41]
	v_mfma_f32_16x16x32_bf16 v[34:37], v[166:169], v[232:235], v[34:37]
	v_mfma_f32_16x16x32_bf16 v[78:81], v[162:165], v[178:181], v[78:81]
	v_mfma_f32_16x16x32_bf16 v[70:73], v[170:173], v[178:181], v[70:73]
	v_mfma_f32_16x16x32_bf16 v[62:65], v[162:165], v[202:205], v[62:65]
	v_mfma_f32_16x16x32_bf16 v[54:57], v[170:173], v[202:205], v[54:57]
	v_mfma_f32_16x16x32_bf16 v[46:49], v[162:165], v[210:213], v[46:49]
	v_mfma_f32_16x16x32_bf16 v[42:45], v[170:173], v[210:213], v[42:45]
	v_mfma_f32_16x16x32_bf16 v[38:41], v[162:165], v[236:239], v[38:41]
	v_mfma_f32_16x16x32_bf16 v[34:37], v[170:173], v[236:239], v[34:37]
	s_setprio 0
	s_barrier
	s_mov_b32 m0, s71
	v_lshl_add_u64 v[186:187], s[38:39], 0, v[134:135]
	ds_read_b128 v[174:177], v140 offset:16384
	ds_read_b128 v[178:181], v140 offset:17408
	ds_read_b128 v[182:185], v140 offset:18432
	ds_read_b128 v[202:205], v140 offset:19456
	ds_read_b128 v[206:209], v140 offset:20480
	ds_read_b128 v[210:213], v140 offset:21504
	ds_read_b128 v[232:235], v140 offset:22528
	ds_read_b128 v[236:239], v140 offset:23552
	global_load_lds_dwordx4 v[186:187], off
	v_lshl_add_u64 v[214:215], s[38:39], 0, v[130:131]
	s_mov_b32 m0, s67
	v_lshl_add_u64 v[240:241], s[40:41], 0, v[134:135]
	global_load_lds_dwordx4 v[214:215], off
	s_mov_b32 m0, s69
	v_lshl_add_u64 v[242:243], s[36:37], 0, v[132:133]
	global_load_lds_dwordx4 v[240:241], off
	v_lshl_add_u64 v[240:241], s[40:41], 0, v[130:131]
	s_mov_b32 m0, s68
	s_nop 0
	global_load_lds_dwordx4 v[240:241], off
	v_lshl_add_u64 v[240:241], s[36:37], 0, v[136:137]
	s_mov_b32 m0, s51
	s_nop 0
	global_load_lds_dwordx4 v[240:241], off
	s_mov_b32 m0, s52
	s_nop 0
	global_load_lds_dwordx4 v[242:243], off
	s_waitcnt vmcnt(8)
	s_waitcnt lgkmcnt(0)
	s_barrier
; #define PG8_STAGE(bufoff, gbase, voff) do { _Pragma("unroll") for (int _i = 0; _i < 2; ++_i) \
;         __builtin_amdgcn_global_load_lds((const unsigned*)((const char*)(gbase) + (voff)[_i]), (PG8_LAS unsigned*)(lds + (bufoff) + ldsw + _i * 8192), 16, 0, 0); } while (0)
; #define PG8_LDA(dst, b, h) do { _Pragma("unroll") for (int m = 0; m < 4; ++m) _Pragma("unroll") for (int k = 0; k < 2; ++k) dst[m][k] = *(const PG8_LAS bf16x8*)(lds + PG8_SA(b, h) + aoff + m * 2048 + k * 1024); } while (0)
; #define PG8_LDB(dst, b, h) do { _Pragma("unroll") for (int n = 0; n < 2; ++n) _Pragma("unroll") for (int k = 0; k < 2; ++k) dst[n][k] = *(const PG8_LAS bf16x8*)(lds + PG8_SB(b, h) + boff + n * 2048 + k * 1024); } while (0)
; #define PG8_MMA(ai, bj, At, Bt) do { __builtin_amdgcn_s_setprio(1); _Pragma("unroll") for (int m = 0; m < 4; ++m) _Pragma("unroll") for (int n = 0; n < 2; ++n) _Pragma("unroll") for (int k = 0; k < 2; ++k) \
;         acc[ai][bj][m][n] = __builtin_amdgcn_mfma_f32_16x16x32_bf16(Bt[n][k], At[m][k], acc[ai][bj][m][n], 0, 0, 0); __builtin_amdgcn_s_setprio(0); } while (0)
; #define PG8_WAIT_V(n) asm volatile("s_waitcnt vmcnt(" #n ")" ::: "memory")
; template <class Epi, class Sched, bool ALIGN_EPI = false, bool SP2 = false>
; __device__ __forceinline__ void gemm_phase(PG8_LAS unsigned char* lds, const Gemm g, const Sched& S, const Epi& E) {
;     ...
;             PG8_LDB(B0, 0, 0); PG8_LDB(B1, 0, 1); PG8_SCHED; PG8_LDA(At, 0, 0); PG8_STAGE(PG8_SA(1, 1), a1 + hstepA, voffA);
;             PG8_WAIT_V(8); PG8_WAIT_L(0); PG8_BAR; PG8_MMA(0, 0, At, B0); PG8_MMA(0, 1, At, B1); PG8_BAR; PG8_SCHED;
;             PG8_LDA(At, 0, 1); PG8_STAGE(PG8_SB(0, 0), b2, voffB); PG8_STAGE(PG8_SB(0, 1), b2 + hstepB, voffB); PG8_STAGE(PG8_SA(0, 0), a2, voffA);
;             PG8_WAIT_V(8); PG8_WAIT_L(0); PG8_BAR; PG8_MMA(1, 0, At, B0); PG8_MMA(1, 1, At, B1); PG8_BAR; PG8_SCHED;
;             PG8_LDB(B0, 1, 0); PG8_LDB(B1, 1, 1); PG8_SCHED; PG8_LDA(At, 1, 0); PG8_STAGE(PG8_SA(0, 1), a2 + hstepA, voffA);
;             PG8_WAIT_V(8); PG8_WAIT_L(0); PG8_BAR; PG8_MMA(0, 0, At, B0); PG8_MMA(0, 1, At, B1); PG8_BAR; PG8_SCHED;
;             PG8_LDA(At, 1, 1); PG8_STAGE(PG8_SB(1, 0), b3, voffB); PG8_STAGE(PG8_SB(1, 1), b3 + hstepB, voffB); PG8_STAGE(PG8_SA(1, 0), a3, voffA);
;             PG8_WAIT_V(8); PG8_WAIT_L(0); PG8_BAR; PG8_MMA(1, 0, At, B0); PG8_MMA(1, 1, At, B1); PG8_BAR; PG8_SCHED;
	s_setprio 1
	s_waitcnt lgkmcnt(0)
	v_mfma_f32_16x16x32_bf16 v[94:97], v[142:145], v[174:177], v[94:97]
	v_mfma_f32_16x16x32_bf16 v[90:93], v[150:153], v[174:177], v[90:93]
	v_mfma_f32_16x16x32_bf16 v[86:89], v[142:145], v[182:185], v[86:89]
	v_mfma_f32_16x16x32_bf16 v[82:85], v[150:153], v[182:185], v[82:85]
	v_mfma_f32_16x16x32_bf16 v[74:77], v[142:145], v[206:209], v[74:77]
	v_mfma_f32_16x16x32_bf16 v[66:69], v[150:153], v[206:209], v[66:69]
	v_mfma_f32_16x16x32_bf16 v[58:61], v[142:145], v[232:235], v[58:61]
	v_mfma_f32_16x16x32_bf16 v[50:53], v[150:153], v[232:235], v[50:53]
	v_mfma_f32_16x16x32_bf16 v[94:97], v[146:149], v[178:181], v[94:97]
	v_mfma_f32_16x16x32_bf16 v[90:93], v[154:157], v[178:181], v[90:93]
	v_mfma_f32_16x16x32_bf16 v[86:89], v[146:149], v[202:205], v[86:89]
	v_mfma_f32_16x16x32_bf16 v[82:85], v[154:157], v[202:205], v[82:85]
	v_mfma_f32_16x16x32_bf16 v[74:77], v[146:149], v[210:213], v[74:77]
	v_mfma_f32_16x16x32_bf16 v[66:69], v[154:157], v[210:213], v[66:69]
	v_mfma_f32_16x16x32_bf16 v[58:61], v[146:149], v[236:239], v[58:61]
	v_mfma_f32_16x16x32_bf16 v[50:53], v[154:157], v[236:239], v[50:53]
	v_mfma_f32_16x16x32_bf16 v[30:33], v[158:161], v[174:177], v[30:33]
	v_mfma_f32_16x16x32_bf16 v[26:29], v[166:169], v[174:177], v[26:29]
	v_mfma_f32_16x16x32_bf16 v[22:25], v[158:161], v[182:185], v[22:25]
	v_mfma_f32_16x16x32_bf16 v[18:21], v[166:169], v[182:185], v[18:21]
	v_mfma_f32_16x16x32_bf16 v[14:17], v[158:161], v[206:209], v[14:17]
	v_mfma_f32_16x16x32_bf16 v[10:13], v[166:169], v[206:209], v[10:13]
	v_mfma_f32_16x16x32_bf16 v[6:9], v[158:161], v[232:235], v[6:9]
	v_mfma_f32_16x16x32_bf16 v[2:5], v[166:169], v[232:235], v[2:5]
	v_mfma_f32_16x16x32_bf16 v[30:33], v[162:165], v[178:181], v[30:33]
	v_mfma_f32_16x16x32_bf16 v[26:29], v[170:173], v[178:181], v[26:29]
	v_mfma_f32_16x16x32_bf16 v[22:25], v[162:165], v[202:205], v[22:25]
	v_mfma_f32_16x16x32_bf16 v[18:21], v[170:173], v[202:205], v[18:21]
	v_mfma_f32_16x16x32_bf16 v[14:17], v[162:165], v[210:213], v[14:17]
	v_mfma_f32_16x16x32_bf16 v[10:13], v[170:173], v[210:213], v[10:13]
	v_mfma_f32_16x16x32_bf16 v[6:9], v[162:165], v[236:239], v[6:9]
	v_mfma_f32_16x16x32_bf16 v[2:5], v[170:173], v[236:239], v[2:5]
	s_setprio 0
	s_barrier
	v_add_u32_e32 v141, s66, v138
	ds_read_b128 v[142:145], v141
	ds_read_b128 v[146:149], v141 offset:1024
	ds_read_b128 v[150:153], v141 offset:2048
	ds_read_b128 v[154:157], v141 offset:3072
	v_add_u32_e32 v141, s65, v138
	ds_read_b128 v[158:161], v141
	ds_read_b128 v[162:165], v141 offset:1024
	ds_read_b128 v[166:169], v141 offset:2048
	ds_read_b128 v[170:173], v141 offset:3072
	s_mov_b32 m0, s53
	v_lshl_add_u64 v[244:245], s[34:35], 0, v[136:137]
	ds_read_b128 v[174:177], v140 offset:32768
	ds_read_b128 v[178:181], v140 offset:33792
	ds_read_b128 v[182:185], v140 offset:34816
	ds_read_b128 v[202:205], v140 offset:35840
	ds_read_b128 v[206:209], v140 offset:36864
	ds_read_b128 v[210:213], v140 offset:37888
	ds_read_b128 v[232:235], v140 offset:38912
	ds_read_b128 v[236:239], v140 offset:39936
	global_load_lds_dwordx4 v[244:245], off
	v_lshl_add_u64 v[244:245], s[34:35], 0, v[132:133]
	s_mov_b32 m0, s54
	s_nop 0
	global_load_lds_dwordx4 v[244:245], off
	s_waitcnt vmcnt(8)
	s_waitcnt lgkmcnt(0)
	s_barrier
	s_setprio 1
	s_waitcnt lgkmcnt(0)
	v_mfma_f32_16x16x32_bf16 v[126:129], v[142:145], v[174:177], v[126:129]
	v_mfma_f32_16x16x32_bf16 v[122:125], v[150:153], v[174:177], v[122:125]
	v_mfma_f32_16x16x32_bf16 v[118:121], v[142:145], v[182:185], v[118:121]
	v_mfma_f32_16x16x32_bf16 v[114:117], v[150:153], v[182:185], v[114:117]
	v_mfma_f32_16x16x32_bf16 v[110:113], v[142:145], v[206:209], v[110:113]
	v_mfma_f32_16x16x32_bf16 v[106:109], v[150:153], v[206:209], v[106:109]
	v_mfma_f32_16x16x32_bf16 v[102:105], v[142:145], v[232:235], v[102:105]
	v_mfma_f32_16x16x32_bf16 v[98:101], v[150:153], v[232:235], v[98:101]
	v_mfma_f32_16x16x32_bf16 v[126:129], v[146:149], v[178:181], v[126:129]
	v_mfma_f32_16x16x32_bf16 v[122:125], v[154:157], v[178:181], v[122:125]
	v_mfma_f32_16x16x32_bf16 v[118:121], v[146:149], v[202:205], v[118:121]
	v_mfma_f32_16x16x32_bf16 v[114:117], v[154:157], v[202:205], v[114:117]
	v_mfma_f32_16x16x32_bf16 v[110:113], v[146:149], v[210:213], v[110:113]
	v_mfma_f32_16x16x32_bf16 v[106:109], v[154:157], v[210:213], v[106:109]
	v_mfma_f32_16x16x32_bf16 v[102:105], v[146:149], v[236:239], v[102:105]
	v_mfma_f32_16x16x32_bf16 v[98:101], v[154:157], v[236:239], v[98:101]
	v_mfma_f32_16x16x32_bf16 v[78:81], v[158:161], v[174:177], v[78:81]
	v_mfma_f32_16x16x32_bf16 v[70:73], v[166:169], v[174:177], v[70:73]
	v_mfma_f32_16x16x32_bf16 v[62:65], v[158:161], v[182:185], v[62:65]
	v_mfma_f32_16x16x32_bf16 v[54:57], v[166:169], v[182:185], v[54:57]
	v_mfma_f32_16x16x32_bf16 v[46:49], v[158:161], v[206:209], v[46:49]
	v_mfma_f32_16x16x32_bf16 v[42:45], v[166:169], v[206:209], v[42:45]
	v_mfma_f32_16x16x32_bf16 v[38:41], v[158:161], v[232:235], v[38:41]
	v_mfma_f32_16x16x32_bf16 v[34:37], v[166:169], v[232:235], v[34:37]
	v_mfma_f32_16x16x32_bf16 v[78:81], v[162:165], v[178:181], v[78:81]
	v_mfma_f32_16x16x32_bf16 v[70:73], v[170:173], v[178:181], v[70:73]
	v_mfma_f32_16x16x32_bf16 v[62:65], v[162:165], v[202:205], v[62:65]
	v_mfma_f32_16x16x32_bf16 v[54:57], v[170:173], v[202:205], v[54:57]
	v_mfma_f32_16x16x32_bf16 v[46:49], v[162:165], v[210:213], v[46:49]
	v_mfma_f32_16x16x32_bf16 v[42:45], v[170:173], v[210:213], v[42:45]
	v_mfma_f32_16x16x32_bf16 v[38:41], v[162:165], v[236:239], v[38:41]
	v_mfma_f32_16x16x32_bf16 v[34:37], v[170:173], v[236:239], v[34:37]
	s_setprio 0
	s_barrier
; #define PG8_STAGE(bufoff, gbase, voff) do { _Pragma("unroll") for (int _i = 0; _i < 2; ++_i) \
;         __builtin_amdgcn_global_load_lds((const unsigned*)((const char*)(gbase) + (voff)[_i]), (PG8_LAS unsigned*)(lds + (bufoff) + ldsw + _i * 8192), 16, 0, 0); } while (0)
; #define PG8_LDA(dst, b, h) do { _Pragma("unroll") for (int m = 0; m < 4; ++m) _Pragma("unroll") for (int k = 0; k < 2; ++k) dst[m][k] = *(const PG8_LAS bf16x8*)(lds + PG8_SA(b, h) + aoff + m * 2048 + k * 1024); } while (0)
; #define PG8_MMA(ai, bj, At, Bt) do { __builtin_amdgcn_s_setprio(1); _Pragma("unroll") for (int m = 0; m < 4; ++m) _Pragma("unroll") for (int n = 0; n < 2; ++n) _Pragma("unroll") for (int k = 0; k < 2; ++k) \
;         acc[ai][bj][m][n] = __builtin_amdgcn_mfma_f32_16x16x32_bf16(Bt[n][k], At[m][k], acc[ai][bj][m][n], 0, 0, 0); __builtin_amdgcn_s_setprio(0); } while (0)
; #define PG8_WAIT_V(n) asm volatile("s_waitcnt vmcnt(" #n ")" ::: "memory")
; #define PG8_WAIT_L(n) asm volatile("s_waitcnt lgkmcnt(" #n ")" ::: "memory")
; #define PG8_BAR __builtin_amdgcn_s_barrier()
; #define PG8_SCHED __builtin_amdgcn_sched_barrier(0)
; template <class Epi, class Sched, bool ALIGN_EPI = false, bool SP2 = false>
; __device__ __forceinline__ void gemm_phase(PG8_LAS unsigned char* lds, const Gemm g, const Sched& S, const Epi& E) {
;     ...
;             PG8_LDA(At, 1, 1); PG8_STAGE(PG8_SB(1, 0), b3, voffB); PG8_STAGE(PG8_SB(1, 1), b3 + hstepB, voffB); PG8_STAGE(PG8_SA(1, 0), a3, voffA);
;             PG8_WAIT_V(8); PG8_WAIT_L(0); PG8_BAR; PG8_MMA(1, 0, At, B0); PG8_MMA(1, 1, At, B1); PG8_BAR; PG8_SCHED;
	s_mov_b32 m0, s64
	v_lshl_add_u64 v[186:187], v[186:187], 0, s[96:97]
	ds_read_b128 v[174:177], v140 offset:49152
	ds_read_b128 v[178:181], v140 offset:50176
	ds_read_b128 v[182:185], v140 offset:51200
	ds_read_b128 v[202:205], v140 offset:52224
	ds_read_b128 v[206:209], v140 offset:53248
	ds_read_b128 v[210:213], v140 offset:54272
	ds_read_b128 v[232:235], v140 offset:55296
	ds_read_b128 v[236:239], v140 offset:56320
	global_load_lds_dwordx4 v[186:187], off
	v_lshl_add_u64 v[186:187], v[214:215], 0, s[96:97]
	s_mov_b32 m0, s63
	s_nop 0
	global_load_lds_dwordx4 v[186:187], off
	v_lshl_add_u64 v[186:187], s[30:31], 0, v[134:135]
	s_mov_b32 m0, s73
	s_nop 0
	global_load_lds_dwordx4 v[186:187], off
	v_lshl_add_u64 v[186:187], s[30:31], 0, v[130:131]
	s_mov_b32 m0, s72
	s_nop 0
	global_load_lds_dwordx4 v[186:187], off
	v_lshl_add_u64 v[186:187], v[240:241], 0, s[96:97]
	s_mov_b32 m0, s55
	s_nop 0
	global_load_lds_dwordx4 v[186:187], off
	v_lshl_add_u64 v[186:187], v[242:243], 0, s[96:97]
	s_mov_b32 m0, s56
	s_nop 0
	global_load_lds_dwordx4 v[186:187], off
	s_waitcnt vmcnt(8)
	s_waitcnt lgkmcnt(0)
	s_barrier
	s_setprio 1
	s_waitcnt lgkmcnt(0)
	v_mfma_f32_16x16x32_bf16 v[94:97], v[142:145], v[174:177], v[94:97]
	v_mfma_f32_16x16x32_bf16 v[90:93], v[150:153], v[174:177], v[90:93]
	v_mfma_f32_16x16x32_bf16 v[86:89], v[142:145], v[182:185], v[86:89]
	v_mfma_f32_16x16x32_bf16 v[82:85], v[150:153], v[182:185], v[82:85]
	v_mfma_f32_16x16x32_bf16 v[74:77], v[142:145], v[206:209], v[74:77]
	v_mfma_f32_16x16x32_bf16 v[66:69], v[150:153], v[206:209], v[66:69]
	v_mfma_f32_16x16x32_bf16 v[58:61], v[142:145], v[232:235], v[58:61]
	v_mfma_f32_16x16x32_bf16 v[50:53], v[150:153], v[232:235], v[50:53]
	v_mfma_f32_16x16x32_bf16 v[94:97], v[146:149], v[178:181], v[94:97]
	v_mfma_f32_16x16x32_bf16 v[90:93], v[154:157], v[178:181], v[90:93]
	v_mfma_f32_16x16x32_bf16 v[86:89], v[146:149], v[202:205], v[86:89]
	v_mfma_f32_16x16x32_bf16 v[82:85], v[154:157], v[202:205], v[82:85]
	v_mfma_f32_16x16x32_bf16 v[74:77], v[146:149], v[210:213], v[74:77]
	v_mfma_f32_16x16x32_bf16 v[66:69], v[154:157], v[210:213], v[66:69]
	v_mfma_f32_16x16x32_bf16 v[58:61], v[146:149], v[236:239], v[58:61]
	v_mfma_f32_16x16x32_bf16 v[50:53], v[154:157], v[236:239], v[50:53]
	v_mfma_f32_16x16x32_bf16 v[30:33], v[158:161], v[174:177], v[30:33]
	v_mfma_f32_16x16x32_bf16 v[26:29], v[166:169], v[174:177], v[26:29]
	v_mfma_f32_16x16x32_bf16 v[22:25], v[158:161], v[182:185], v[22:25]
	v_mfma_f32_16x16x32_bf16 v[18:21], v[166:169], v[182:185], v[18:21]
	v_mfma_f32_16x16x32_bf16 v[14:17], v[158:161], v[206:209], v[14:17]
	v_mfma_f32_16x16x32_bf16 v[10:13], v[166:169], v[206:209], v[10:13]
	v_mfma_f32_16x16x32_bf16 v[6:9], v[158:161], v[232:235], v[6:9]
	v_mfma_f32_16x16x32_bf16 v[2:5], v[166:169], v[232:235], v[2:5]
	v_mfma_f32_16x16x32_bf16 v[30:33], v[162:165], v[178:181], v[30:33]
	v_mfma_f32_16x16x32_bf16 v[26:29], v[170:173], v[178:181], v[26:29]
	v_mfma_f32_16x16x32_bf16 v[22:25], v[162:165], v[202:205], v[22:25]
	v_mfma_f32_16x16x32_bf16 v[18:21], v[170:173], v[202:205], v[18:21]
	v_mfma_f32_16x16x32_bf16 v[14:17], v[162:165], v[210:213], v[14:17]
	v_mfma_f32_16x16x32_bf16 v[10:13], v[170:173], v[210:213], v[10:13]
	v_mfma_f32_16x16x32_bf16 v[6:9], v[162:165], v[236:239], v[6:9]
	v_mfma_f32_16x16x32_bf16 v[2:5], v[170:173], v[236:239], v[2:5]
	s_setprio 0
	s_barrier
	s_movk_i32 s34, 0x100
	s_andn2_b64 vcc, exec, s[28:29]
	s_mov_b64 s[30:31], -1
	s_mov_b64 s[28:29], 0
	s_cbranch_vccz .LBB0_1176
	s_and_b64 vcc, exec, s[16:17]
	s_cbranch_vccz .LBB0_1179
	s_barrier

; #define PG8_STAGE(bufoff, gbase, voff) do { _Pragma("unroll") for (int _i = 0; _i < 2; ++_i) \
;         __builtin_amdgcn_global_load_lds((const unsigned*)((const char*)(gbase) + (voff)[_i]), (PG8_LAS unsigned*)(lds + (bufoff) + ldsw + _i * 8192), 16, 0, 0); } while (0)
; #define PG8_LDA(dst, b, h) do { _Pragma("unroll") for (int m = 0; m < 4; ++m) _Pragma("unroll") for (int k = 0; k < 2; ++k) dst[m][k] = *(const PG8_LAS bf16x8*)(lds + PG8_SA(b, h) + aoff + m * 2048 + k * 1024); } while (0)
; #define PG8_LDB(dst, b, h) do { _Pragma("unroll") for (int n = 0; n < 2; ++n) _Pragma("unroll") for (int k = 0; k < 2; ++k) dst[n][k] = *(const PG8_LAS bf16x8*)(lds + PG8_SB(b, h) + boff + n * 2048 + k * 1024); } while (0)
; template <class Epi, class Sched, bool ALIGN_EPI = false, bool SP2 = false>
; __device__ __forceinline__ void gemm_phase(PG8_LAS unsigned char* lds, const Gemm g, const Sched& S, const Epi& E) {
;     ...
;         for (int t = 0; t < nt; t += 2) {
;             const bool last = (t == nt - 2);
;             const char* a1 = cA + (size_t)(t + 1) * kstep;
;             const char* a2 = last ? nA : cA + (size_t)(t + 2) * kstep; const char* b2 = last ? nB : cB + (size_t)(t + 2) * kstep;
;             const char* a3 = a2 + kstep; const char* b3 = b2 + kstep;
;             if (last && has_next) S.a_ready(nxt);
;             if constexpr (SP2) {
;             PG8_LDB(B0, 0, 0); PG8_LDB(B1, 0, 1); PG8_SCHED; PG8_LDA(At, 0, 0); PG8_STAGE(PG8_SA(1, 1), a1 + hstepA, voffA);
;             PG8_WAIT_V(8); PG8_WAIT_L(0); PG8_BAR; PG8_MMA(0, 0, At, B0); PG8_MMA(0, 1, At, B1); PG8_BAR; PG8_SCHED;
;             PG8_LDA(At, 0, 1); PG8_STAGE(PG8_SB(0, 0), b2, voffB); PG8_STAGE(PG8_SB(0, 1), b2 + hstepB, voffB); PG8_STAGE(PG8_SA(0, 0), a2, voffA);
;             PG8_WAIT_V(8); PG8_WAIT_L(0); PG8_BAR; PG8_MMA(1, 0, At, B0); PG8_MMA(1, 1, At, B1); PG8_BAR; PG8_SCHED;
;             PG8_LDB(B0, 1, 0); PG8_LDB(B1, 1, 1); PG8_SCHED; PG8_LDA(At, 1, 0); PG8_STAGE(PG8_SA(0, 1), a2 + hstepA, voffA);
;             PG8_WAIT_V(8); PG8_WAIT_L(0); PG8_BAR; PG8_MMA(0, 0, At, B0); PG8_MMA(0, 1, At, B1); PG8_BAR; PG8_SCHED;
;             PG8_LDA(At, 1, 1); PG8_STAGE(PG8_SB(1, 0), b3, voffB); PG8_STAGE(PG8_SB(1, 1), b3 + hstepB, voffB); PG8_STAGE(PG8_SA(1, 0), a3, voffA);
;             PG8_WAIT_V(8); PG8_WAIT_L(0); PG8_BAR; PG8_MMA(1, 0, At, B0); PG8_MMA(1, 1, At, B1); PG8_BAR; PG8_SCHED;
.LBB0_1190:
	s_add_u32 s24, s22, 0xfffc0080
	s_addc_u32 s25, s23, -1
	s_add_i32 s51, 0, 0x10000
	s_cmp_eq_u32 s50, 12
	s_cselect_b32 s27, s44, s25
	s_cselect_b32 s26, s45, s24
	s_cselect_b32 s25, s46, s49
	s_cselect_b32 s24, s47, s48
	s_add_i32 s54, 0, 0x14000
	v_add_u32_e32 v142, s51, v168
	v_add_u32_e32 v166, s54, v168
	ds_read_b128 v[130:133], v142
	ds_read_b128 v[134:137], v142 offset:1024
	ds_read_b128 v[138:141], v142 offset:2048
	ds_read_b128 v[142:145], v142 offset:3072
	ds_read_b128 v[158:161], v166
	ds_read_b128 v[162:165], v166 offset:1024
	ds_read_b128 v[172:175], v166 offset:2048
	ds_read_b128 v[176:179], v166 offset:3072
	s_add_i32 m0, s7, 0xc000
	ds_read_b128 v[180:183], v171
	ds_read_b128 v[184:187], v171 offset:1024
	ds_read_b128 v[202:205], v171 offset:2048
	ds_read_b128 v[206:209], v171 offset:3072
	ds_read_b128 v[210:213], v171 offset:4096
	ds_read_b128 v[232:235], v171 offset:5120
	ds_read_b128 v[236:239], v171 offset:6144
	ds_read_b128 v[240:243], v171 offset:7168
	global_load_lds_dwordx4 v154, s[22:23]
	s_add_i32 m0, s7, 0xe000
	s_nop 0
	global_load_lds_dwordx4 v156, s[22:23]
	s_waitcnt vmcnt(8)
	s_waitcnt lgkmcnt(0)
	s_barrier
	s_setprio 1
	s_waitcnt lgkmcnt(0)
	v_mfma_f32_16x16x32_bf16 v[126:129], v[130:133], v[180:183], v[126:129]
	v_mfma_f32_16x16x32_bf16 v[118:121], v[138:141], v[180:183], v[118:121]
	v_mfma_f32_16x16x32_bf16 v[110:113], v[130:133], v[202:205], v[110:113]
	v_mfma_f32_16x16x32_bf16 v[102:105], v[138:141], v[202:205], v[102:105]
	v_mfma_f32_16x16x32_bf16 v[94:97], v[130:133], v[210:213], v[94:97]
	v_mfma_f32_16x16x32_bf16 v[86:89], v[138:141], v[210:213], v[86:89]
	v_mfma_f32_16x16x32_bf16 v[78:81], v[130:133], v[236:239], v[78:81]
	v_mfma_f32_16x16x32_bf16 v[70:73], v[138:141], v[236:239], v[70:73]
	v_mfma_f32_16x16x32_bf16 v[126:129], v[134:137], v[184:187], v[126:129]
	v_mfma_f32_16x16x32_bf16 v[118:121], v[142:145], v[184:187], v[118:121]
	v_mfma_f32_16x16x32_bf16 v[110:113], v[134:137], v[206:209], v[110:113]
	v_mfma_f32_16x16x32_bf16 v[102:105], v[142:145], v[206:209], v[102:105]
	v_mfma_f32_16x16x32_bf16 v[94:97], v[134:137], v[232:235], v[94:97]
	v_mfma_f32_16x16x32_bf16 v[86:89], v[142:145], v[232:235], v[86:89]
	v_mfma_f32_16x16x32_bf16 v[78:81], v[134:137], v[240:243], v[78:81]
	v_mfma_f32_16x16x32_bf16 v[70:73], v[142:145], v[240:243], v[70:73]
	v_mfma_f32_16x16x32_bf16 v[122:125], v[158:161], v[180:183], v[122:125]
	v_mfma_f32_16x16x32_bf16 v[114:117], v[172:175], v[180:183], v[114:117]
	v_mfma_f32_16x16x32_bf16 v[106:109], v[158:161], v[202:205], v[106:109]
	v_mfma_f32_16x16x32_bf16 v[98:101], v[172:175], v[202:205], v[98:101]
	v_mfma_f32_16x16x32_bf16 v[90:93], v[158:161], v[210:213], v[90:93]
	v_mfma_f32_16x16x32_bf16 v[82:85], v[172:175], v[210:213], v[82:85]
	v_mfma_f32_16x16x32_bf16 v[74:77], v[158:161], v[236:239], v[74:77]
	v_mfma_f32_16x16x32_bf16 v[66:69], v[172:175], v[236:239], v[66:69]
	v_mfma_f32_16x16x32_bf16 v[122:125], v[162:165], v[184:187], v[122:125]
	v_mfma_f32_16x16x32_bf16 v[114:117], v[176:179], v[184:187], v[114:117]
	v_mfma_f32_16x16x32_bf16 v[106:109], v[162:165], v[206:209], v[106:109]
	v_mfma_f32_16x16x32_bf16 v[98:101], v[176:179], v[206:209], v[98:101]
	v_mfma_f32_16x16x32_bf16 v[90:93], v[162:165], v[232:235], v[90:93]
	v_mfma_f32_16x16x32_bf16 v[82:85], v[176:179], v[232:235], v[82:85]
	v_mfma_f32_16x16x32_bf16 v[74:77], v[162:165], v[240:243], v[74:77]
	v_mfma_f32_16x16x32_bf16 v[66:69], v[176:179], v[240:243], v[66:69]
	s_setprio 0
	s_barrier
	s_add_i32 s51, s51, s30
	s_mov_b32 m0, s51
	ds_read_b128 v[180:183], v171 offset:16384
	ds_read_b128 v[184:187], v171 offset:17408
	ds_read_b128 v[202:205], v171 offset:18432
	ds_read_b128 v[206:209], v171 offset:19456
	ds_read_b128 v[210:213], v171 offset:20480
	ds_read_b128 v[232:235], v171 offset:21504
	ds_read_b128 v[236:239], v171 offset:22528
	ds_read_b128 v[240:243], v171 offset:23552
	s_add_u32 s60, s24, 0x80
	s_addc_u32 s61, s25, 0
	s_add_u32 s62, s26, 0x80
	s_addc_u32 s63, s27, 0
	global_load_lds_dwordx4 v150, s[24:25]
	s_add_i32 m0, s51, 0x2000
	s_add_u32 s52, s24, 0x40000
	s_addc_u32 s53, s25, 0
	s_add_i32 s51, s54, s30
	global_load_lds_dwordx4 v146, s[24:25]
	s_mov_b32 m0, s51
	s_nop 0
	global_load_lds_dwordx4 v150, s[52:53]
	s_add_i32 m0, s51, 0x2000
	s_nop 0
	global_load_lds_dwordx4 v146, s[52:53]
	s_mov_b32 m0, s7
	s_nop 0
	global_load_lds_dwordx4 v152, s[26:27]
	s_mov_b32 m0, s36
	s_nop 0
	global_load_lds_dwordx4 v148, s[26:27]
	s_waitcnt vmcnt(8)
	s_waitcnt lgkmcnt(0)
	s_barrier
	s_setprio 1
	s_waitcnt lgkmcnt(0)
	v_mfma_f32_16x16x32_bf16 v[62:65], v[130:133], v[180:183], v[62:65]
	v_mfma_f32_16x16x32_bf16 v[54:57], v[138:141], v[180:183], v[54:57]
	v_mfma_f32_16x16x32_bf16 v[46:49], v[130:133], v[202:205], v[46:49]
	v_mfma_f32_16x16x32_bf16 v[38:41], v[138:141], v[202:205], v[38:41]
	v_mfma_f32_16x16x32_bf16 v[30:33], v[130:133], v[210:213], v[30:33]
	v_mfma_f32_16x16x32_bf16 v[22:25], v[138:141], v[210:213], v[22:25]
	v_mfma_f32_16x16x32_bf16 v[14:17], v[130:133], v[236:239], v[14:17]
	v_mfma_f32_16x16x32_bf16 v[6:9], v[138:141], v[236:239], v[6:9]
	v_mfma_f32_16x16x32_bf16 v[62:65], v[134:137], v[184:187], v[62:65]
	v_mfma_f32_16x16x32_bf16 v[54:57], v[142:145], v[184:187], v[54:57]
	v_mfma_f32_16x16x32_bf16 v[46:49], v[134:137], v[206:209], v[46:49]
	v_mfma_f32_16x16x32_bf16 v[38:41], v[142:145], v[206:209], v[38:41]
	v_mfma_f32_16x16x32_bf16 v[30:33], v[134:137], v[232:235], v[30:33]
	v_mfma_f32_16x16x32_bf16 v[22:25], v[142:145], v[232:235], v[22:25]
	v_mfma_f32_16x16x32_bf16 v[14:17], v[134:137], v[240:243], v[14:17]
	v_mfma_f32_16x16x32_bf16 v[6:9], v[142:145], v[240:243], v[6:9]
	v_mfma_f32_16x16x32_bf16 v[58:61], v[158:161], v[180:183], v[58:61]
	v_mfma_f32_16x16x32_bf16 v[50:53], v[172:175], v[180:183], v[50:53]
	v_mfma_f32_16x16x32_bf16 v[42:45], v[158:161], v[202:205], v[42:45]
	v_mfma_f32_16x16x32_bf16 v[34:37], v[172:175], v[202:205], v[34:37]
	v_mfma_f32_16x16x32_bf16 v[26:29], v[158:161], v[210:213], v[26:29]
	v_mfma_f32_16x16x32_bf16 v[18:21], v[172:175], v[210:213], v[18:21]
	v_mfma_f32_16x16x32_bf16 v[10:13], v[158:161], v[236:239], v[10:13]
	v_mfma_f32_16x16x32_bf16 v[2:5], v[172:175], v[236:239], v[2:5]
	v_mfma_f32_16x16x32_bf16 v[58:61], v[162:165], v[184:187], v[58:61]
	v_mfma_f32_16x16x32_bf16 v[50:53], v[176:179], v[184:187], v[50:53]
	v_mfma_f32_16x16x32_bf16 v[42:45], v[162:165], v[206:209], v[42:45]
	v_mfma_f32_16x16x32_bf16 v[34:37], v[176:179], v[206:209], v[34:37]
	v_mfma_f32_16x16x32_bf16 v[26:29], v[162:165], v[232:235], v[26:29]
	v_mfma_f32_16x16x32_bf16 v[18:21], v[176:179], v[232:235], v[18:21]
	v_mfma_f32_16x16x32_bf16 v[10:13], v[162:165], v[240:243], v[10:13]
	v_mfma_f32_16x16x32_bf16 v[2:5], v[176:179], v[240:243], v[2:5]
	s_setprio 0
	s_barrier
; #define PG8_STAGE(bufoff, gbase, voff) do { _Pragma("unroll") for (int _i = 0; _i < 2; ++_i) \
;         __builtin_amdgcn_global_load_lds((const unsigned*)((const char*)(gbase) + (voff)[_i]), (PG8_LAS unsigned*)(lds + (bufoff) + ldsw + _i * 8192), 16, 0, 0); } while (0)
; #define PG8_LDA(dst, b, h) do { _Pragma("unroll") for (int m = 0; m < 4; ++m) _Pragma("unroll") for (int k = 0; k < 2; ++k) dst[m][k] = *(const PG8_LAS bf16x8*)(lds + PG8_SA(b, h) + aoff + m * 2048 + k * 1024); } while (0)
; #define PG8_LDB(dst, b, h) do { _Pragma("unroll") for (int n = 0; n < 2; ++n) _Pragma("unroll") for (int k = 0; k < 2; ++k) dst[n][k] = *(const PG8_LAS bf16x8*)(lds + PG8_SB(b, h) + boff + n * 2048 + k * 1024); } while (0)
; #define PG8_MMA(ai, bj, At, Bt) do { __builtin_amdgcn_s_setprio(1); _Pragma("unroll") for (int m = 0; m < 4; ++m) _Pragma("unroll") for (int n = 0; n < 2; ++n) _Pragma("unroll") for (int k = 0; k < 2; ++k) \
;         acc[ai][bj][m][n] = __builtin_amdgcn_mfma_f32_16x16x32_bf16(Bt[n][k], At[m][k], acc[ai][bj][m][n], 0, 0, 0); __builtin_amdgcn_s_setprio(0); } while (0)
; #define PG8_WAIT_V(n) asm volatile("s_waitcnt vmcnt(" #n ")" ::: "memory")
; template <class Epi, class Sched, bool ALIGN_EPI = false, bool SP2 = false>
; __device__ __forceinline__ void gemm_phase(PG8_LAS unsigned char* lds, const Gemm g, const Sched& S, const Epi& E) {
;     ...
;             PG8_LDB(B0, 0, 0); PG8_LDB(B1, 0, 1); PG8_SCHED; PG8_LDA(At, 0, 0); PG8_STAGE(PG8_SA(1, 1), a1 + hstepA, voffA);
;             PG8_WAIT_V(8); PG8_WAIT_L(0); PG8_BAR; PG8_MMA(0, 0, At, B0); PG8_MMA(0, 1, At, B1); PG8_BAR; PG8_SCHED;
;             PG8_LDA(At, 0, 1); PG8_STAGE(PG8_SB(0, 0), b2, voffB); PG8_STAGE(PG8_SB(0, 1), b2 + hstepB, voffB); PG8_STAGE(PG8_SA(0, 0), a2, voffA);
;             PG8_WAIT_V(8); PG8_WAIT_L(0); PG8_BAR; PG8_MMA(1, 0, At, B0); PG8_MMA(1, 1, At, B1); PG8_BAR; PG8_SCHED;
;             PG8_LDB(B0, 1, 0); PG8_LDB(B1, 1, 1); PG8_SCHED; PG8_LDA(At, 1, 0); PG8_STAGE(PG8_SA(0, 1), a2 + hstepA, voffA);
;             PG8_WAIT_V(8); PG8_WAIT_L(0); PG8_BAR; PG8_MMA(0, 0, At, B0); PG8_MMA(0, 1, At, B1); PG8_BAR; PG8_SCHED;
;             PG8_LDA(At, 1, 1); PG8_STAGE(PG8_SB(1, 0), b3, voffB); PG8_STAGE(PG8_SB(1, 1), b3 + hstepB, voffB); PG8_STAGE(PG8_SA(1, 0), a3, voffA);
;             PG8_WAIT_V(8); PG8_WAIT_L(0); PG8_BAR; PG8_MMA(1, 0, At, B0); PG8_MMA(1, 1, At, B1); PG8_BAR; PG8_SCHED;
	s_add_i32 s51, 0, 0x18000
	s_add_i32 s52, 0, 0x1c000
	v_add_u32_e32 v142, s51, v168
	v_add_u32_e32 v176, s52, v168
	ds_read_b128 v[130:133], v142
	ds_read_b128 v[134:137], v142 offset:1024
	ds_read_b128 v[138:141], v142 offset:2048
	ds_read_b128 v[142:145], v142 offset:3072
	ds_read_b128 v[158:161], v176
	ds_read_b128 v[162:165], v176 offset:1024
	ds_read_b128 v[172:175], v176 offset:2048
	ds_read_b128 v[176:179], v176 offset:3072
	s_add_u32 s26, s26, 0x40000
	s_addc_u32 s27, s27, 0
	s_mov_b32 m0, s37
	ds_read_b128 v[180:183], v171 offset:32768
	ds_read_b128 v[184:187], v171 offset:33792
	ds_read_b128 v[202:205], v171 offset:34816
	ds_read_b128 v[206:209], v171 offset:35840
	ds_read_b128 v[210:213], v171 offset:36864
	ds_read_b128 v[232:235], v171 offset:37888
	ds_read_b128 v[236:239], v171 offset:38912
	ds_read_b128 v[240:243], v171 offset:39936
	global_load_lds_dwordx4 v152, s[26:27]
	s_mov_b32 m0, s38
	s_nop 0
	global_load_lds_dwordx4 v148, s[26:27]
	s_waitcnt vmcnt(8)
	s_waitcnt lgkmcnt(0)
	s_barrier
	s_setprio 1
	s_waitcnt lgkmcnt(0)
	v_mfma_f32_16x16x32_bf16 v[126:129], v[130:133], v[180:183], v[126:129]
	v_mfma_f32_16x16x32_bf16 v[118:121], v[138:141], v[180:183], v[118:121]
	v_mfma_f32_16x16x32_bf16 v[110:113], v[130:133], v[202:205], v[110:113]
	v_mfma_f32_16x16x32_bf16 v[102:105], v[138:141], v[202:205], v[102:105]
	v_mfma_f32_16x16x32_bf16 v[94:97], v[130:133], v[210:213], v[94:97]
	v_mfma_f32_16x16x32_bf16 v[86:89], v[138:141], v[210:213], v[86:89]
	v_mfma_f32_16x16x32_bf16 v[78:81], v[130:133], v[236:239], v[78:81]
	v_mfma_f32_16x16x32_bf16 v[70:73], v[138:141], v[236:239], v[70:73]
	v_mfma_f32_16x16x32_bf16 v[126:129], v[134:137], v[184:187], v[126:129]
	v_mfma_f32_16x16x32_bf16 v[118:121], v[142:145], v[184:187], v[118:121]
	v_mfma_f32_16x16x32_bf16 v[110:113], v[134:137], v[206:209], v[110:113]
	v_mfma_f32_16x16x32_bf16 v[102:105], v[142:145], v[206:209], v[102:105]
	v_mfma_f32_16x16x32_bf16 v[94:97], v[134:137], v[232:235], v[94:97]
	v_mfma_f32_16x16x32_bf16 v[86:89], v[142:145], v[232:235], v[86:89]
	v_mfma_f32_16x16x32_bf16 v[78:81], v[134:137], v[240:243], v[78:81]
	v_mfma_f32_16x16x32_bf16 v[70:73], v[142:145], v[240:243], v[70:73]
	v_mfma_f32_16x16x32_bf16 v[122:125], v[158:161], v[180:183], v[122:125]
	v_mfma_f32_16x16x32_bf16 v[114:117], v[172:175], v[180:183], v[114:117]
	v_mfma_f32_16x16x32_bf16 v[106:109], v[158:161], v[202:205], v[106:109]
	v_mfma_f32_16x16x32_bf16 v[98:101], v[172:175], v[202:205], v[98:101]
	v_mfma_f32_16x16x32_bf16 v[90:93], v[158:161], v[210:213], v[90:93]
	v_mfma_f32_16x16x32_bf16 v[82:85], v[172:175], v[210:213], v[82:85]
	v_mfma_f32_16x16x32_bf16 v[74:77], v[158:161], v[236:239], v[74:77]
	v_mfma_f32_16x16x32_bf16 v[66:69], v[172:175], v[236:239], v[66:69]
	v_mfma_f32_16x16x32_bf16 v[122:125], v[162:165], v[184:187], v[122:125]
	v_mfma_f32_16x16x32_bf16 v[114:117], v[176:179], v[184:187], v[114:117]
	v_mfma_f32_16x16x32_bf16 v[106:109], v[162:165], v[206:209], v[106:109]
	v_mfma_f32_16x16x32_bf16 v[98:101], v[176:179], v[206:209], v[98:101]
	v_mfma_f32_16x16x32_bf16 v[90:93], v[162:165], v[232:235], v[90:93]
	v_mfma_f32_16x16x32_bf16 v[82:85], v[176:179], v[232:235], v[82:85]
	v_mfma_f32_16x16x32_bf16 v[74:77], v[162:165], v[240:243], v[74:77]
	v_mfma_f32_16x16x32_bf16 v[66:69], v[176:179], v[240:243], v[66:69]
	s_setprio 0
	s_barrier
	s_add_i32 s26, s51, s30
	s_mov_b32 m0, s26
	ds_read_b128 v[180:183], v171 offset:49152
	ds_read_b128 v[184:187], v171 offset:50176
	ds_read_b128 v[202:205], v171 offset:51200
	ds_read_b128 v[206:209], v171 offset:52224
	ds_read_b128 v[210:213], v171 offset:53248
	ds_read_b128 v[232:235], v171 offset:54272
	ds_read_b128 v[236:239], v171 offset:55296
	ds_read_b128 v[240:243], v171 offset:56320
	global_load_lds_dwordx4 v150, s[60:61]
	s_add_i32 m0, s26, 0x2000
	s_add_u32 s24, s24, 0x40080
	s_addc_u32 s25, s25, 0
	s_add_i32 s26, s52, s30
	global_load_lds_dwordx4 v146, s[60:61]
	s_mov_b32 m0, s26
	s_nop 0
	global_load_lds_dwordx4 v150, s[24:25]
	s_add_i32 m0, s26, 0x2000
	s_nop 0
	global_load_lds_dwordx4 v146, s[24:25]
	s_mov_b32 m0, s39
	s_nop 0
	global_load_lds_dwordx4 v152, s[62:63]
	s_mov_b32 m0, s40
	s_nop 0
	global_load_lds_dwordx4 v148, s[62:63]
	s_waitcnt vmcnt(8)
	s_waitcnt lgkmcnt(0)
	s_barrier
	s_setprio 1
	s_waitcnt lgkmcnt(0)
	v_mfma_f32_16x16x32_bf16 v[62:65], v[130:133], v[180:183], v[62:65]
	v_mfma_f32_16x16x32_bf16 v[54:57], v[138:141], v[180:183], v[54:57]
	v_mfma_f32_16x16x32_bf16 v[46:49], v[130:133], v[202:205], v[46:49]
	v_mfma_f32_16x16x32_bf16 v[38:41], v[138:141], v[202:205], v[38:41]
	v_mfma_f32_16x16x32_bf16 v[30:33], v[130:133], v[210:213], v[30:33]
	v_mfma_f32_16x16x32_bf16 v[22:25], v[138:141], v[210:213], v[22:25]
	v_mfma_f32_16x16x32_bf16 v[14:17], v[130:133], v[236:239], v[14:17]
	v_mfma_f32_16x16x32_bf16 v[6:9], v[138:141], v[236:239], v[6:9]
	v_mfma_f32_16x16x32_bf16 v[62:65], v[134:137], v[184:187], v[62:65]
	v_mfma_f32_16x16x32_bf16 v[54:57], v[142:145], v[184:187], v[54:57]
	v_mfma_f32_16x16x32_bf16 v[46:49], v[134:137], v[206:209], v[46:49]
	v_mfma_f32_16x16x32_bf16 v[38:41], v[142:145], v[206:209], v[38:41]
	v_mfma_f32_16x16x32_bf16 v[30:33], v[134:137], v[232:235], v[30:33]
	v_mfma_f32_16x16x32_bf16 v[22:25], v[142:145], v[232:235], v[22:25]
	v_mfma_f32_16x16x32_bf16 v[14:17], v[134:137], v[240:243], v[14:17]
	v_mfma_f32_16x16x32_bf16 v[6:9], v[142:145], v[240:243], v[6:9]
	v_mfma_f32_16x16x32_bf16 v[58:61], v[158:161], v[180:183], v[58:61]
	v_mfma_f32_16x16x32_bf16 v[50:53], v[172:175], v[180:183], v[50:53]
	v_mfma_f32_16x16x32_bf16 v[42:45], v[158:161], v[202:205], v[42:45]
	v_mfma_f32_16x16x32_bf16 v[34:37], v[172:175], v[202:205], v[34:37]
	v_mfma_f32_16x16x32_bf16 v[26:29], v[158:161], v[210:213], v[26:29]
	v_mfma_f32_16x16x32_bf16 v[18:21], v[172:175], v[210:213], v[18:21]
	v_mfma_f32_16x16x32_bf16 v[10:13], v[158:161], v[236:239], v[10:13]
	v_mfma_f32_16x16x32_bf16 v[2:5], v[172:175], v[236:239], v[2:5]
	v_mfma_f32_16x16x32_bf16 v[58:61], v[162:165], v[184:187], v[58:61]
	v_mfma_f32_16x16x32_bf16 v[50:53], v[176:179], v[184:187], v[50:53]
	v_mfma_f32_16x16x32_bf16 v[42:45], v[162:165], v[206:209], v[42:45]
	v_mfma_f32_16x16x32_bf16 v[34:37], v[176:179], v[206:209], v[34:37]
	v_mfma_f32_16x16x32_bf16 v[26:29], v[162:165], v[232:235], v[26:29]
	v_mfma_f32_16x16x32_bf16 v[18:21], v[176:179], v[232:235], v[18:21]
	v_mfma_f32_16x16x32_bf16 v[10:13], v[162:165], v[240:243], v[10:13]
	v_mfma_f32_16x16x32_bf16 v[2:5], v[176:179], v[240:243], v[2:5]
	s_setprio 0
	s_barrier
	s_add_i32 s50, s50, 2
	s_add_u32 s22, s22, 0x100
	s_addc_u32 s23, s23, 0
	s_add_u32 s48, s48, 0x100
	s_addc_u32 s49, s49, 0
	s_cmp_gt_u32 s50, 13
	s_cbranch_scc0 .LBB0_1190
	s_and_b64 vcc, exec, s[18:19]
	s_cbranch_vccz .LBB0_1193
	s_barrier

; #define PG8_STAGE(bufoff, gbase, voff) do { _Pragma("unroll") for (int _i = 0; _i < 2; ++_i) \
;         __builtin_amdgcn_global_load_lds((const unsigned*)((const char*)(gbase) + (voff)[_i]), (PG8_LAS unsigned*)(lds + (bufoff) + ldsw + _i * 8192), 16, 0, 0); } while (0)
; #define PG8_LDA(dst, b, h) do { _Pragma("unroll") for (int m = 0; m < 4; ++m) _Pragma("unroll") for (int k = 0; k < 2; ++k) dst[m][k] = *(const PG8_LAS bf16x8*)(lds + PG8_SA(b, h) + aoff + m * 2048 + k * 1024); } while (0)
; #define PG8_LDB(dst, b, h) do { _Pragma("unroll") for (int n = 0; n < 2; ++n) _Pragma("unroll") for (int k = 0; k < 2; ++k) dst[n][k] = *(const PG8_LAS bf16x8*)(lds + PG8_SB(b, h) + boff + n * 2048 + k * 1024); } while (0)
; template <class Epi, class Sched, bool ALIGN_EPI = false, bool SP2 = false>
; __device__ __forceinline__ void gemm_phase(PG8_LAS unsigned char* lds, const Gemm g, const Sched& S, const Epi& E) {
;     ...
;         for (int t = 0; t < nt; t += 2) {
;             const bool last = (t == nt - 2);
;             const char* a1 = cA + (size_t)(t + 1) * kstep;
;             const char* a2 = last ? nA : cA + (size_t)(t + 2) * kstep; const char* b2 = last ? nB : cB + (size_t)(t + 2) * kstep;
;             const char* a3 = a2 + kstep; const char* b3 = b2 + kstep;
;             if (last && has_next) S.a_ready(nxt);
;             if constexpr (SP2) {
;             PG8_LDB(B0, 0, 0); PG8_LDB(B1, 0, 1); PG8_SCHED; PG8_LDA(At, 0, 0); PG8_STAGE(PG8_SA(1, 1), a1 + hstepA, voffA);
;             PG8_WAIT_V(8); PG8_WAIT_L(0); PG8_BAR; PG8_MMA(0, 0, At, B0); PG8_MMA(0, 1, At, B1); PG8_BAR; PG8_SCHED;
;             PG8_LDA(At, 0, 1); PG8_STAGE(PG8_SB(0, 0), b2, voffB); PG8_STAGE(PG8_SB(0, 1), b2 + hstepB, voffB); PG8_STAGE(PG8_SA(0, 0), a2, voffA);
;             PG8_WAIT_V(8); PG8_WAIT_L(0); PG8_BAR; PG8_MMA(1, 0, At, B0); PG8_MMA(1, 1, At, B1); PG8_BAR; PG8_SCHED;
;             PG8_LDB(B0, 1, 0); PG8_LDB(B1, 1, 1); PG8_SCHED; PG8_LDA(At, 1, 0); PG8_STAGE(PG8_SA(0, 1), a2 + hstepA, voffA);
;             PG8_WAIT_V(8); PG8_WAIT_L(0); PG8_BAR; PG8_MMA(0, 0, At, B0); PG8_MMA(0, 1, At, B1); PG8_BAR; PG8_SCHED;
;             PG8_LDA(At, 1, 1); PG8_STAGE(PG8_SB(1, 0), b3, voffB); PG8_STAGE(PG8_SB(1, 1), b3 + hstepB, voffB); PG8_STAGE(PG8_SA(1, 0), a3, voffA);
;             PG8_WAIT_V(8); PG8_WAIT_L(0); PG8_BAR; PG8_MMA(1, 0, At, B0); PG8_MMA(1, 1, At, B1); PG8_BAR; PG8_SCHED;
.LBB0_1270:
	s_add_u32 s28, s26, 0xfffc0080
	s_addc_u32 s29, s27, -1
	s_add_i32 s52, 0, 0x10000
	s_cmp_eq_u32 s51, 12
	s_cselect_b32 s31, s17, s29
	s_cselect_b32 s30, s23, s28
	s_cselect_b32 s29, s15, s50
	s_cselect_b32 s28, s25, s49
	s_add_i32 s54, 0, 0x14000
	v_add_u32_e32 v142, s52, v186
	v_add_u32_e32 v172, s54, v186
	ds_read_b128 v[130:133], v142
	ds_read_b128 v[134:137], v142 offset:1024
	ds_read_b128 v[138:141], v142 offset:2048
	ds_read_b128 v[142:145], v142 offset:3072
	ds_read_b128 v[146:149], v172
	ds_read_b128 v[150:153], v172 offset:1024
	ds_read_b128 v[168:171], v172 offset:2048
	ds_read_b128 v[172:175], v172 offset:3072
	s_add_i32 m0, s39, 0xc000
	ds_read_b128 v[176:179], v200
	ds_read_b128 v[180:183], v200 offset:1024
	ds_read_b128 v[202:205], v200 offset:2048
	ds_read_b128 v[206:209], v200 offset:3072
	ds_read_b128 v[210:213], v200 offset:4096
	ds_read_b128 v[232:235], v200 offset:5120
	ds_read_b128 v[236:239], v200 offset:6144
	ds_read_b128 v[240:243], v200 offset:7168
	global_load_lds_dwordx4 v164, s[26:27]
	s_add_i32 m0, s39, 0xe000
	s_nop 0
	global_load_lds_dwordx4 v166, s[26:27]
	s_waitcnt vmcnt(8)
	s_waitcnt lgkmcnt(0)
	s_barrier
	s_setprio 1
	s_waitcnt lgkmcnt(0)
	v_mfma_f32_16x16x32_bf16 v[126:129], v[130:133], v[176:179], v[126:129]
	v_mfma_f32_16x16x32_bf16 v[122:125], v[138:141], v[176:179], v[122:125]
	v_mfma_f32_16x16x32_bf16 v[110:113], v[130:133], v[202:205], v[110:113]
	v_mfma_f32_16x16x32_bf16 v[106:109], v[138:141], v[202:205], v[106:109]
	v_mfma_f32_16x16x32_bf16 v[94:97], v[130:133], v[210:213], v[94:97]
	v_mfma_f32_16x16x32_bf16 v[90:93], v[138:141], v[210:213], v[90:93]
	v_mfma_f32_16x16x32_bf16 v[78:81], v[130:133], v[236:239], v[78:81]
	v_mfma_f32_16x16x32_bf16 v[74:77], v[138:141], v[236:239], v[74:77]
	v_mfma_f32_16x16x32_bf16 v[126:129], v[134:137], v[180:183], v[126:129]
	v_mfma_f32_16x16x32_bf16 v[122:125], v[142:145], v[180:183], v[122:125]
	v_mfma_f32_16x16x32_bf16 v[110:113], v[134:137], v[206:209], v[110:113]
	v_mfma_f32_16x16x32_bf16 v[106:109], v[142:145], v[206:209], v[106:109]
	v_mfma_f32_16x16x32_bf16 v[94:97], v[134:137], v[232:235], v[94:97]
	v_mfma_f32_16x16x32_bf16 v[90:93], v[142:145], v[232:235], v[90:93]
	v_mfma_f32_16x16x32_bf16 v[78:81], v[134:137], v[240:243], v[78:81]
	v_mfma_f32_16x16x32_bf16 v[74:77], v[142:145], v[240:243], v[74:77]
	v_mfma_f32_16x16x32_bf16 v[118:121], v[146:149], v[176:179], v[118:121]
	v_mfma_f32_16x16x32_bf16 v[114:117], v[168:171], v[176:179], v[114:117]
	v_mfma_f32_16x16x32_bf16 v[102:105], v[146:149], v[202:205], v[102:105]
	v_mfma_f32_16x16x32_bf16 v[98:101], v[168:171], v[202:205], v[98:101]
	v_mfma_f32_16x16x32_bf16 v[86:89], v[146:149], v[210:213], v[86:89]
	v_mfma_f32_16x16x32_bf16 v[82:85], v[168:171], v[210:213], v[82:85]
	v_mfma_f32_16x16x32_bf16 v[70:73], v[146:149], v[236:239], v[70:73]
	v_mfma_f32_16x16x32_bf16 v[66:69], v[168:171], v[236:239], v[66:69]
	v_mfma_f32_16x16x32_bf16 v[118:121], v[150:153], v[180:183], v[118:121]
	v_mfma_f32_16x16x32_bf16 v[114:117], v[172:175], v[180:183], v[114:117]
	v_mfma_f32_16x16x32_bf16 v[102:105], v[150:153], v[206:209], v[102:105]
	v_mfma_f32_16x16x32_bf16 v[98:101], v[172:175], v[206:209], v[98:101]
	v_mfma_f32_16x16x32_bf16 v[86:89], v[150:153], v[232:235], v[86:89]
	v_mfma_f32_16x16x32_bf16 v[82:85], v[172:175], v[232:235], v[82:85]
	v_mfma_f32_16x16x32_bf16 v[70:73], v[150:153], v[240:243], v[70:73]
	v_mfma_f32_16x16x32_bf16 v[66:69], v[172:175], v[240:243], v[66:69]
	s_setprio 0
	s_barrier
	s_add_i32 s52, s52, s38
	s_mov_b32 m0, s52
	ds_read_b128 v[176:179], v200 offset:16384
	ds_read_b128 v[180:183], v200 offset:17408
	ds_read_b128 v[202:205], v200 offset:18432
	ds_read_b128 v[206:209], v200 offset:19456
	ds_read_b128 v[210:213], v200 offset:20480
	ds_read_b128 v[232:235], v200 offset:21504
	ds_read_b128 v[236:239], v200 offset:22528
	ds_read_b128 v[240:243], v200 offset:23552
	s_add_u32 s60, s28, 0x80
	s_addc_u32 s61, s29, 0
	s_add_u32 s62, s30, 0x80
	s_addc_u32 s63, s31, 0
	global_load_lds_dwordx4 v156, s[28:29]
	s_add_i32 m0, s52, 0x2000
	s_add_u32 s52, s28, 0x40000
	s_addc_u32 s53, s29, 0
	s_add_i32 s54, s54, s38
	global_load_lds_dwordx4 v160, s[28:29]
	s_mov_b32 m0, s54
	s_nop 0
	global_load_lds_dwordx4 v156, s[52:53]
	s_add_i32 m0, s54, 0x2000
	s_nop 0
	global_load_lds_dwordx4 v160, s[52:53]
	s_mov_b32 m0, s39
	s_nop 0
	global_load_lds_dwordx4 v154, s[30:31]
	s_mov_b32 m0, s40
	s_nop 0
	global_load_lds_dwordx4 v158, s[30:31]
	s_waitcnt vmcnt(8)
	s_waitcnt lgkmcnt(0)
	s_barrier
	s_setprio 1
	s_waitcnt lgkmcnt(0)
	v_mfma_f32_16x16x32_bf16 v[62:65], v[130:133], v[176:179], v[62:65]
	v_mfma_f32_16x16x32_bf16 v[58:61], v[138:141], v[176:179], v[58:61]
	v_mfma_f32_16x16x32_bf16 v[46:49], v[130:133], v[202:205], v[46:49]
	v_mfma_f32_16x16x32_bf16 v[42:45], v[138:141], v[202:205], v[42:45]
	v_mfma_f32_16x16x32_bf16 v[30:33], v[130:133], v[210:213], v[30:33]
	v_mfma_f32_16x16x32_bf16 v[26:29], v[138:141], v[210:213], v[26:29]
	v_mfma_f32_16x16x32_bf16 v[14:17], v[130:133], v[236:239], v[14:17]
	v_mfma_f32_16x16x32_bf16 v[10:13], v[138:141], v[236:239], v[10:13]
	v_mfma_f32_16x16x32_bf16 v[62:65], v[134:137], v[180:183], v[62:65]
	v_mfma_f32_16x16x32_bf16 v[58:61], v[142:145], v[180:183], v[58:61]
	v_mfma_f32_16x16x32_bf16 v[46:49], v[134:137], v[206:209], v[46:49]
	v_mfma_f32_16x16x32_bf16 v[42:45], v[142:145], v[206:209], v[42:45]
	v_mfma_f32_16x16x32_bf16 v[30:33], v[134:137], v[232:235], v[30:33]
	v_mfma_f32_16x16x32_bf16 v[26:29], v[142:145], v[232:235], v[26:29]
	v_mfma_f32_16x16x32_bf16 v[14:17], v[134:137], v[240:243], v[14:17]
	v_mfma_f32_16x16x32_bf16 v[10:13], v[142:145], v[240:243], v[10:13]
	v_mfma_f32_16x16x32_bf16 v[54:57], v[146:149], v[176:179], v[54:57]
	v_mfma_f32_16x16x32_bf16 v[50:53], v[168:171], v[176:179], v[50:53]
	v_mfma_f32_16x16x32_bf16 v[38:41], v[146:149], v[202:205], v[38:41]
	v_mfma_f32_16x16x32_bf16 v[34:37], v[168:171], v[202:205], v[34:37]
	v_mfma_f32_16x16x32_bf16 v[22:25], v[146:149], v[210:213], v[22:25]
	v_mfma_f32_16x16x32_bf16 v[18:21], v[168:171], v[210:213], v[18:21]
	v_mfma_f32_16x16x32_bf16 v[6:9], v[146:149], v[236:239], v[6:9]
	v_mfma_f32_16x16x32_bf16 v[2:5], v[168:171], v[236:239], v[2:5]
	v_mfma_f32_16x16x32_bf16 v[54:57], v[150:153], v[180:183], v[54:57]
	v_mfma_f32_16x16x32_bf16 v[50:53], v[172:175], v[180:183], v[50:53]
	v_mfma_f32_16x16x32_bf16 v[38:41], v[150:153], v[206:209], v[38:41]
	v_mfma_f32_16x16x32_bf16 v[34:37], v[172:175], v[206:209], v[34:37]
	v_mfma_f32_16x16x32_bf16 v[22:25], v[150:153], v[232:235], v[22:25]
	v_mfma_f32_16x16x32_bf16 v[18:21], v[172:175], v[232:235], v[18:21]
	v_mfma_f32_16x16x32_bf16 v[6:9], v[150:153], v[240:243], v[6:9]
	v_mfma_f32_16x16x32_bf16 v[2:5], v[172:175], v[240:243], v[2:5]
	s_setprio 0
	s_barrier
; #define PG8_STAGE(bufoff, gbase, voff) do { _Pragma("unroll") for (int _i = 0; _i < 2; ++_i) \
;         __builtin_amdgcn_global_load_lds((const unsigned*)((const char*)(gbase) + (voff)[_i]), (PG8_LAS unsigned*)(lds + (bufoff) + ldsw + _i * 8192), 16, 0, 0); } while (0)
; #define PG8_LDA(dst, b, h) do { _Pragma("unroll") for (int m = 0; m < 4; ++m) _Pragma("unroll") for (int k = 0; k < 2; ++k) dst[m][k] = *(const PG8_LAS bf16x8*)(lds + PG8_SA(b, h) + aoff + m * 2048 + k * 1024); } while (0)
; #define PG8_LDB(dst, b, h) do { _Pragma("unroll") for (int n = 0; n < 2; ++n) _Pragma("unroll") for (int k = 0; k < 2; ++k) dst[n][k] = *(const PG8_LAS bf16x8*)(lds + PG8_SB(b, h) + boff + n * 2048 + k * 1024); } while (0)
; #define PG8_MMA(ai, bj, At, Bt) do { __builtin_amdgcn_s_setprio(1); _Pragma("unroll") for (int m = 0; m < 4; ++m) _Pragma("unroll") for (int n = 0; n < 2; ++n) _Pragma("unroll") for (int k = 0; k < 2; ++k) \
;         acc[ai][bj][m][n] = __builtin_amdgcn_mfma_f32_16x16x32_bf16(Bt[n][k], At[m][k], acc[ai][bj][m][n], 0, 0, 0); __builtin_amdgcn_s_setprio(0); } while (0)
; #define PG8_WAIT_V(n) asm volatile("s_waitcnt vmcnt(" #n ")" ::: "memory")
; template <class Epi, class Sched, bool ALIGN_EPI = false, bool SP2 = false>
; __device__ __forceinline__ void gemm_phase(PG8_LAS unsigned char* lds, const Gemm g, const Sched& S, const Epi& E) {
;     ...
;             PG8_LDB(B0, 0, 0); PG8_LDB(B1, 0, 1); PG8_SCHED; PG8_LDA(At, 0, 0); PG8_STAGE(PG8_SA(1, 1), a1 + hstepA, voffA);
;             PG8_WAIT_V(8); PG8_WAIT_L(0); PG8_BAR; PG8_MMA(0, 0, At, B0); PG8_MMA(0, 1, At, B1); PG8_BAR; PG8_SCHED;
;             PG8_LDA(At, 0, 1); PG8_STAGE(PG8_SB(0, 0), b2, voffB); PG8_STAGE(PG8_SB(0, 1), b2 + hstepB, voffB); PG8_STAGE(PG8_SA(0, 0), a2, voffA);
;             PG8_WAIT_V(8); PG8_WAIT_L(0); PG8_BAR; PG8_MMA(1, 0, At, B0); PG8_MMA(1, 1, At, B1); PG8_BAR; PG8_SCHED;
;             PG8_LDB(B0, 1, 0); PG8_LDB(B1, 1, 1); PG8_SCHED; PG8_LDA(At, 1, 0); PG8_STAGE(PG8_SA(0, 1), a2 + hstepA, voffA);
;             PG8_WAIT_V(8); PG8_WAIT_L(0); PG8_BAR; PG8_MMA(0, 0, At, B0); PG8_MMA(0, 1, At, B1); PG8_BAR; PG8_SCHED;
;             PG8_LDA(At, 1, 1); PG8_STAGE(PG8_SB(1, 0), b3, voffB); PG8_STAGE(PG8_SB(1, 1), b3 + hstepB, voffB); PG8_STAGE(PG8_SA(1, 0), a3, voffA);
;             PG8_WAIT_V(8); PG8_WAIT_L(0); PG8_BAR; PG8_MMA(1, 0, At, B0); PG8_MMA(1, 1, At, B1); PG8_BAR; PG8_SCHED;
	s_add_i32 s52, 0, 0x18000
	s_add_i32 s53, 0, 0x1c000
	v_add_u32_e32 v142, s52, v186
	v_add_u32_e32 v172, s53, v186
	ds_read_b128 v[130:133], v142
	ds_read_b128 v[134:137], v142 offset:1024
	ds_read_b128 v[138:141], v142 offset:2048
	ds_read_b128 v[142:145], v142 offset:3072
	ds_read_b128 v[146:149], v172
	ds_read_b128 v[150:153], v172 offset:1024
	ds_read_b128 v[168:171], v172 offset:2048
	ds_read_b128 v[172:175], v172 offset:3072
	s_add_u32 s30, s30, 0x40000
	s_addc_u32 s31, s31, 0
	s_mov_b32 m0, s41
	ds_read_b128 v[176:179], v200 offset:32768
	ds_read_b128 v[180:183], v200 offset:33792
	ds_read_b128 v[202:205], v200 offset:34816
	ds_read_b128 v[206:209], v200 offset:35840
	ds_read_b128 v[210:213], v200 offset:36864
	ds_read_b128 v[232:235], v200 offset:37888
	ds_read_b128 v[236:239], v200 offset:38912
	ds_read_b128 v[240:243], v200 offset:39936
	global_load_lds_dwordx4 v154, s[30:31]
	s_mov_b32 m0, s42
	s_nop 0
	global_load_lds_dwordx4 v158, s[30:31]
	s_waitcnt vmcnt(8)
	s_waitcnt lgkmcnt(0)
	s_barrier
	s_setprio 1
	s_waitcnt lgkmcnt(0)
	v_mfma_f32_16x16x32_bf16 v[126:129], v[130:133], v[176:179], v[126:129]
	v_mfma_f32_16x16x32_bf16 v[122:125], v[138:141], v[176:179], v[122:125]
	v_mfma_f32_16x16x32_bf16 v[110:113], v[130:133], v[202:205], v[110:113]
	v_mfma_f32_16x16x32_bf16 v[106:109], v[138:141], v[202:205], v[106:109]
	v_mfma_f32_16x16x32_bf16 v[94:97], v[130:133], v[210:213], v[94:97]
	v_mfma_f32_16x16x32_bf16 v[90:93], v[138:141], v[210:213], v[90:93]
	v_mfma_f32_16x16x32_bf16 v[78:81], v[130:133], v[236:239], v[78:81]
	v_mfma_f32_16x16x32_bf16 v[74:77], v[138:141], v[236:239], v[74:77]
	v_mfma_f32_16x16x32_bf16 v[126:129], v[134:137], v[180:183], v[126:129]
	v_mfma_f32_16x16x32_bf16 v[122:125], v[142:145], v[180:183], v[122:125]
	v_mfma_f32_16x16x32_bf16 v[110:113], v[134:137], v[206:209], v[110:113]
	v_mfma_f32_16x16x32_bf16 v[106:109], v[142:145], v[206:209], v[106:109]
	v_mfma_f32_16x16x32_bf16 v[94:97], v[134:137], v[232:235], v[94:97]
	v_mfma_f32_16x16x32_bf16 v[90:93], v[142:145], v[232:235], v[90:93]
	v_mfma_f32_16x16x32_bf16 v[78:81], v[134:137], v[240:243], v[78:81]
	v_mfma_f32_16x16x32_bf16 v[74:77], v[142:145], v[240:243], v[74:77]
	v_mfma_f32_16x16x32_bf16 v[118:121], v[146:149], v[176:179], v[118:121]
	v_mfma_f32_16x16x32_bf16 v[114:117], v[168:171], v[176:179], v[114:117]
	v_mfma_f32_16x16x32_bf16 v[102:105], v[146:149], v[202:205], v[102:105]
	v_mfma_f32_16x16x32_bf16 v[98:101], v[168:171], v[202:205], v[98:101]
	v_mfma_f32_16x16x32_bf16 v[86:89], v[146:149], v[210:213], v[86:89]
	v_mfma_f32_16x16x32_bf16 v[82:85], v[168:171], v[210:213], v[82:85]
	v_mfma_f32_16x16x32_bf16 v[70:73], v[146:149], v[236:239], v[70:73]
	v_mfma_f32_16x16x32_bf16 v[66:69], v[168:171], v[236:239], v[66:69]
	v_mfma_f32_16x16x32_bf16 v[118:121], v[150:153], v[180:183], v[118:121]
	v_mfma_f32_16x16x32_bf16 v[114:117], v[172:175], v[180:183], v[114:117]
	v_mfma_f32_16x16x32_bf16 v[102:105], v[150:153], v[206:209], v[102:105]
	v_mfma_f32_16x16x32_bf16 v[98:101], v[172:175], v[206:209], v[98:101]
	v_mfma_f32_16x16x32_bf16 v[86:89], v[150:153], v[232:235], v[86:89]
	v_mfma_f32_16x16x32_bf16 v[82:85], v[172:175], v[232:235], v[82:85]
	v_mfma_f32_16x16x32_bf16 v[70:73], v[150:153], v[240:243], v[70:73]
	v_mfma_f32_16x16x32_bf16 v[66:69], v[172:175], v[240:243], v[66:69]
	s_setprio 0
	s_barrier
	s_add_i32 s30, s52, s38
	s_mov_b32 m0, s30
	ds_read_b128 v[176:179], v200 offset:49152
	ds_read_b128 v[180:183], v200 offset:50176
	ds_read_b128 v[202:205], v200 offset:51200
	ds_read_b128 v[206:209], v200 offset:52224
	ds_read_b128 v[210:213], v200 offset:53248
	ds_read_b128 v[232:235], v200 offset:54272
	ds_read_b128 v[236:239], v200 offset:55296
	ds_read_b128 v[240:243], v200 offset:56320
	global_load_lds_dwordx4 v156, s[60:61]
	s_add_i32 m0, s30, 0x2000
	s_add_u32 s28, s28, 0x40080
	s_addc_u32 s29, s29, 0
	s_add_i32 s30, s53, s38
	global_load_lds_dwordx4 v160, s[60:61]
	s_mov_b32 m0, s30
	s_nop 0
	global_load_lds_dwordx4 v156, s[28:29]
	s_add_i32 m0, s30, 0x2000
	s_nop 0
	global_load_lds_dwordx4 v160, s[28:29]
	s_mov_b32 m0, s44
	s_nop 0
	global_load_lds_dwordx4 v154, s[62:63]
	s_mov_b32 m0, s45
	s_nop 0
	global_load_lds_dwordx4 v158, s[62:63]
	s_waitcnt vmcnt(8)
	s_waitcnt lgkmcnt(0)
	s_barrier
	s_setprio 1
	s_waitcnt lgkmcnt(0)
	v_mfma_f32_16x16x32_bf16 v[62:65], v[130:133], v[176:179], v[62:65]
	v_mfma_f32_16x16x32_bf16 v[58:61], v[138:141], v[176:179], v[58:61]
	v_mfma_f32_16x16x32_bf16 v[46:49], v[130:133], v[202:205], v[46:49]
	v_mfma_f32_16x16x32_bf16 v[42:45], v[138:141], v[202:205], v[42:45]
	v_mfma_f32_16x16x32_bf16 v[30:33], v[130:133], v[210:213], v[30:33]
	v_mfma_f32_16x16x32_bf16 v[26:29], v[138:141], v[210:213], v[26:29]
	v_mfma_f32_16x16x32_bf16 v[14:17], v[130:133], v[236:239], v[14:17]
	v_mfma_f32_16x16x32_bf16 v[10:13], v[138:141], v[236:239], v[10:13]
	v_mfma_f32_16x16x32_bf16 v[62:65], v[134:137], v[180:183], v[62:65]
	v_mfma_f32_16x16x32_bf16 v[58:61], v[142:145], v[180:183], v[58:61]
	v_mfma_f32_16x16x32_bf16 v[46:49], v[134:137], v[206:209], v[46:49]
	v_mfma_f32_16x16x32_bf16 v[42:45], v[142:145], v[206:209], v[42:45]
	v_mfma_f32_16x16x32_bf16 v[30:33], v[134:137], v[232:235], v[30:33]
	v_mfma_f32_16x16x32_bf16 v[26:29], v[142:145], v[232:235], v[26:29]
	v_mfma_f32_16x16x32_bf16 v[14:17], v[134:137], v[240:243], v[14:17]
	v_mfma_f32_16x16x32_bf16 v[10:13], v[142:145], v[240:243], v[10:13]
	v_mfma_f32_16x16x32_bf16 v[54:57], v[146:149], v[176:179], v[54:57]
	v_mfma_f32_16x16x32_bf16 v[50:53], v[168:171], v[176:179], v[50:53]
	v_mfma_f32_16x16x32_bf16 v[38:41], v[146:149], v[202:205], v[38:41]
	v_mfma_f32_16x16x32_bf16 v[34:37], v[168:171], v[202:205], v[34:37]
	v_mfma_f32_16x16x32_bf16 v[22:25], v[146:149], v[210:213], v[22:25]
	v_mfma_f32_16x16x32_bf16 v[18:21], v[168:171], v[210:213], v[18:21]
	v_mfma_f32_16x16x32_bf16 v[6:9], v[146:149], v[236:239], v[6:9]
	v_mfma_f32_16x16x32_bf16 v[2:5], v[168:171], v[236:239], v[2:5]
	v_mfma_f32_16x16x32_bf16 v[54:57], v[150:153], v[180:183], v[54:57]
	v_mfma_f32_16x16x32_bf16 v[50:53], v[172:175], v[180:183], v[50:53]
	v_mfma_f32_16x16x32_bf16 v[38:41], v[150:153], v[206:209], v[38:41]
	v_mfma_f32_16x16x32_bf16 v[34:37], v[172:175], v[206:209], v[34:37]
	v_mfma_f32_16x16x32_bf16 v[22:25], v[150:153], v[232:235], v[22:25]
	v_mfma_f32_16x16x32_bf16 v[18:21], v[172:175], v[232:235], v[18:21]
	v_mfma_f32_16x16x32_bf16 v[6:9], v[150:153], v[240:243], v[6:9]
	v_mfma_f32_16x16x32_bf16 v[2:5], v[172:175], v[240:243], v[2:5]
	s_setprio 0
	s_barrier
	s_add_i32 s51, s51, 2
	s_add_u32 s26, s26, 0x100
	s_addc_u32 s27, s27, 0
	s_add_u32 s49, s49, 0x100
	s_addc_u32 s50, s50, 0
	s_cmp_gt_u32 s51, 13
	s_cbranch_scc0 .LBB0_1270
	s_and_b64 vcc, exec, s[12:13]
	s_cbranch_vccz .LBB0_1273
	s_barrier

; #define PG8_STAGE(bufoff, gbase, voff) do { _Pragma("unroll") for (int _i = 0; _i < 2; ++_i) \
;         __builtin_amdgcn_global_load_lds((const unsigned*)((const char*)(gbase) + (voff)[_i]), (PG8_LAS unsigned*)(lds + (bufoff) + ldsw + _i * 8192), 16, 0, 0); } while (0)
; #define PG8_LDA(dst, b, h) do { _Pragma("unroll") for (int m = 0; m < 4; ++m) _Pragma("unroll") for (int k = 0; k < 2; ++k) dst[m][k] = *(const PG8_LAS bf16x8*)(lds + PG8_SA(b, h) + aoff + m * 2048 + k * 1024); } while (0)
; #define PG8_LDB(dst, b, h) do { _Pragma("unroll") for (int n = 0; n < 2; ++n) _Pragma("unroll") for (int k = 0; k < 2; ++k) dst[n][k] = *(const PG8_LAS bf16x8*)(lds + PG8_SB(b, h) + boff + n * 2048 + k * 1024); } while (0)
; template <class Epi, class Sched, bool ALIGN_EPI = false, bool SP2 = false>
; __device__ __forceinline__ void gemm_phase(PG8_LAS unsigned char* lds, const Gemm g, const Sched& S, const Epi& E) {
;     ...
;         for (int t = 0; t < nt; t += 2) {
;             const bool last = (t == nt - 2);
;             const char* a1 = cA + (size_t)(t + 1) * kstep;
;             const char* a2 = last ? nA : cA + (size_t)(t + 2) * kstep; const char* b2 = last ? nB : cB + (size_t)(t + 2) * kstep;
;             const char* a3 = a2 + kstep; const char* b3 = b2 + kstep;
;             if (last && has_next) S.a_ready(nxt);
;             if constexpr (SP2) {
;             PG8_LDB(B0, 0, 0); PG8_LDB(B1, 0, 1); PG8_SCHED; PG8_LDA(At, 0, 0); PG8_STAGE(PG8_SA(1, 1), a1 + hstepA, voffA);
;             PG8_WAIT_V(8); PG8_WAIT_L(0); PG8_BAR; PG8_MMA(0, 0, At, B0); PG8_MMA(0, 1, At, B1); PG8_BAR; PG8_SCHED;
;             PG8_LDA(At, 0, 1); PG8_STAGE(PG8_SB(0, 0), b2, voffB); PG8_STAGE(PG8_SB(0, 1), b2 + hstepB, voffB); PG8_STAGE(PG8_SA(0, 0), a2, voffA);
;             PG8_WAIT_V(8); PG8_WAIT_L(0); PG8_BAR; PG8_MMA(1, 0, At, B0); PG8_MMA(1, 1, At, B1); PG8_BAR; PG8_SCHED;
;             PG8_LDB(B0, 1, 0); PG8_LDB(B1, 1, 1); PG8_SCHED; PG8_LDA(At, 1, 0); PG8_STAGE(PG8_SA(0, 1), a2 + hstepA, voffA);
;             PG8_WAIT_V(8); PG8_WAIT_L(0); PG8_BAR; PG8_MMA(0, 0, At, B0); PG8_MMA(0, 1, At, B1); PG8_BAR; PG8_SCHED;
;             PG8_LDA(At, 1, 1); PG8_STAGE(PG8_SB(1, 0), b3, voffB); PG8_STAGE(PG8_SB(1, 1), b3 + hstepB, voffB); PG8_STAGE(PG8_SA(1, 0), a3, voffA);
;             PG8_WAIT_V(8); PG8_WAIT_L(0); PG8_BAR; PG8_MMA(1, 0, At, B0); PG8_MMA(1, 1, At, B1); PG8_BAR; PG8_SCHED;
.LBB0_1354:
	s_add_u32 s24, s22, 0xfffc0080
	s_addc_u32 s25, s23, -1
	s_add_i32 s49, 0, 0x10000
	s_cmp_eq_u32 s48, 12
	s_cselect_b32 s27, s15, s25
	s_cselect_b32 s26, s21, s24
	v_add_u32_e32 v142, s49, v145
	s_cselect_b32 s25, s13, s47
	s_cselect_b32 s24, s45, s46
	s_add_i32 s52, 0, 0x14000
	ds_read_b128 v[150:153], v142
	ds_read_b128 v[154:157], v142 offset:1024
	ds_read_b128 v[158:161], v142 offset:2048
	ds_read_b128 v[162:165], v142 offset:3072
	v_add_u32_e32 v142, s52, v145
	ds_read_b128 v[166:169], v142
	ds_read_b128 v[170:173], v142 offset:1024
	ds_read_b128 v[174:177], v142 offset:2048
	ds_read_b128 v[178:181], v142 offset:3072
	s_add_i32 m0, s36, 0xc000
	ds_read_b128 v[182:185], v148
	ds_read_b128 v[202:205], v148 offset:1024
	ds_read_b128 v[206:209], v148 offset:2048
	ds_read_b128 v[210:213], v148 offset:3072
	ds_read_b128 v[232:235], v148 offset:4096
	ds_read_b128 v[236:239], v148 offset:5120
	ds_read_b128 v[240:243], v148 offset:6144
	ds_read_b128 v[244:247], v148 offset:7168
	global_load_lds_dwordx4 v138, s[22:23]
	s_add_i32 m0, s36, 0xe000
	s_nop 0
	global_load_lds_dwordx4 v140, s[22:23]
	s_waitcnt vmcnt(8)
	s_waitcnt lgkmcnt(0)
	s_barrier
	s_setprio 1
	s_waitcnt lgkmcnt(0)
	v_mfma_f32_16x16x32_bf16 v[126:129], v[150:153], v[182:185], v[126:129]
	v_mfma_f32_16x16x32_bf16 v[122:125], v[158:161], v[182:185], v[122:125]
	v_mfma_f32_16x16x32_bf16 v[114:117], v[150:153], v[206:209], v[114:117]
	v_mfma_f32_16x16x32_bf16 v[106:109], v[158:161], v[206:209], v[106:109]
	v_mfma_f32_16x16x32_bf16 v[98:101], v[150:153], v[232:235], v[98:101]
	v_mfma_f32_16x16x32_bf16 v[90:93], v[158:161], v[232:235], v[90:93]
	v_mfma_f32_16x16x32_bf16 v[78:81], v[150:153], v[240:243], v[78:81]
	v_mfma_f32_16x16x32_bf16 v[74:77], v[158:161], v[240:243], v[74:77]
	v_mfma_f32_16x16x32_bf16 v[126:129], v[154:157], v[202:205], v[126:129]
	v_mfma_f32_16x16x32_bf16 v[122:125], v[162:165], v[202:205], v[122:125]
	v_mfma_f32_16x16x32_bf16 v[114:117], v[154:157], v[210:213], v[114:117]
	v_mfma_f32_16x16x32_bf16 v[106:109], v[162:165], v[210:213], v[106:109]
	v_mfma_f32_16x16x32_bf16 v[98:101], v[154:157], v[236:239], v[98:101]
	v_mfma_f32_16x16x32_bf16 v[90:93], v[162:165], v[236:239], v[90:93]
	v_mfma_f32_16x16x32_bf16 v[78:81], v[154:157], v[244:247], v[78:81]
	v_mfma_f32_16x16x32_bf16 v[74:77], v[162:165], v[244:247], v[74:77]
	v_mfma_f32_16x16x32_bf16 v[118:121], v[166:169], v[182:185], v[118:121]
	v_mfma_f32_16x16x32_bf16 v[110:113], v[174:177], v[182:185], v[110:113]
	v_mfma_f32_16x16x32_bf16 v[102:105], v[166:169], v[206:209], v[102:105]
	v_mfma_f32_16x16x32_bf16 v[94:97], v[174:177], v[206:209], v[94:97]
	v_mfma_f32_16x16x32_bf16 v[86:89], v[166:169], v[232:235], v[86:89]
	v_mfma_f32_16x16x32_bf16 v[82:85], v[174:177], v[232:235], v[82:85]
	v_mfma_f32_16x16x32_bf16 v[70:73], v[166:169], v[240:243], v[70:73]
	v_mfma_f32_16x16x32_bf16 v[66:69], v[174:177], v[240:243], v[66:69]
	v_mfma_f32_16x16x32_bf16 v[118:121], v[170:173], v[202:205], v[118:121]
	v_mfma_f32_16x16x32_bf16 v[110:113], v[178:181], v[202:205], v[110:113]
	v_mfma_f32_16x16x32_bf16 v[102:105], v[170:173], v[210:213], v[102:105]
	v_mfma_f32_16x16x32_bf16 v[94:97], v[178:181], v[210:213], v[94:97]
	v_mfma_f32_16x16x32_bf16 v[86:89], v[170:173], v[236:239], v[86:89]
	v_mfma_f32_16x16x32_bf16 v[82:85], v[178:181], v[236:239], v[82:85]
	v_mfma_f32_16x16x32_bf16 v[70:73], v[170:173], v[244:247], v[70:73]
	v_mfma_f32_16x16x32_bf16 v[66:69], v[178:181], v[244:247], v[66:69]
	s_setprio 0
	s_barrier
	s_add_i32 s49, s49, s34
	s_mov_b32 m0, s49
	ds_read_b128 v[182:185], v148 offset:16384
	ds_read_b128 v[202:205], v148 offset:17408
	ds_read_b128 v[206:209], v148 offset:18432
	ds_read_b128 v[210:213], v148 offset:19456
	ds_read_b128 v[232:235], v148 offset:20480
	ds_read_b128 v[236:239], v148 offset:21504
	ds_read_b128 v[240:243], v148 offset:22528
	ds_read_b128 v[244:247], v148 offset:23552
	s_add_u32 s60, s24, 0x80
	s_addc_u32 s61, s25, 0
	s_add_u32 s62, s26, 0x80
	s_addc_u32 s63, s27, 0
	global_load_lds_dwordx4 v134, s[24:25]
	s_add_i32 m0, s49, 0x2000
	s_add_u32 s50, s24, 0x40000
	s_addc_u32 s51, s25, 0
	s_add_i32 s49, s52, s34
	global_load_lds_dwordx4 v130, s[24:25]
	s_mov_b32 m0, s49
	s_nop 0
	global_load_lds_dwordx4 v134, s[50:51]
	s_add_i32 m0, s49, 0x2000
	s_nop 0
	global_load_lds_dwordx4 v130, s[50:51]
	s_mov_b32 m0, s36
	s_nop 0
	global_load_lds_dwordx4 v136, s[26:27]
	s_mov_b32 m0, s37
	s_nop 0
	global_load_lds_dwordx4 v132, s[26:27]
	s_waitcnt vmcnt(8)
	s_waitcnt lgkmcnt(0)
	s_barrier
	s_setprio 1
	s_waitcnt lgkmcnt(0)
	v_mfma_f32_16x16x32_bf16 v[62:65], v[150:153], v[182:185], v[62:65]
	v_mfma_f32_16x16x32_bf16 v[58:61], v[158:161], v[182:185], v[58:61]
	v_mfma_f32_16x16x32_bf16 v[46:49], v[150:153], v[206:209], v[46:49]
	v_mfma_f32_16x16x32_bf16 v[42:45], v[158:161], v[206:209], v[42:45]
	v_mfma_f32_16x16x32_bf16 v[30:33], v[150:153], v[232:235], v[30:33]
	v_mfma_f32_16x16x32_bf16 v[26:29], v[158:161], v[232:235], v[26:29]
	v_mfma_f32_16x16x32_bf16 v[14:17], v[150:153], v[240:243], v[14:17]
	v_mfma_f32_16x16x32_bf16 v[10:13], v[158:161], v[240:243], v[10:13]
	v_mfma_f32_16x16x32_bf16 v[62:65], v[154:157], v[202:205], v[62:65]
	v_mfma_f32_16x16x32_bf16 v[58:61], v[162:165], v[202:205], v[58:61]
	v_mfma_f32_16x16x32_bf16 v[46:49], v[154:157], v[210:213], v[46:49]
	v_mfma_f32_16x16x32_bf16 v[42:45], v[162:165], v[210:213], v[42:45]
	v_mfma_f32_16x16x32_bf16 v[30:33], v[154:157], v[236:239], v[30:33]
	v_mfma_f32_16x16x32_bf16 v[26:29], v[162:165], v[236:239], v[26:29]
	v_mfma_f32_16x16x32_bf16 v[14:17], v[154:157], v[244:247], v[14:17]
	v_mfma_f32_16x16x32_bf16 v[10:13], v[162:165], v[244:247], v[10:13]
	v_mfma_f32_16x16x32_bf16 v[54:57], v[166:169], v[182:185], v[54:57]
	v_mfma_f32_16x16x32_bf16 v[50:53], v[174:177], v[182:185], v[50:53]
	v_mfma_f32_16x16x32_bf16 v[38:41], v[166:169], v[206:209], v[38:41]
	v_mfma_f32_16x16x32_bf16 v[34:37], v[174:177], v[206:209], v[34:37]
	v_mfma_f32_16x16x32_bf16 v[22:25], v[166:169], v[232:235], v[22:25]
	v_mfma_f32_16x16x32_bf16 v[18:21], v[174:177], v[232:235], v[18:21]
	v_mfma_f32_16x16x32_bf16 v[6:9], v[166:169], v[240:243], v[6:9]
	v_mfma_f32_16x16x32_bf16 v[2:5], v[174:177], v[240:243], v[2:5]
	v_mfma_f32_16x16x32_bf16 v[54:57], v[170:173], v[202:205], v[54:57]
	v_mfma_f32_16x16x32_bf16 v[50:53], v[178:181], v[202:205], v[50:53]
	v_mfma_f32_16x16x32_bf16 v[38:41], v[170:173], v[210:213], v[38:41]
	v_mfma_f32_16x16x32_bf16 v[34:37], v[178:181], v[210:213], v[34:37]
	v_mfma_f32_16x16x32_bf16 v[22:25], v[170:173], v[236:239], v[22:25]
	v_mfma_f32_16x16x32_bf16 v[18:21], v[178:181], v[236:239], v[18:21]
	v_mfma_f32_16x16x32_bf16 v[6:9], v[170:173], v[244:247], v[6:9]
	v_mfma_f32_16x16x32_bf16 v[2:5], v[178:181], v[244:247], v[2:5]
	s_setprio 0
	s_barrier
; #define PG8_STAGE(bufoff, gbase, voff) do { _Pragma("unroll") for (int _i = 0; _i < 2; ++_i) \
;         __builtin_amdgcn_global_load_lds((const unsigned*)((const char*)(gbase) + (voff)[_i]), (PG8_LAS unsigned*)(lds + (bufoff) + ldsw + _i * 8192), 16, 0, 0); } while (0)
; #define PG8_LDA(dst, b, h) do { _Pragma("unroll") for (int m = 0; m < 4; ++m) _Pragma("unroll") for (int k = 0; k < 2; ++k) dst[m][k] = *(const PG8_LAS bf16x8*)(lds + PG8_SA(b, h) + aoff + m * 2048 + k * 1024); } while (0)
; #define PG8_LDB(dst, b, h) do { _Pragma("unroll") for (int n = 0; n < 2; ++n) _Pragma("unroll") for (int k = 0; k < 2; ++k) dst[n][k] = *(const PG8_LAS bf16x8*)(lds + PG8_SB(b, h) + boff + n * 2048 + k * 1024); } while (0)
; #define PG8_MMA(ai, bj, At, Bt) do { __builtin_amdgcn_s_setprio(1); _Pragma("unroll") for (int m = 0; m < 4; ++m) _Pragma("unroll") for (int n = 0; n < 2; ++n) _Pragma("unroll") for (int k = 0; k < 2; ++k) \
;         acc[ai][bj][m][n] = __builtin_amdgcn_mfma_f32_16x16x32_bf16(Bt[n][k], At[m][k], acc[ai][bj][m][n], 0, 0, 0); __builtin_amdgcn_s_setprio(0); } while (0)
; #define PG8_WAIT_V(n) asm volatile("s_waitcnt vmcnt(" #n ")" ::: "memory")
; template <class Epi, class Sched, bool ALIGN_EPI = false, bool SP2 = false>
; __device__ __forceinline__ void gemm_phase(PG8_LAS unsigned char* lds, const Gemm g, const Sched& S, const Epi& E) {
;     ...
;             PG8_LDB(B0, 0, 0); PG8_LDB(B1, 0, 1); PG8_SCHED; PG8_LDA(At, 0, 0); PG8_STAGE(PG8_SA(1, 1), a1 + hstepA, voffA);
;             PG8_WAIT_V(8); PG8_WAIT_L(0); PG8_BAR; PG8_MMA(0, 0, At, B0); PG8_MMA(0, 1, At, B1); PG8_BAR; PG8_SCHED;
;             PG8_LDA(At, 0, 1); PG8_STAGE(PG8_SB(0, 0), b2, voffB); PG8_STAGE(PG8_SB(0, 1), b2 + hstepB, voffB); PG8_STAGE(PG8_SA(0, 0), a2, voffA);
;             PG8_WAIT_V(8); PG8_WAIT_L(0); PG8_BAR; PG8_MMA(1, 0, At, B0); PG8_MMA(1, 1, At, B1); PG8_BAR; PG8_SCHED;
;             PG8_LDB(B0, 1, 0); PG8_LDB(B1, 1, 1); PG8_SCHED; PG8_LDA(At, 1, 0); PG8_STAGE(PG8_SA(0, 1), a2 + hstepA, voffA);
;             PG8_WAIT_V(8); PG8_WAIT_L(0); PG8_BAR; PG8_MMA(0, 0, At, B0); PG8_MMA(0, 1, At, B1); PG8_BAR; PG8_SCHED;
;             PG8_LDA(At, 1, 1); PG8_STAGE(PG8_SB(1, 0), b3, voffB); PG8_STAGE(PG8_SB(1, 1), b3 + hstepB, voffB); PG8_STAGE(PG8_SA(1, 0), a3, voffA);
;             PG8_WAIT_V(8); PG8_WAIT_L(0); PG8_BAR; PG8_MMA(1, 0, At, B0); PG8_MMA(1, 1, At, B1); PG8_BAR; PG8_SCHED;
	s_add_i32 s49, 0, 0x18000
	v_add_u32_e32 v144, s49, v145
	s_add_i32 s50, 0, 0x1c000
	ds_read_b128 v[150:153], v144
	ds_read_b128 v[154:157], v144 offset:1024
	ds_read_b128 v[158:161], v144 offset:2048
	ds_read_b128 v[162:165], v144 offset:3072
	v_add_u32_e32 v144, s50, v145
	ds_read_b128 v[166:169], v144
	ds_read_b128 v[170:173], v144 offset:1024
	ds_read_b128 v[174:177], v144 offset:2048
	ds_read_b128 v[178:181], v144 offset:3072
	s_add_u32 s26, s26, 0x40000
	s_addc_u32 s27, s27, 0
	s_mov_b32 m0, s38
	ds_read_b128 v[182:185], v148 offset:32768
	ds_read_b128 v[202:205], v148 offset:33792
	ds_read_b128 v[206:209], v148 offset:34816
	ds_read_b128 v[210:213], v148 offset:35840
	ds_read_b128 v[232:235], v148 offset:36864
	ds_read_b128 v[236:239], v148 offset:37888
	ds_read_b128 v[240:243], v148 offset:38912
	ds_read_b128 v[244:247], v148 offset:39936
	global_load_lds_dwordx4 v136, s[26:27]
	s_mov_b32 m0, s39
	s_nop 0
	global_load_lds_dwordx4 v132, s[26:27]
	s_waitcnt vmcnt(8)
	s_waitcnt lgkmcnt(0)
	s_barrier
	s_setprio 1
	s_waitcnt lgkmcnt(0)
	v_mfma_f32_16x16x32_bf16 v[126:129], v[150:153], v[182:185], v[126:129]
	v_mfma_f32_16x16x32_bf16 v[122:125], v[158:161], v[182:185], v[122:125]
	v_mfma_f32_16x16x32_bf16 v[114:117], v[150:153], v[206:209], v[114:117]
	v_mfma_f32_16x16x32_bf16 v[106:109], v[158:161], v[206:209], v[106:109]
	v_mfma_f32_16x16x32_bf16 v[98:101], v[150:153], v[232:235], v[98:101]
	v_mfma_f32_16x16x32_bf16 v[90:93], v[158:161], v[232:235], v[90:93]
	v_mfma_f32_16x16x32_bf16 v[78:81], v[150:153], v[240:243], v[78:81]
	v_mfma_f32_16x16x32_bf16 v[74:77], v[158:161], v[240:243], v[74:77]
	v_mfma_f32_16x16x32_bf16 v[126:129], v[154:157], v[202:205], v[126:129]
	v_mfma_f32_16x16x32_bf16 v[122:125], v[162:165], v[202:205], v[122:125]
	v_mfma_f32_16x16x32_bf16 v[114:117], v[154:157], v[210:213], v[114:117]
	v_mfma_f32_16x16x32_bf16 v[106:109], v[162:165], v[210:213], v[106:109]
	v_mfma_f32_16x16x32_bf16 v[98:101], v[154:157], v[236:239], v[98:101]
	v_mfma_f32_16x16x32_bf16 v[90:93], v[162:165], v[236:239], v[90:93]
	v_mfma_f32_16x16x32_bf16 v[78:81], v[154:157], v[244:247], v[78:81]
	v_mfma_f32_16x16x32_bf16 v[74:77], v[162:165], v[244:247], v[74:77]
	v_mfma_f32_16x16x32_bf16 v[118:121], v[166:169], v[182:185], v[118:121]
	v_mfma_f32_16x16x32_bf16 v[110:113], v[174:177], v[182:185], v[110:113]
	v_mfma_f32_16x16x32_bf16 v[102:105], v[166:169], v[206:209], v[102:105]
	v_mfma_f32_16x16x32_bf16 v[94:97], v[174:177], v[206:209], v[94:97]
	v_mfma_f32_16x16x32_bf16 v[86:89], v[166:169], v[232:235], v[86:89]
	v_mfma_f32_16x16x32_bf16 v[82:85], v[174:177], v[232:235], v[82:85]
	v_mfma_f32_16x16x32_bf16 v[70:73], v[166:169], v[240:243], v[70:73]
	v_mfma_f32_16x16x32_bf16 v[66:69], v[174:177], v[240:243], v[66:69]
	v_mfma_f32_16x16x32_bf16 v[118:121], v[170:173], v[202:205], v[118:121]
	v_mfma_f32_16x16x32_bf16 v[110:113], v[178:181], v[202:205], v[110:113]
	v_mfma_f32_16x16x32_bf16 v[102:105], v[170:173], v[210:213], v[102:105]
	v_mfma_f32_16x16x32_bf16 v[94:97], v[178:181], v[210:213], v[94:97]
	v_mfma_f32_16x16x32_bf16 v[86:89], v[170:173], v[236:239], v[86:89]
	v_mfma_f32_16x16x32_bf16 v[82:85], v[178:181], v[236:239], v[82:85]
	v_mfma_f32_16x16x32_bf16 v[70:73], v[170:173], v[244:247], v[70:73]
	v_mfma_f32_16x16x32_bf16 v[66:69], v[178:181], v[244:247], v[66:69]
	s_setprio 0
	s_barrier
	s_add_i32 s26, s49, s34
	s_mov_b32 m0, s26
	ds_read_b128 v[182:185], v148 offset:49152
	ds_read_b128 v[202:205], v148 offset:50176
	ds_read_b128 v[206:209], v148 offset:51200
	ds_read_b128 v[210:213], v148 offset:52224
	ds_read_b128 v[232:235], v148 offset:53248
	ds_read_b128 v[236:239], v148 offset:54272
	ds_read_b128 v[240:243], v148 offset:55296
	ds_read_b128 v[244:247], v148 offset:56320
	global_load_lds_dwordx4 v134, s[60:61]
	s_add_i32 m0, s26, 0x2000
	s_add_u32 s24, s24, 0x40080
	s_addc_u32 s25, s25, 0
	s_add_i32 s26, s50, s34
	global_load_lds_dwordx4 v130, s[60:61]
	s_mov_b32 m0, s26
	s_nop 0
	global_load_lds_dwordx4 v134, s[24:25]
	s_add_i32 m0, s26, 0x2000
	s_nop 0
	global_load_lds_dwordx4 v130, s[24:25]
	s_mov_b32 m0, s40
	s_nop 0
	global_load_lds_dwordx4 v136, s[62:63]
	s_mov_b32 m0, s41
	s_nop 0
	global_load_lds_dwordx4 v132, s[62:63]
	s_waitcnt vmcnt(8)
	s_waitcnt lgkmcnt(0)
	s_barrier
	s_setprio 1
	s_waitcnt lgkmcnt(0)
	v_mfma_f32_16x16x32_bf16 v[62:65], v[150:153], v[182:185], v[62:65]
	v_mfma_f32_16x16x32_bf16 v[58:61], v[158:161], v[182:185], v[58:61]
	v_mfma_f32_16x16x32_bf16 v[46:49], v[150:153], v[206:209], v[46:49]
	v_mfma_f32_16x16x32_bf16 v[42:45], v[158:161], v[206:209], v[42:45]
	v_mfma_f32_16x16x32_bf16 v[30:33], v[150:153], v[232:235], v[30:33]
	v_mfma_f32_16x16x32_bf16 v[26:29], v[158:161], v[232:235], v[26:29]
	v_mfma_f32_16x16x32_bf16 v[14:17], v[150:153], v[240:243], v[14:17]
	v_mfma_f32_16x16x32_bf16 v[10:13], v[158:161], v[240:243], v[10:13]
	v_mfma_f32_16x16x32_bf16 v[62:65], v[154:157], v[202:205], v[62:65]
	v_mfma_f32_16x16x32_bf16 v[58:61], v[162:165], v[202:205], v[58:61]
	v_mfma_f32_16x16x32_bf16 v[46:49], v[154:157], v[210:213], v[46:49]
	v_mfma_f32_16x16x32_bf16 v[42:45], v[162:165], v[210:213], v[42:45]
	v_mfma_f32_16x16x32_bf16 v[30:33], v[154:157], v[236:239], v[30:33]
	v_mfma_f32_16x16x32_bf16 v[26:29], v[162:165], v[236:239], v[26:29]
	v_mfma_f32_16x16x32_bf16 v[14:17], v[154:157], v[244:247], v[14:17]
	v_mfma_f32_16x16x32_bf16 v[10:13], v[162:165], v[244:247], v[10:13]
	v_mfma_f32_16x16x32_bf16 v[54:57], v[166:169], v[182:185], v[54:57]
	v_mfma_f32_16x16x32_bf16 v[50:53], v[174:177], v[182:185], v[50:53]
	v_mfma_f32_16x16x32_bf16 v[38:41], v[166:169], v[206:209], v[38:41]
	v_mfma_f32_16x16x32_bf16 v[34:37], v[174:177], v[206:209], v[34:37]
	v_mfma_f32_16x16x32_bf16 v[22:25], v[166:169], v[232:235], v[22:25]
	v_mfma_f32_16x16x32_bf16 v[18:21], v[174:177], v[232:235], v[18:21]
	v_mfma_f32_16x16x32_bf16 v[6:9], v[166:169], v[240:243], v[6:9]
	v_mfma_f32_16x16x32_bf16 v[2:5], v[174:177], v[240:243], v[2:5]
	v_mfma_f32_16x16x32_bf16 v[54:57], v[170:173], v[202:205], v[54:57]
	v_mfma_f32_16x16x32_bf16 v[50:53], v[178:181], v[202:205], v[50:53]
	v_mfma_f32_16x16x32_bf16 v[38:41], v[170:173], v[210:213], v[38:41]
	v_mfma_f32_16x16x32_bf16 v[34:37], v[178:181], v[210:213], v[34:37]
	v_mfma_f32_16x16x32_bf16 v[22:25], v[170:173], v[236:239], v[22:25]
	v_mfma_f32_16x16x32_bf16 v[18:21], v[178:181], v[236:239], v[18:21]
	v_mfma_f32_16x16x32_bf16 v[6:9], v[170:173], v[244:247], v[6:9]
	v_mfma_f32_16x16x32_bf16 v[2:5], v[178:181], v[244:247], v[2:5]
	s_setprio 0
	s_barrier
	s_add_i32 s48, s48, 2
	s_add_u32 s22, s22, 0x100
	s_addc_u32 s23, s23, 0
	s_add_u32 s46, s46, 0x100
	s_addc_u32 s47, s47, 0
	s_cmp_gt_u32 s48, 13
	s_cbranch_scc0 .LBB0_1354
	s_and_b64 vcc, exec, s[10:11]
	s_cbranch_vccz .LBB0_1357
	s_barrier

; #define PG8_STAGE(bufoff, gbase, voff) do { _Pragma("unroll") for (int _i = 0; _i < 2; ++_i) \
;         __builtin_amdgcn_global_load_lds((const unsigned*)((const char*)(gbase) + (voff)[_i]), (PG8_LAS unsigned*)(lds + (bufoff) + ldsw + _i * 8192), 16, 0, 0); } while (0)
; #define PG8_LDA(dst, b, h) do { _Pragma("unroll") for (int m = 0; m < 4; ++m) _Pragma("unroll") for (int k = 0; k < 2; ++k) dst[m][k] = *(const PG8_LAS bf16x8*)(lds + PG8_SA(b, h) + aoff + m * 2048 + k * 1024); } while (0)
; #define PG8_LDB(dst, b, h) do { _Pragma("unroll") for (int n = 0; n < 2; ++n) _Pragma("unroll") for (int k = 0; k < 2; ++k) dst[n][k] = *(const PG8_LAS bf16x8*)(lds + PG8_SB(b, h) + boff + n * 2048 + k * 1024); } while (0)
; template <class Epi, class Sched, bool ALIGN_EPI = false, bool SP2 = false>
; __device__ __forceinline__ void gemm_phase(PG8_LAS unsigned char* lds, const Gemm g, const Sched& S, const Epi& E) {
;     ...
;         for (int t = 0; t < nt; t += 2) {
;             const bool last = (t == nt - 2);
;             const char* a1 = cA + (size_t)(t + 1) * kstep;
;             const char* a2 = last ? nA : cA + (size_t)(t + 2) * kstep; const char* b2 = last ? nB : cB + (size_t)(t + 2) * kstep;
;             const char* a3 = a2 + kstep; const char* b3 = b2 + kstep;
;             if (last && has_next) S.a_ready(nxt);
;             if constexpr (SP2) {
;             PG8_LDB(B0, 0, 0); PG8_LDB(B1, 0, 1); PG8_SCHED; PG8_LDA(At, 0, 0); PG8_STAGE(PG8_SA(1, 1), a1 + hstepA, voffA);
;             PG8_WAIT_V(8); PG8_WAIT_L(0); PG8_BAR; PG8_MMA(0, 0, At, B0); PG8_MMA(0, 1, At, B1); PG8_BAR; PG8_SCHED;
;             PG8_LDA(At, 0, 1); PG8_STAGE(PG8_SB(0, 0), b2, voffB); PG8_STAGE(PG8_SB(0, 1), b2 + hstepB, voffB); PG8_STAGE(PG8_SA(0, 0), a2, voffA);
;             PG8_WAIT_V(8); PG8_WAIT_L(0); PG8_BAR; PG8_MMA(1, 0, At, B0); PG8_MMA(1, 1, At, B1); PG8_BAR; PG8_SCHED;
;             PG8_LDB(B0, 1, 0); PG8_LDB(B1, 1, 1); PG8_SCHED; PG8_LDA(At, 1, 0); PG8_STAGE(PG8_SA(0, 1), a2 + hstepA, voffA);
;             PG8_WAIT_V(8); PG8_WAIT_L(0); PG8_BAR; PG8_MMA(0, 0, At, B0); PG8_MMA(0, 1, At, B1); PG8_BAR; PG8_SCHED;
;             PG8_LDA(At, 1, 1); PG8_STAGE(PG8_SB(1, 0), b3, voffB); PG8_STAGE(PG8_SB(1, 1), b3 + hstepB, voffB); PG8_STAGE(PG8_SA(1, 0), a3, voffA);
;             PG8_WAIT_V(8); PG8_WAIT_L(0); PG8_BAR; PG8_MMA(1, 0, At, B0); PG8_MMA(1, 1, At, B1); PG8_BAR; PG8_SCHED;
.LBB0_1438:
	s_add_u32 s20, s18, 0x100
	s_addc_u32 s21, s19, 0
	s_add_i32 s50, 0, 0x10000
	s_cmp_eq_u32 s49, 40
	s_cselect_b32 s25, s9, s21
	s_cselect_b32 s24, s8, s20
	s_cselect_b32 s23, s17, s48
	s_cselect_b32 s22, s16, s47
	s_add_i32 s51, 0, 0x14000
	v_add_u32_e32 v142, s50, v186
	v_add_u32_e32 v172, s51, v186
	ds_read_b128 v[130:133], v142
	ds_read_b128 v[134:137], v142 offset:1024
	ds_read_b128 v[138:141], v142 offset:2048
	ds_read_b128 v[142:145], v142 offset:3072
	ds_read_b128 v[146:149], v172
	ds_read_b128 v[150:153], v172 offset:1024
	ds_read_b128 v[168:171], v172 offset:2048
	ds_read_b128 v[172:175], v172 offset:3072
	s_add_i32 m0, s31, 0xc000
	ds_read_b128 v[176:179], v200
	ds_read_b128 v[180:183], v200 offset:1024
	ds_read_b128 v[202:205], v200 offset:2048
	ds_read_b128 v[206:209], v200 offset:3072
	ds_read_b128 v[210:213], v200 offset:4096
	ds_read_b128 v[232:235], v200 offset:5120
	ds_read_b128 v[236:239], v200 offset:6144
	ds_read_b128 v[240:243], v200 offset:7168
	global_load_lds_dwordx4 v164, s[18:19]
	s_add_i32 m0, s31, 0xe000
	s_nop 0
	global_load_lds_dwordx4 v166, s[18:19]
	s_waitcnt vmcnt(8)
	s_waitcnt lgkmcnt(0)
	s_barrier
	s_setprio 1
	s_waitcnt lgkmcnt(0)
	v_mfma_f32_16x16x32_bf16 v[126:129], v[130:133], v[176:179], v[126:129]
	v_mfma_f32_16x16x32_bf16 v[122:125], v[138:141], v[176:179], v[122:125]
	v_mfma_f32_16x16x32_bf16 v[110:113], v[130:133], v[202:205], v[110:113]
	v_mfma_f32_16x16x32_bf16 v[106:109], v[138:141], v[202:205], v[106:109]
	v_mfma_f32_16x16x32_bf16 v[94:97], v[130:133], v[210:213], v[94:97]
	v_mfma_f32_16x16x32_bf16 v[90:93], v[138:141], v[210:213], v[90:93]
	v_mfma_f32_16x16x32_bf16 v[78:81], v[130:133], v[236:239], v[78:81]
	v_mfma_f32_16x16x32_bf16 v[74:77], v[138:141], v[236:239], v[74:77]
	v_mfma_f32_16x16x32_bf16 v[126:129], v[134:137], v[180:183], v[126:129]
	v_mfma_f32_16x16x32_bf16 v[122:125], v[142:145], v[180:183], v[122:125]
	v_mfma_f32_16x16x32_bf16 v[110:113], v[134:137], v[206:209], v[110:113]
	v_mfma_f32_16x16x32_bf16 v[106:109], v[142:145], v[206:209], v[106:109]
	v_mfma_f32_16x16x32_bf16 v[94:97], v[134:137], v[232:235], v[94:97]
	v_mfma_f32_16x16x32_bf16 v[90:93], v[142:145], v[232:235], v[90:93]
	v_mfma_f32_16x16x32_bf16 v[78:81], v[134:137], v[240:243], v[78:81]
	v_mfma_f32_16x16x32_bf16 v[74:77], v[142:145], v[240:243], v[74:77]
	v_mfma_f32_16x16x32_bf16 v[118:121], v[146:149], v[176:179], v[118:121]
	v_mfma_f32_16x16x32_bf16 v[114:117], v[168:171], v[176:179], v[114:117]
	v_mfma_f32_16x16x32_bf16 v[102:105], v[146:149], v[202:205], v[102:105]
	v_mfma_f32_16x16x32_bf16 v[98:101], v[168:171], v[202:205], v[98:101]
	v_mfma_f32_16x16x32_bf16 v[86:89], v[146:149], v[210:213], v[86:89]
	v_mfma_f32_16x16x32_bf16 v[82:85], v[168:171], v[210:213], v[82:85]
	v_mfma_f32_16x16x32_bf16 v[70:73], v[146:149], v[236:239], v[70:73]
	v_mfma_f32_16x16x32_bf16 v[66:69], v[168:171], v[236:239], v[66:69]
	v_mfma_f32_16x16x32_bf16 v[118:121], v[150:153], v[180:183], v[118:121]
	v_mfma_f32_16x16x32_bf16 v[114:117], v[172:175], v[180:183], v[114:117]
	v_mfma_f32_16x16x32_bf16 v[102:105], v[150:153], v[206:209], v[102:105]
	v_mfma_f32_16x16x32_bf16 v[98:101], v[172:175], v[206:209], v[98:101]
	v_mfma_f32_16x16x32_bf16 v[86:89], v[150:153], v[232:235], v[86:89]
	v_mfma_f32_16x16x32_bf16 v[82:85], v[172:175], v[232:235], v[82:85]
	v_mfma_f32_16x16x32_bf16 v[70:73], v[150:153], v[240:243], v[70:73]
	v_mfma_f32_16x16x32_bf16 v[66:69], v[172:175], v[240:243], v[66:69]
	s_setprio 0
	s_barrier
	s_add_i32 s18, s50, s30
	s_mov_b32 m0, s18
	ds_read_b128 v[176:179], v200 offset:16384
	ds_read_b128 v[180:183], v200 offset:17408
	ds_read_b128 v[202:205], v200 offset:18432
	ds_read_b128 v[206:209], v200 offset:19456
	ds_read_b128 v[210:213], v200 offset:20480
	ds_read_b128 v[232:235], v200 offset:21504
	ds_read_b128 v[236:239], v200 offset:22528
	ds_read_b128 v[240:243], v200 offset:23552
	s_add_u32 s60, s22, 0x80
	s_addc_u32 s61, s23, 0
	s_add_u32 s62, s24, 0x80
	s_addc_u32 s63, s25, 0
	global_load_lds_dwordx4 v156, s[22:23]
	s_add_i32 m0, s18, 0x2000
	s_add_u32 s18, s22, 0xb0000
	s_addc_u32 s19, s23, 0
	s_add_i32 s50, s51, s30
	global_load_lds_dwordx4 v160, s[22:23]
	s_mov_b32 m0, s50
	s_nop 0
	global_load_lds_dwordx4 v156, s[18:19]
	s_add_i32 m0, s50, 0x2000
	s_nop 0
	global_load_lds_dwordx4 v160, s[18:19]
	s_mov_b32 m0, s31
	s_nop 0
	global_load_lds_dwordx4 v154, s[24:25]
	s_mov_b32 m0, s34
	s_nop 0
	global_load_lds_dwordx4 v158, s[24:25]
	s_waitcnt vmcnt(8)
	s_waitcnt lgkmcnt(0)
	s_barrier
	s_setprio 1
	s_waitcnt lgkmcnt(0)
	v_mfma_f32_16x16x32_bf16 v[62:65], v[130:133], v[176:179], v[62:65]
	v_mfma_f32_16x16x32_bf16 v[58:61], v[138:141], v[176:179], v[58:61]
	v_mfma_f32_16x16x32_bf16 v[46:49], v[130:133], v[202:205], v[46:49]
	v_mfma_f32_16x16x32_bf16 v[42:45], v[138:141], v[202:205], v[42:45]
	v_mfma_f32_16x16x32_bf16 v[30:33], v[130:133], v[210:213], v[30:33]
	v_mfma_f32_16x16x32_bf16 v[26:29], v[138:141], v[210:213], v[26:29]
	v_mfma_f32_16x16x32_bf16 v[14:17], v[130:133], v[236:239], v[14:17]
	v_mfma_f32_16x16x32_bf16 v[10:13], v[138:141], v[236:239], v[10:13]
	v_mfma_f32_16x16x32_bf16 v[62:65], v[134:137], v[180:183], v[62:65]
	v_mfma_f32_16x16x32_bf16 v[58:61], v[142:145], v[180:183], v[58:61]
	v_mfma_f32_16x16x32_bf16 v[46:49], v[134:137], v[206:209], v[46:49]
	v_mfma_f32_16x16x32_bf16 v[42:45], v[142:145], v[206:209], v[42:45]
	v_mfma_f32_16x16x32_bf16 v[30:33], v[134:137], v[232:235], v[30:33]
	v_mfma_f32_16x16x32_bf16 v[26:29], v[142:145], v[232:235], v[26:29]
	v_mfma_f32_16x16x32_bf16 v[14:17], v[134:137], v[240:243], v[14:17]
	v_mfma_f32_16x16x32_bf16 v[10:13], v[142:145], v[240:243], v[10:13]
	v_mfma_f32_16x16x32_bf16 v[54:57], v[146:149], v[176:179], v[54:57]
	v_mfma_f32_16x16x32_bf16 v[50:53], v[168:171], v[176:179], v[50:53]
	v_mfma_f32_16x16x32_bf16 v[38:41], v[146:149], v[202:205], v[38:41]
	v_mfma_f32_16x16x32_bf16 v[34:37], v[168:171], v[202:205], v[34:37]
	v_mfma_f32_16x16x32_bf16 v[22:25], v[146:149], v[210:213], v[22:25]
	v_mfma_f32_16x16x32_bf16 v[18:21], v[168:171], v[210:213], v[18:21]
	v_mfma_f32_16x16x32_bf16 v[6:9], v[146:149], v[236:239], v[6:9]
	v_mfma_f32_16x16x32_bf16 v[2:5], v[168:171], v[236:239], v[2:5]
	v_mfma_f32_16x16x32_bf16 v[54:57], v[150:153], v[180:183], v[54:57]
	v_mfma_f32_16x16x32_bf16 v[50:53], v[172:175], v[180:183], v[50:53]
	v_mfma_f32_16x16x32_bf16 v[38:41], v[150:153], v[206:209], v[38:41]
	v_mfma_f32_16x16x32_bf16 v[34:37], v[172:175], v[206:209], v[34:37]
	v_mfma_f32_16x16x32_bf16 v[22:25], v[150:153], v[232:235], v[22:25]
	v_mfma_f32_16x16x32_bf16 v[18:21], v[172:175], v[232:235], v[18:21]
	v_mfma_f32_16x16x32_bf16 v[6:9], v[150:153], v[240:243], v[6:9]
	v_mfma_f32_16x16x32_bf16 v[2:5], v[172:175], v[240:243], v[2:5]
	s_setprio 0
	s_barrier
; #define PG8_STAGE(bufoff, gbase, voff) do { _Pragma("unroll") for (int _i = 0; _i < 2; ++_i) \
;         __builtin_amdgcn_global_load_lds((const unsigned*)((const char*)(gbase) + (voff)[_i]), (PG8_LAS unsigned*)(lds + (bufoff) + ldsw + _i * 8192), 16, 0, 0); } while (0)
; #define PG8_LDA(dst, b, h) do { _Pragma("unroll") for (int m = 0; m < 4; ++m) _Pragma("unroll") for (int k = 0; k < 2; ++k) dst[m][k] = *(const PG8_LAS bf16x8*)(lds + PG8_SA(b, h) + aoff + m * 2048 + k * 1024); } while (0)
; #define PG8_LDB(dst, b, h) do { _Pragma("unroll") for (int n = 0; n < 2; ++n) _Pragma("unroll") for (int k = 0; k < 2; ++k) dst[n][k] = *(const PG8_LAS bf16x8*)(lds + PG8_SB(b, h) + boff + n * 2048 + k * 1024); } while (0)
; #define PG8_MMA(ai, bj, At, Bt) do { __builtin_amdgcn_s_setprio(1); _Pragma("unroll") for (int m = 0; m < 4; ++m) _Pragma("unroll") for (int n = 0; n < 2; ++n) _Pragma("unroll") for (int k = 0; k < 2; ++k) \
;         acc[ai][bj][m][n] = __builtin_amdgcn_mfma_f32_16x16x32_bf16(Bt[n][k], At[m][k], acc[ai][bj][m][n], 0, 0, 0); __builtin_amdgcn_s_setprio(0); } while (0)
; #define PG8_WAIT_V(n) asm volatile("s_waitcnt vmcnt(" #n ")" ::: "memory")
; template <class Epi, class Sched, bool ALIGN_EPI = false, bool SP2 = false>
; __device__ __forceinline__ void gemm_phase(PG8_LAS unsigned char* lds, const Gemm g, const Sched& S, const Epi& E) {
;     ...
;             PG8_LDB(B0, 0, 0); PG8_LDB(B1, 0, 1); PG8_SCHED; PG8_LDA(At, 0, 0); PG8_STAGE(PG8_SA(1, 1), a1 + hstepA, voffA);
;             PG8_WAIT_V(8); PG8_WAIT_L(0); PG8_BAR; PG8_MMA(0, 0, At, B0); PG8_MMA(0, 1, At, B1); PG8_BAR; PG8_SCHED;
;             PG8_LDA(At, 0, 1); PG8_STAGE(PG8_SB(0, 0), b2, voffB); PG8_STAGE(PG8_SB(0, 1), b2 + hstepB, voffB); PG8_STAGE(PG8_SA(0, 0), a2, voffA);
;             PG8_WAIT_V(8); PG8_WAIT_L(0); PG8_BAR; PG8_MMA(1, 0, At, B0); PG8_MMA(1, 1, At, B1); PG8_BAR; PG8_SCHED;
;             PG8_LDB(B0, 1, 0); PG8_LDB(B1, 1, 1); PG8_SCHED; PG8_LDA(At, 1, 0); PG8_STAGE(PG8_SA(0, 1), a2 + hstepA, voffA);
;             PG8_WAIT_V(8); PG8_WAIT_L(0); PG8_BAR; PG8_MMA(0, 0, At, B0); PG8_MMA(0, 1, At, B1); PG8_BAR; PG8_SCHED;
;             PG8_LDA(At, 1, 1); PG8_STAGE(PG8_SB(1, 0), b3, voffB); PG8_STAGE(PG8_SB(1, 1), b3 + hstepB, voffB); PG8_STAGE(PG8_SA(1, 0), a3, voffA);
;             PG8_WAIT_V(8); PG8_WAIT_L(0); PG8_BAR; PG8_MMA(1, 0, At, B0); PG8_MMA(1, 1, At, B1); PG8_BAR; PG8_SCHED;
	s_add_i32 s50, 0, 0x18000
	s_add_i32 s51, 0, 0x1c000
	v_add_u32_e32 v142, s50, v186
	v_add_u32_e32 v172, s51, v186
	ds_read_b128 v[130:133], v142
	ds_read_b128 v[134:137], v142 offset:1024
	ds_read_b128 v[138:141], v142 offset:2048
	ds_read_b128 v[142:145], v142 offset:3072
	ds_read_b128 v[146:149], v172
	ds_read_b128 v[150:153], v172 offset:1024
	ds_read_b128 v[168:171], v172 offset:2048
	ds_read_b128 v[172:175], v172 offset:3072
	s_add_u32 s18, s24, 0xb0000
	s_addc_u32 s19, s25, 0
	s_mov_b32 m0, s35
	ds_read_b128 v[176:179], v200 offset:32768
	ds_read_b128 v[180:183], v200 offset:33792
	ds_read_b128 v[202:205], v200 offset:34816
	ds_read_b128 v[206:209], v200 offset:35840
	ds_read_b128 v[210:213], v200 offset:36864
	ds_read_b128 v[232:235], v200 offset:37888
	ds_read_b128 v[236:239], v200 offset:38912
	ds_read_b128 v[240:243], v200 offset:39936
	global_load_lds_dwordx4 v154, s[18:19]
	s_mov_b32 m0, s36
	s_nop 0
	global_load_lds_dwordx4 v158, s[18:19]
	s_waitcnt vmcnt(8)
	s_waitcnt lgkmcnt(0)
	s_barrier
	s_setprio 1
	s_waitcnt lgkmcnt(0)
	v_mfma_f32_16x16x32_bf16 v[126:129], v[130:133], v[176:179], v[126:129]
	v_mfma_f32_16x16x32_bf16 v[122:125], v[138:141], v[176:179], v[122:125]
	v_mfma_f32_16x16x32_bf16 v[110:113], v[130:133], v[202:205], v[110:113]
	v_mfma_f32_16x16x32_bf16 v[106:109], v[138:141], v[202:205], v[106:109]
	v_mfma_f32_16x16x32_bf16 v[94:97], v[130:133], v[210:213], v[94:97]
	v_mfma_f32_16x16x32_bf16 v[90:93], v[138:141], v[210:213], v[90:93]
	v_mfma_f32_16x16x32_bf16 v[78:81], v[130:133], v[236:239], v[78:81]
	v_mfma_f32_16x16x32_bf16 v[74:77], v[138:141], v[236:239], v[74:77]
	v_mfma_f32_16x16x32_bf16 v[126:129], v[134:137], v[180:183], v[126:129]
	v_mfma_f32_16x16x32_bf16 v[122:125], v[142:145], v[180:183], v[122:125]
	v_mfma_f32_16x16x32_bf16 v[110:113], v[134:137], v[206:209], v[110:113]
	v_mfma_f32_16x16x32_bf16 v[106:109], v[142:145], v[206:209], v[106:109]
	v_mfma_f32_16x16x32_bf16 v[94:97], v[134:137], v[232:235], v[94:97]
	v_mfma_f32_16x16x32_bf16 v[90:93], v[142:145], v[232:235], v[90:93]
	v_mfma_f32_16x16x32_bf16 v[78:81], v[134:137], v[240:243], v[78:81]
	v_mfma_f32_16x16x32_bf16 v[74:77], v[142:145], v[240:243], v[74:77]
	v_mfma_f32_16x16x32_bf16 v[118:121], v[146:149], v[176:179], v[118:121]
	v_mfma_f32_16x16x32_bf16 v[114:117], v[168:171], v[176:179], v[114:117]
	v_mfma_f32_16x16x32_bf16 v[102:105], v[146:149], v[202:205], v[102:105]
	v_mfma_f32_16x16x32_bf16 v[98:101], v[168:171], v[202:205], v[98:101]
	v_mfma_f32_16x16x32_bf16 v[86:89], v[146:149], v[210:213], v[86:89]
	v_mfma_f32_16x16x32_bf16 v[82:85], v[168:171], v[210:213], v[82:85]
	v_mfma_f32_16x16x32_bf16 v[70:73], v[146:149], v[236:239], v[70:73]
	v_mfma_f32_16x16x32_bf16 v[66:69], v[168:171], v[236:239], v[66:69]
	v_mfma_f32_16x16x32_bf16 v[118:121], v[150:153], v[180:183], v[118:121]
	v_mfma_f32_16x16x32_bf16 v[114:117], v[172:175], v[180:183], v[114:117]
	v_mfma_f32_16x16x32_bf16 v[102:105], v[150:153], v[206:209], v[102:105]
	v_mfma_f32_16x16x32_bf16 v[98:101], v[172:175], v[206:209], v[98:101]
	v_mfma_f32_16x16x32_bf16 v[86:89], v[150:153], v[232:235], v[86:89]
	v_mfma_f32_16x16x32_bf16 v[82:85], v[172:175], v[232:235], v[82:85]
	v_mfma_f32_16x16x32_bf16 v[70:73], v[150:153], v[240:243], v[70:73]
	v_mfma_f32_16x16x32_bf16 v[66:69], v[172:175], v[240:243], v[66:69]
	s_setprio 0
	s_barrier
	s_add_i32 s18, s50, s30
	s_mov_b32 m0, s18
	ds_read_b128 v[176:179], v200 offset:49152
	ds_read_b128 v[180:183], v200 offset:50176
	ds_read_b128 v[202:205], v200 offset:51200
	ds_read_b128 v[206:209], v200 offset:52224
	ds_read_b128 v[210:213], v200 offset:53248
	ds_read_b128 v[232:235], v200 offset:54272
	ds_read_b128 v[236:239], v200 offset:55296
	ds_read_b128 v[240:243], v200 offset:56320
	global_load_lds_dwordx4 v156, s[60:61]
	s_add_i32 m0, s18, 0x2000
	s_add_u32 s18, s22, 0xb0080
	s_addc_u32 s19, s23, 0
	s_add_i32 s22, s51, s30
	global_load_lds_dwordx4 v160, s[60:61]
	s_mov_b32 m0, s22
	s_nop 0
	global_load_lds_dwordx4 v156, s[18:19]
	s_add_i32 m0, s22, 0x2000
	s_nop 0
	global_load_lds_dwordx4 v160, s[18:19]
	s_mov_b32 m0, s38
	s_nop 0
	global_load_lds_dwordx4 v154, s[62:63]
	s_mov_b32 m0, s39
	s_nop 0
	global_load_lds_dwordx4 v158, s[62:63]
	s_waitcnt vmcnt(8)
	s_waitcnt lgkmcnt(0)
	s_barrier
	s_setprio 1
	s_waitcnt lgkmcnt(0)
	v_mfma_f32_16x16x32_bf16 v[62:65], v[130:133], v[176:179], v[62:65]
	v_mfma_f32_16x16x32_bf16 v[58:61], v[138:141], v[176:179], v[58:61]
	v_mfma_f32_16x16x32_bf16 v[46:49], v[130:133], v[202:205], v[46:49]
	v_mfma_f32_16x16x32_bf16 v[42:45], v[138:141], v[202:205], v[42:45]
	v_mfma_f32_16x16x32_bf16 v[30:33], v[130:133], v[210:213], v[30:33]
	v_mfma_f32_16x16x32_bf16 v[26:29], v[138:141], v[210:213], v[26:29]
	v_mfma_f32_16x16x32_bf16 v[14:17], v[130:133], v[236:239], v[14:17]
	v_mfma_f32_16x16x32_bf16 v[10:13], v[138:141], v[236:239], v[10:13]
	v_mfma_f32_16x16x32_bf16 v[62:65], v[134:137], v[180:183], v[62:65]
	v_mfma_f32_16x16x32_bf16 v[58:61], v[142:145], v[180:183], v[58:61]
	v_mfma_f32_16x16x32_bf16 v[46:49], v[134:137], v[206:209], v[46:49]
	v_mfma_f32_16x16x32_bf16 v[42:45], v[142:145], v[206:209], v[42:45]
	v_mfma_f32_16x16x32_bf16 v[30:33], v[134:137], v[232:235], v[30:33]
	v_mfma_f32_16x16x32_bf16 v[26:29], v[142:145], v[232:235], v[26:29]
	v_mfma_f32_16x16x32_bf16 v[14:17], v[134:137], v[240:243], v[14:17]
	v_mfma_f32_16x16x32_bf16 v[10:13], v[142:145], v[240:243], v[10:13]
	v_mfma_f32_16x16x32_bf16 v[54:57], v[146:149], v[176:179], v[54:57]
	v_mfma_f32_16x16x32_bf16 v[50:53], v[168:171], v[176:179], v[50:53]
	v_mfma_f32_16x16x32_bf16 v[38:41], v[146:149], v[202:205], v[38:41]
	v_mfma_f32_16x16x32_bf16 v[34:37], v[168:171], v[202:205], v[34:37]
	v_mfma_f32_16x16x32_bf16 v[22:25], v[146:149], v[210:213], v[22:25]
	v_mfma_f32_16x16x32_bf16 v[18:21], v[168:171], v[210:213], v[18:21]
	v_mfma_f32_16x16x32_bf16 v[6:9], v[146:149], v[236:239], v[6:9]
	v_mfma_f32_16x16x32_bf16 v[2:5], v[168:171], v[236:239], v[2:5]
	v_mfma_f32_16x16x32_bf16 v[54:57], v[150:153], v[180:183], v[54:57]
	v_mfma_f32_16x16x32_bf16 v[50:53], v[172:175], v[180:183], v[50:53]
	v_mfma_f32_16x16x32_bf16 v[38:41], v[150:153], v[206:209], v[38:41]
	v_mfma_f32_16x16x32_bf16 v[34:37], v[172:175], v[206:209], v[34:37]
	v_mfma_f32_16x16x32_bf16 v[22:25], v[150:153], v[232:235], v[22:25]
	v_mfma_f32_16x16x32_bf16 v[18:21], v[172:175], v[232:235], v[18:21]
	v_mfma_f32_16x16x32_bf16 v[6:9], v[150:153], v[240:243], v[6:9]
	v_mfma_f32_16x16x32_bf16 v[2:5], v[172:175], v[240:243], v[2:5]
	s_setprio 0
	s_barrier
	s_add_i32 s49, s49, 2
	s_add_u32 s47, s47, 0x100
	s_addc_u32 s48, s48, 0
	s_cmp_gt_u32 s49, 41
	s_mov_b64 s[18:19], s[20:21]
	s_cbranch_scc0 .LBB0_1438
	s_and_b64 vcc, exec, s[14:15]
	s_cbranch_vccz .LBB0_1441
	s_barrier
